# k_nope tiles XCD-local mapping (8 heads of a kv row-block on one XCD)
# baseline (speedup 1.0000x reference)
; DI int get_tid() { int t = threadIdx.x; asm volatile("" : "+v"(t)); return t; }
; DI float zero_f() { float z = 0.f; asm volatile("" : "+v"(z)); return z; }
; template <int N> DI void wait_vm() { asm volatile("s_waitcnt vmcnt(%0)" ::"n"(N) : "memory"); }
; template <int BM, class Epi>
; DI void gemm_dma(const u16* __restrict__ X, long ldx, const u16* __restrict__ W, long ldw, int K, char* smem,
;                  int m0, int n0, const Epi& epi) {
;     ...
;   const int tid = get_tid(), lane = tid & 63, wave = tid >> 6;
;   const int lr = lane & 15, g = lane >> 4;
;   const int rd = lr * 64 + ((g ^ ((4 - (lr >> 2)) & 3)) << 4);
;   const int xrow0 = BIG ? wave * 64 : (wave & 1) * (BM / 2);
;   const int wrow0 = BIG ? 0 : (wave >> 1) * 64;
;   f32x4 acc[NT][MT];
;   { const float z = zero_f();
; #pragma unroll
;   for (int a = 0; a < NT; ++a)
; #pragma unroll
;     for (int b = 0; b < MT; ++b) acc[a][b] = (f32x4){z, z, z, z}; }
;   const int wu = __builtin_amdgcn_readfirstlane(wave);
;   const unsigned sbase = (unsigned)__builtin_amdgcn_readfirstlane((int)(unsigned)(size_t)smem);
;   const int r16 = lane >> 2, chunk = (lane & 3) ^ ((4 - (r16 >> 2)) & 3);
;   const u16* xs = X + (long)(wu * XD * 16 + r16) * ldx + (chunk << 3);
;   const u16* ws = W + (long)(wu * 32 + r16) * ldw + (chunk << 3);
;   const long ldx16 = 16 * ldx, ldw16 = 16 * ldw;
;   const unsigned xdst = sbase + wu * XD * 1024, wdst = sbase + BM * 64 + wu * 2048;
;     ...
;   const int nk = K >> 5;
;   __syncthreads();
; #pragma unroll
;   for (int s = 0; s < D - 1; ++s) GD_ISSUE(s)
;   int cur = 0, nxt = D - 1, kt = 0;
;   do {
;     if (kt + D - 2 < nk) wait_vm<PW * (D - 2)>(); else wait_vm<0>();
;     __syncthreads();
;     if (kt + D - 1 < nk) GD_ISSUE(nxt)
;     nxt = (nxt + 1 == D) ? 0 : nxt + 1;
;     const char* base = smem + cur * STG;
;     cur = (cur + 1 == D) ? 0 : cur + 1;
;     bf16x8 xf[MT];
; #pragma unroll
;     for (int i = 0; i < MT; ++i) xf[i] = *(const bf16x8*)(base + (xrow0 + i * 16) * 64 + rd);
; DI void knope_tile(const Params& p, int u, char* smem) {
;   const u16* W = (const u16*)(p.ws + OFF_W);
;   const u16* ckvb = (const u16*)(p.ws + OFF_CKVB);
;   EpiBF16 ek{(u16*)(p.ws + OFF_KN), 1024};
;   const int tm = u >> 3, tn = u & 7;
;   gemm_dma<256>(ckvb + (size_t)tm * 256 * 256, 256, W + WO_KV + (size_t)tn * 128 * 256, 256, 256, smem, tm * 256, tn * 128, ek);
.LBB0_84:
	s_cmpk_gt_i32 s4, 0x77f
	s_cbranch_scc1 .LBB0_92
	s_cmpk_gt_i32 s4, 0x43f
	s_mov_b64 s[38:39], -1
	s_cbranch_scc0 .LBB0_87
	s_add_i32 s5, s4, 0xfffffcc0
	s_bfe_u32 s98, s5, 0x30003
	s_and_b32 s99, s5, 7
	s_lshl_b32 s99, s99, 3
	s_andn2_b32 s5, s5, 63
	s_or_b32 s5, s5, s99
	s_or_b32 s5, s5, s98
	s_lshr_b32 s6, s5, 3
	s_and_b32 s5, s5, 7
	s_lshl_b32 s7, s6, 17
	s_add_u32 s8, s0, s7
	s_addc_u32 s9, s1, 0
	s_lshl_b32 s7, s5, 16
	v_mov_b32_e32 v11, v185
	s_add_u32 s10, s87, s7
	s_addc_u32 s11, s90, 0
	v_readfirstlane_b32 s7, v11
	v_lshrrev_b32_e32 v6, 4, v11
	s_ashr_i32 s12, s7, 6
	v_bfe_u32 v8, v11, 2, 4
	v_sub_u32_e32 v6, 0, v6
	s_andn2_b32 s7, s7, 63
	v_lshrrev_b32_e32 v3, 2, v11
	v_xor_b32_e32 v9, v11, v6
	v_or_b32_e32 v6, s7, v8
	v_and_b32_e32 v90, 15, v11
	v_bfe_u32 v1, v11, 4, 2
	v_sub_u32_e32 v3, 0, v3
	v_ashrrev_i32_e32 v7, 31, v6
	v_lshlrev_b32_e32 v2, 6, v90
	v_bitop3_b32 v3, v1, v3, 3 bitop3:0x78
	v_lshlrev_b64 v[6:7], 9, v[6:7]
	v_lshlrev_b32_e32 v9, 4, v9
	v_lshl_or_b32 v8, s12, 5, v8
	v_lshl_or_b32 v10, v3, 4, v2
	v_mov_b32_e32 v2, v183
	v_lshl_add_u64 v[6:7], s[8:9], 0, v[6:7]
	v_and_b32_e32 v182, 48, v9
	v_ashrrev_i32_e32 v9, 31, v8
	v_lshl_add_u64 v[6:7], v[6:7], 0, v[182:183]
	v_lshlrev_b64 v[8:9], 9, v[8:9]
	s_lshl_b32 s14, s12, 12
	s_barrier
	s_mov_b32 s7, m0
	s_mov_b32 m0, s14
	s_nop 0
	global_load_lds_dwordx4 v[6:7], off
	s_mov_b32 m0, s7
	s_mov_b64 s[8:9], 0x2000
	v_lshl_add_u64 v[8:9], s[10:11], 0, v[8:9]
	v_lshl_add_u64 v[12:13], v[6:7], 0, s[8:9]
	s_or_b32 s15, s14, 0x400
	s_mov_b32 s7, m0
	s_mov_b32 m0, s15
	s_nop 0
	global_load_lds_dwordx4 v[12:13], off
	s_mov_b32 m0, s7
	s_mov_b64 s[10:11], 0x4000
	v_lshl_add_u64 v[12:13], v[6:7], 0, s[10:11]
	s_or_b32 s16, s14, 0x800
	s_mov_b32 s7, m0
	s_mov_b32 m0, s16
	s_nop 0
	global_load_lds_dwordx4 v[12:13], off
	s_mov_b32 m0, s7
	s_mov_b64 s[10:11], 0x6000
	s_lshl_b32 s41, s12, 11
	v_lshl_add_u64 v[12:13], v[6:7], 0, s[10:11]
	s_or_b32 s17, s14, 0xc00
	s_mov_b32 s7, m0
	s_mov_b32 m0, s17
	s_nop 0
	global_load_lds_dwordx4 v[12:13], off
	s_mov_b32 m0, s7
	v_lshl_add_u64 v[8:9], v[8:9], 0, v[182:183]
	s_add_i32 s13, s41, 0x4000
	s_mov_b32 s7, m0
	s_mov_b32 m0, s13
	s_nop 0
	global_load_lds_dwordx4 v[8:9], off
	s_mov_b32 m0, s7
	v_lshl_add_u64 v[12:13], v[8:9], 0, s[8:9]
	s_add_i32 s18, s41, 0x4400
	s_mov_b32 s7, m0
	s_mov_b32 m0, s18
	s_nop 0
	global_load_lds_dwordx4 v[12:13], off
	s_mov_b32 m0, s7
	v_lshl_add_u64 v[12:13], v[6:7], 0, 64
	s_add_i32 s7, s14, 0x6000
	s_mov_b32 s8, m0
	s_mov_b32 m0, s7
	s_nop 0
	global_load_lds_dwordx4 v[12:13], off
	s_mov_b32 m0, s8
	s_mov_b64 s[20:21], 0x2040
	v_lshl_add_u64 v[12:13], v[6:7], 0, s[20:21]
	s_add_i32 s8, s14, 0x6400
	s_mov_b32 s9, m0
	s_mov_b32 m0, s8
	s_nop 0
	global_load_lds_dwordx4 v[12:13], off
	s_mov_b32 m0, s9
	s_mov_b64 s[10:11], 0x4040
	v_lshl_add_u64 v[12:13], v[6:7], 0, s[10:11]
	s_add_i32 s9, s14, 0x6800
	s_mov_b32 s10, m0
	s_mov_b32 m0, s9
	s_nop 0
	global_load_lds_dwordx4 v[12:13], off
	s_mov_b32 m0, s10
	s_mov_b64 s[10:11], 0x6040
	v_lshl_add_u64 v[12:13], v[6:7], 0, s[10:11]
	s_add_i32 s10, s14, 0x6c00
	s_mov_b32 s11, m0
	s_mov_b32 m0, s10
	s_nop 0
	global_load_lds_dwordx4 v[12:13], off
	s_mov_b32 m0, s11
	v_lshl_add_u64 v[14:15], v[8:9], 0, 64
	s_add_i32 s11, s41, 0xa000
	s_mov_b32 s12, m0
	s_mov_b32 m0, s11
	s_nop 0
	global_load_lds_dwordx4 v[14:15], off
	s_mov_b32 m0, s12
	v_lshl_add_u64 v[12:13], v[8:9], 0, s[20:21]
	s_add_i32 s12, s41, 0xa400
	s_mov_b32 s19, m0
	s_mov_b32 m0, s12
	s_nop 0
	global_load_lds_dwordx4 v[12:13], off
	s_mov_b32 m0, s19
	s_waitcnt vmcnt(6)
	s_barrier
	v_lshl_add_u64 v[14:15], v[6:7], 0, s[28:29]
	s_add_i32 s19, s14, 0xc000
	s_mov_b32 s34, m0
	s_mov_b32 m0, s19
	s_nop 0
	global_load_lds_dwordx4 v[14:15], off
	s_mov_b32 m0, s34
	s_mov_b64 s[20:21], 0x2080
	v_lshl_add_u64 v[14:15], v[6:7], 0, s[20:21]
	s_add_i32 s34, s14, 0xc400
	s_mov_b32 s38, m0
	s_mov_b32 m0, s34
	s_nop 0
	global_load_lds_dwordx4 v[14:15], off
	s_mov_b32 m0, s38
	v_lshl_add_u64 v[14:15], v[6:7], 0, s[94:95]
	s_add_i32 s38, s14, 0xc800
	s_mov_b32 s39, m0
	s_mov_b32 m0, s38
	s_nop 0
	global_load_lds_dwordx4 v[14:15], off
	s_mov_b32 m0, s39
	s_mov_b64 s[22:23], 0x6080
	v_lshl_add_u64 v[14:15], v[6:7], 0, s[22:23]
	s_add_i32 s39, s14, 0xcc00
	s_mov_b32 s40, m0
	s_mov_b32 m0, s39
	s_nop 0
	global_load_lds_dwordx4 v[14:15], off
	s_mov_b32 m0, s40
	v_and_b32_e32 v91, 0xffffffc0, v11
	v_lshl_add_u64 v[12:13], v[8:9], 0, s[28:29]
	s_add_i32 s40, s41, 0x10000
	s_mov_b32 s42, m0
	s_mov_b32 m0, s40
	s_nop 0
	global_load_lds_dwordx4 v[12:13], off
	s_mov_b32 m0, s42
	v_lshl_add_u64 v[12:13], v[8:9], 0, s[20:21]
	s_add_i32 s41, s41, 0x10400
	s_mov_b32 s42, m0
	s_mov_b32 m0, s41
	s_nop 0
	global_load_lds_dwordx4 v[12:13], off
	s_mov_b32 m0, s42
	v_lshl_or_b32 v11, v91, 6, v10
	ds_read_b128 v[12:15], v11
	ds_read_b128 v[16:19], v11 offset:1024
	ds_read_b128 v[20:23], v11 offset:2048
	ds_read_b128 v[24:27], v11 offset:3072
	ds_read_b128 v[28:31], v10 offset:16384
	ds_read_b128 v[32:35], v10 offset:17408
	ds_read_b128 v[36:39], v10 offset:18432
	ds_read_b128 v[40:43], v10 offset:19456
	ds_read_b128 v[96:99], v10 offset:20480
	ds_read_b128 v[100:103], v10 offset:21504
	ds_read_b128 v[104:107], v10 offset:22528
	ds_read_b128 v[108:111], v10 offset:23552
	s_mov_b64 s[20:21], 0xc0
	v_mov_b32_e32 v3, v2
	v_mov_b32_e32 v4, v2
	v_mov_b32_e32 v5, v2
	v_lshl_add_u64 v[88:89], v[6:7], 0, s[20:21]
	v_lshl_add_u64 v[148:149], v[8:9], 0, s[20:21]
	s_waitcnt vmcnt(6)
	s_waitcnt lgkmcnt(0)
	s_barrier
; template <int N> DI void wait_vm() { asm volatile("s_waitcnt vmcnt(%0)" ::"n"(N) : "memory"); }
; template <int BM, class Epi>
; DI void gemm_dma(const u16* __restrict__ X, long ldx, const u16* __restrict__ W, long ldw, int K, char* smem,
;                  int m0, int n0, const Epi& epi) {
;     ...
;   do {
;     if (kt + D - 2 < nk) wait_vm<PW * (D - 2)>(); else wait_vm<0>();
;     __syncthreads();
;     if (kt + D - 1 < nk) GD_ISSUE(nxt)
;     nxt = (nxt + 1 == D) ? 0 : nxt + 1;
;     const char* base = smem + cur * STG;
;     cur = (cur + 1 == D) ? 0 : cur + 1;
;     bf16x8 xf[MT];
; #pragma unroll
;     for (int i = 0; i < MT; ++i) xf[i] = *(const bf16x8*)(base + (xrow0 + i * 16) * 64 + rd);
; #pragma unroll
;     for (int nh = 0; nh < NT / 4; ++nh) {
;       bf16x8 wf[4];
; #pragma unroll
;       for (int i = 0; i < 4; ++i) wf[i] = *(const bf16x8*)(base + BM * 64 + (wrow0 + (nh * 4 + i) * 16) * 64 + rd);
; #pragma unroll
;       for (int i = 0; i < 4; ++i)
; #pragma unroll
;         for (int mt = 0; mt < MT; ++mt)
;           acc[nh * 4 + i][mt] = __builtin_amdgcn_mfma_f32_16x16x32_bf16(wf[i], xf[mt], acc[nh * 4 + i][mt], 0, 0, 0);
;     }
;   } while (++kt < nk);
	s_mov_b32 s42, m0
	s_mov_b32 m0, s14
	s_nop 0
	global_load_lds_dwordx4 v[88:89], off
	s_mov_b32 m0, s42
	s_mov_b64 s[20:21], 0x20c0
	v_mfma_f32_16x16x32_bf16 v[44:47], v[28:31], v[12:15], v[2:5]
	s_mov_b64 s[22:23], 0x40c0
	v_or_b32_e32 v174, 0x10000, v10
	v_or_b32_e32 v175, 0x10400, v10
	v_mfma_f32_16x16x32_bf16 v[48:51], v[28:31], v[16:19], v[2:5]
	v_or_b32_e32 v176, 0x10800, v10
	v_or_b32_e32 v177, 0x10c00, v10
	v_or_b32_e32 v178, 0x11000, v10
	v_mfma_f32_16x16x32_bf16 v[52:55], v[28:31], v[20:23], v[2:5]
	v_or_b32_e32 v179, 0x11400, v10
	v_or_b32_e32 v180, 0x11800, v10
	v_or_b32_e32 v181, 0x11c00, v10
	v_mfma_f32_16x16x32_bf16 v[28:31], v[28:31], v[24:27], v[2:5]
	v_lshl_add_u32 v91, s6, 8, v91
	s_lshl_b32 s5, s5, 8
	v_lshl_or_b32 v182, v1, 3, s5
	v_mfma_f32_16x16x32_bf16 v[56:59], v[32:35], v[12:15], v[2:5]
	v_mfma_f32_16x16x32_bf16 v[60:63], v[32:35], v[16:19], v[2:5]
	v_mfma_f32_16x16x32_bf16 v[64:67], v[32:35], v[20:23], v[2:5]
	v_mfma_f32_16x16x32_bf16 v[32:35], v[32:35], v[24:27], v[2:5]
	v_mfma_f32_16x16x32_bf16 v[68:71], v[36:39], v[12:15], v[2:5]
	v_mfma_f32_16x16x32_bf16 v[72:75], v[36:39], v[16:19], v[2:5]
	v_mfma_f32_16x16x32_bf16 v[76:79], v[36:39], v[20:23], v[2:5]
	v_mfma_f32_16x16x32_bf16 v[36:39], v[36:39], v[24:27], v[2:5]
	v_mfma_f32_16x16x32_bf16 v[80:83], v[40:43], v[12:15], v[2:5]
	v_mfma_f32_16x16x32_bf16 v[84:87], v[40:43], v[16:19], v[2:5]
	v_mfma_f32_16x16x32_bf16 v[92:95], v[40:43], v[20:23], v[2:5]
	v_mfma_f32_16x16x32_bf16 v[40:43], v[40:43], v[24:27], v[2:5]
	v_mfma_f32_16x16x32_bf16 v[112:115], v[96:99], v[12:15], v[2:5]
	v_mfma_f32_16x16x32_bf16 v[116:119], v[96:99], v[16:19], v[2:5]
	v_mfma_f32_16x16x32_bf16 v[120:123], v[96:99], v[20:23], v[2:5]
	v_mfma_f32_16x16x32_bf16 v[96:99], v[96:99], v[24:27], v[2:5]
	v_mfma_f32_16x16x32_bf16 v[124:127], v[100:103], v[12:15], v[2:5]
	v_mfma_f32_16x16x32_bf16 v[128:131], v[100:103], v[16:19], v[2:5]
	v_mfma_f32_16x16x32_bf16 v[132:135], v[100:103], v[20:23], v[2:5]
	v_mfma_f32_16x16x32_bf16 v[100:103], v[100:103], v[24:27], v[2:5]
	v_mfma_f32_16x16x32_bf16 v[136:139], v[104:107], v[12:15], v[2:5]
	v_mfma_f32_16x16x32_bf16 v[140:143], v[104:107], v[16:19], v[2:5]
	v_mfma_f32_16x16x32_bf16 v[144:147], v[104:107], v[20:23], v[2:5]
	v_mfma_f32_16x16x32_bf16 v[104:107], v[104:107], v[24:27], v[2:5]
	v_mfma_f32_16x16x32_bf16 v[12:15], v[108:111], v[12:15], v[2:5]
	v_mfma_f32_16x16x32_bf16 v[16:19], v[108:111], v[16:19], v[2:5]
	v_mfma_f32_16x16x32_bf16 v[20:23], v[108:111], v[20:23], v[2:5]
	v_mfma_f32_16x16x32_bf16 v[2:5], v[108:111], v[24:27], v[2:5]
	v_lshl_add_u64 v[24:25], v[6:7], 0, s[20:21]
	s_mov_b32 s42, m0
	s_mov_b32 m0, s15
	s_nop 0
	global_load_lds_dwordx4 v[24:25], off
	s_mov_b32 m0, s42
	v_lshl_add_u64 v[24:25], v[6:7], 0, s[22:23]
	s_mov_b32 s42, m0
	s_mov_b32 m0, s16
	s_nop 0
	global_load_lds_dwordx4 v[24:25], off
	s_mov_b32 m0, s42
	s_mov_b64 s[22:23], 0x60c0
	v_lshl_add_u64 v[24:25], v[6:7], 0, s[22:23]
	s_mov_b32 s42, m0
	s_mov_b32 m0, s17
	s_nop 0
	global_load_lds_dwordx4 v[24:25], off
	s_mov_b32 m0, s42
	v_lshl_add_u64 v[24:25], v[8:9], 0, s[20:21]
	s_mov_b32 s42, m0
	s_mov_b32 m0, s13
	s_nop 0
	global_load_lds_dwordx4 v[148:149], off
	s_mov_b32 m0, s42
	s_mov_b64 s[20:21], 0x100
	s_mov_b32 s42, m0
	s_mov_b32 m0, s18
	s_nop 0
	global_load_lds_dwordx4 v[24:25], off
	s_mov_b32 m0, s42
	ds_read_b128 v[24:27], v11 offset:24576
	ds_read_b128 v[108:111], v11 offset:25600
	ds_read_b128 v[148:151], v11 offset:26624
	ds_read_b128 v[152:155], v11 offset:27648
	ds_read_b128 v[156:159], v10 offset:40960
	ds_read_b128 v[160:163], v10 offset:41984
	ds_read_b128 v[164:167], v10 offset:43008
	ds_read_b128 v[168:171], v10 offset:44032
	s_waitcnt lgkmcnt(3)
	v_mfma_f32_16x16x32_bf16 v[44:47], v[156:159], v[24:27], v[44:47]
	v_lshl_add_u64 v[88:89], v[6:7], 0, s[20:21]
	v_lshl_add_u64 v[172:173], v[8:9], 0, s[20:21]
	s_mov_b64 s[20:21], 0x2100
	v_mfma_f32_16x16x32_bf16 v[48:51], v[156:159], v[108:111], v[48:51]
	s_mov_b64 s[22:23], 0x4100
	v_mfma_f32_16x16x32_bf16 v[52:55], v[156:159], v[148:151], v[52:55]
	v_mfma_f32_16x16x32_bf16 v[28:31], v[156:159], v[152:155], v[28:31]
	s_waitcnt lgkmcnt(2)
	v_mfma_f32_16x16x32_bf16 v[56:59], v[160:163], v[24:27], v[56:59]
	v_mfma_f32_16x16x32_bf16 v[60:63], v[160:163], v[108:111], v[60:63]
	v_mfma_f32_16x16x32_bf16 v[64:67], v[160:163], v[148:151], v[64:67]
	v_mfma_f32_16x16x32_bf16 v[32:35], v[160:163], v[152:155], v[32:35]
	s_waitcnt lgkmcnt(1)
	v_mfma_f32_16x16x32_bf16 v[68:71], v[164:167], v[24:27], v[68:71]
	v_mfma_f32_16x16x32_bf16 v[72:75], v[164:167], v[108:111], v[72:75]
	v_mfma_f32_16x16x32_bf16 v[76:79], v[164:167], v[148:151], v[76:79]
	v_mfma_f32_16x16x32_bf16 v[36:39], v[164:167], v[152:155], v[36:39]
	s_waitcnt lgkmcnt(0)
	v_mfma_f32_16x16x32_bf16 v[80:83], v[168:171], v[24:27], v[80:83]
	v_mfma_f32_16x16x32_bf16 v[84:87], v[168:171], v[108:111], v[84:87]
	v_mfma_f32_16x16x32_bf16 v[92:95], v[168:171], v[148:151], v[92:95]
	v_mfma_f32_16x16x32_bf16 v[40:43], v[168:171], v[152:155], v[40:43]
	ds_read_b128 v[156:159], v10 offset:45056
	ds_read_b128 v[160:163], v10 offset:46080
	ds_read_b128 v[164:167], v10 offset:47104
	ds_read_b128 v[168:171], v10 offset:48128
	s_waitcnt vmcnt(6)
	s_waitcnt lgkmcnt(0)
	s_barrier
; template <int N> DI void wait_vm() { asm volatile("s_waitcnt vmcnt(%0)" ::"n"(N) : "memory"); }
; template <int BM, class Epi>
; DI void gemm_dma(const u16* __restrict__ X, long ldx, const u16* __restrict__ W, long ldw, int K, char* smem,
;                  int m0, int n0, const Epi& epi) {
;     ...
;   do {
;     if (kt + D - 2 < nk) wait_vm<PW * (D - 2)>(); else wait_vm<0>();
;     __syncthreads();
;     if (kt + D - 1 < nk) GD_ISSUE(nxt)
;     nxt = (nxt + 1 == D) ? 0 : nxt + 1;
;     const char* base = smem + cur * STG;
;     cur = (cur + 1 == D) ? 0 : cur + 1;
;     bf16x8 xf[MT];
; #pragma unroll
;     for (int i = 0; i < MT; ++i) xf[i] = *(const bf16x8*)(base + (xrow0 + i * 16) * 64 + rd);
; #pragma unroll
;     for (int nh = 0; nh < NT / 4; ++nh) {
;       bf16x8 wf[4];
; #pragma unroll
;       for (int i = 0; i < 4; ++i) wf[i] = *(const bf16x8*)(base + BM * 64 + (wrow0 + (nh * 4 + i) * 16) * 64 + rd);
; #pragma unroll
;       for (int i = 0; i < 4; ++i)
; #pragma unroll
;         for (int mt = 0; mt < MT; ++mt)
;           acc[nh * 4 + i][mt] = __builtin_amdgcn_mfma_f32_16x16x32_bf16(wf[i], xf[mt], acc[nh * 4 + i][mt], 0, 0, 0);
;     }
;   } while (++kt < nk);
	s_mov_b32 s42, m0
	s_mov_b32 m0, s7
	s_nop 0
	global_load_lds_dwordx4 v[88:89], off
	s_mov_b32 m0, s42
	v_mfma_f32_16x16x32_bf16 v[112:115], v[156:159], v[24:27], v[112:115]
	v_mfma_f32_16x16x32_bf16 v[124:127], v[160:163], v[24:27], v[124:127]
	v_mfma_f32_16x16x32_bf16 v[136:139], v[164:167], v[24:27], v[136:139]
	v_mfma_f32_16x16x32_bf16 v[12:15], v[168:171], v[24:27], v[12:15]
	v_lshl_add_u64 v[24:25], v[6:7], 0, s[20:21]
	s_mov_b32 s42, m0
	s_mov_b32 m0, s8
	s_nop 0
	global_load_lds_dwordx4 v[24:25], off
	s_mov_b32 m0, s42
	v_lshl_add_u64 v[24:25], v[6:7], 0, s[22:23]
	s_mov_b32 s42, m0
	s_mov_b32 m0, s9
	s_nop 0
	global_load_lds_dwordx4 v[24:25], off
	s_mov_b32 m0, s42
	s_mov_b64 s[22:23], 0x6100
	v_lshl_add_u64 v[24:25], v[6:7], 0, s[22:23]
	s_mov_b32 s42, m0
	s_mov_b32 m0, s10
	s_nop 0
	global_load_lds_dwordx4 v[24:25], off
	s_mov_b32 m0, s42
	v_lshl_add_u64 v[24:25], v[8:9], 0, s[20:21]
	s_mov_b32 s42, m0
	s_mov_b32 m0, s11
	s_nop 0
	global_load_lds_dwordx4 v[172:173], off
	s_mov_b32 m0, s42
	v_mfma_f32_16x16x32_bf16 v[116:119], v[156:159], v[108:111], v[116:119]
	s_mov_b32 s42, m0
	s_mov_b32 m0, s12
	s_nop 0
	global_load_lds_dwordx4 v[24:25], off
	s_mov_b32 m0, s42
	s_mov_b64 s[20:21], 0x140
	v_lshl_add_u64 v[88:89], v[6:7], 0, s[20:21]
	v_mfma_f32_16x16x32_bf16 v[120:123], v[156:159], v[148:151], v[120:123]
	v_lshl_add_u64 v[172:173], v[8:9], 0, s[20:21]
	s_mov_b64 s[20:21], 0x2140
	s_mov_b64 s[22:23], 0x4140
	v_mfma_f32_16x16x32_bf16 v[96:99], v[156:159], v[152:155], v[96:99]
	v_mfma_f32_16x16x32_bf16 v[128:131], v[160:163], v[108:111], v[128:131]
	v_mfma_f32_16x16x32_bf16 v[132:135], v[160:163], v[148:151], v[132:135]
	v_mfma_f32_16x16x32_bf16 v[100:103], v[160:163], v[152:155], v[100:103]
	v_mfma_f32_16x16x32_bf16 v[140:143], v[164:167], v[108:111], v[140:143]
	v_mfma_f32_16x16x32_bf16 v[144:147], v[164:167], v[148:151], v[144:147]
	v_mfma_f32_16x16x32_bf16 v[104:107], v[164:167], v[152:155], v[104:107]
	v_mfma_f32_16x16x32_bf16 v[16:19], v[168:171], v[108:111], v[16:19]
	v_mfma_f32_16x16x32_bf16 v[20:23], v[168:171], v[148:151], v[20:23]
	v_mfma_f32_16x16x32_bf16 v[2:5], v[168:171], v[152:155], v[2:5]
	ds_read_b128 v[24:27], v11 offset:49152
	ds_read_b128 v[108:111], v11 offset:50176
	ds_read_b128 v[148:151], v11 offset:51200
	ds_read_b128 v[152:155], v11 offset:52224
	ds_read_b128 v[156:159], v174
	ds_read_b128 v[160:163], v175
	ds_read_b128 v[164:167], v176
	ds_read_b128 v[168:171], v177
	s_waitcnt lgkmcnt(3)
	v_mfma_f32_16x16x32_bf16 v[44:47], v[156:159], v[24:27], v[44:47]
	v_mfma_f32_16x16x32_bf16 v[48:51], v[156:159], v[108:111], v[48:51]
	v_mfma_f32_16x16x32_bf16 v[52:55], v[156:159], v[148:151], v[52:55]
	v_mfma_f32_16x16x32_bf16 v[28:31], v[156:159], v[152:155], v[28:31]
	ds_read_b128 v[156:159], v178
	s_waitcnt lgkmcnt(3)
	v_mfma_f32_16x16x32_bf16 v[56:59], v[160:163], v[24:27], v[56:59]
	v_mfma_f32_16x16x32_bf16 v[60:63], v[160:163], v[108:111], v[60:63]
	v_mfma_f32_16x16x32_bf16 v[64:67], v[160:163], v[148:151], v[64:67]
	v_mfma_f32_16x16x32_bf16 v[32:35], v[160:163], v[152:155], v[32:35]
	ds_read_b128 v[160:163], v179
	s_waitcnt lgkmcnt(3)
	v_mfma_f32_16x16x32_bf16 v[68:71], v[164:167], v[24:27], v[68:71]
	v_mfma_f32_16x16x32_bf16 v[72:75], v[164:167], v[108:111], v[72:75]
	v_mfma_f32_16x16x32_bf16 v[76:79], v[164:167], v[148:151], v[76:79]
	v_mfma_f32_16x16x32_bf16 v[36:39], v[164:167], v[152:155], v[36:39]
	ds_read_b128 v[164:167], v180
	s_waitcnt lgkmcnt(3)
	v_mfma_f32_16x16x32_bf16 v[80:83], v[168:171], v[24:27], v[80:83]
	v_mfma_f32_16x16x32_bf16 v[84:87], v[168:171], v[108:111], v[84:87]
	v_mfma_f32_16x16x32_bf16 v[92:95], v[168:171], v[148:151], v[92:95]
	v_mfma_f32_16x16x32_bf16 v[40:43], v[168:171], v[152:155], v[40:43]
	ds_read_b128 v[168:171], v181
	s_waitcnt vmcnt(6)
	s_waitcnt lgkmcnt(0)
	s_barrier
	s_mov_b32 s42, m0
	s_mov_b32 m0, s19
	s_nop 0
	global_load_lds_dwordx4 v[88:89], off
	s_mov_b32 m0, s42
	v_mfma_f32_16x16x32_bf16 v[112:115], v[156:159], v[24:27], v[112:115]
	v_mfma_f32_16x16x32_bf16 v[124:127], v[160:163], v[24:27], v[124:127]
	v_mfma_f32_16x16x32_bf16 v[136:139], v[164:167], v[24:27], v[136:139]
	v_mfma_f32_16x16x32_bf16 v[12:15], v[168:171], v[24:27], v[12:15]
	v_lshl_add_u64 v[24:25], v[6:7], 0, s[20:21]
	s_mov_b32 s19, m0
	s_mov_b32 m0, s34
	s_nop 0
	global_load_lds_dwordx4 v[24:25], off
	s_mov_b32 m0, s19
	v_lshl_add_u64 v[24:25], v[6:7], 0, s[22:23]
	s_mov_b32 s19, m0
	s_mov_b32 m0, s38
	s_nop 0
	global_load_lds_dwordx4 v[24:25], off
	s_mov_b32 m0, s19
	s_mov_b64 s[22:23], 0x6140
	v_lshl_add_u64 v[24:25], v[6:7], 0, s[22:23]
	s_mov_b32 s19, m0
	s_mov_b32 m0, s39
	s_nop 0
	global_load_lds_dwordx4 v[24:25], off
	s_mov_b32 m0, s19
	v_lshl_add_u64 v[24:25], v[8:9], 0, s[20:21]
	s_mov_b32 s19, m0
	s_mov_b32 m0, s40
	s_nop 0
	global_load_lds_dwordx4 v[172:173], off
	s_mov_b32 m0, s19
	v_mfma_f32_16x16x32_bf16 v[116:119], v[156:159], v[108:111], v[116:119]
	s_mov_b32 s19, m0
	s_mov_b32 m0, s41
	s_nop 0
	global_load_lds_dwordx4 v[24:25], off
	s_mov_b32 m0, s19
	s_mov_b64 s[20:21], 0x180
	v_lshl_add_u64 v[88:89], v[6:7], 0, s[20:21]
	v_mfma_f32_16x16x32_bf16 v[120:123], v[156:159], v[148:151], v[120:123]
	v_lshl_add_u64 v[172:173], v[8:9], 0, s[20:21]
	s_mov_b64 s[20:21], 0x2180
	s_mov_b64 s[38:39], 0
	v_mfma_f32_16x16x32_bf16 v[96:99], v[156:159], v[152:155], v[96:99]
	v_mfma_f32_16x16x32_bf16 v[128:131], v[160:163], v[108:111], v[128:131]
	v_mfma_f32_16x16x32_bf16 v[132:135], v[160:163], v[148:151], v[132:135]
	v_mfma_f32_16x16x32_bf16 v[100:103], v[160:163], v[152:155], v[100:103]
	v_mfma_f32_16x16x32_bf16 v[140:143], v[164:167], v[108:111], v[140:143]
	v_mfma_f32_16x16x32_bf16 v[144:147], v[164:167], v[148:151], v[144:147]
	v_mfma_f32_16x16x32_bf16 v[104:107], v[164:167], v[152:155], v[104:107]
	v_mfma_f32_16x16x32_bf16 v[16:19], v[168:171], v[108:111], v[16:19]
	v_mfma_f32_16x16x32_bf16 v[20:23], v[168:171], v[148:151], v[20:23]
	v_mfma_f32_16x16x32_bf16 v[2:5], v[168:171], v[152:155], v[2:5]
	ds_read_b128 v[24:27], v11
	ds_read_b128 v[108:111], v11 offset:1024
	ds_read_b128 v[148:151], v11 offset:2048
	ds_read_b128 v[152:155], v11 offset:3072
	ds_read_b128 v[156:159], v10 offset:16384
	ds_read_b128 v[160:163], v10 offset:17408
	ds_read_b128 v[164:167], v10 offset:18432
	ds_read_b128 v[168:171], v10 offset:19456
	s_waitcnt lgkmcnt(3)
; template <int N> DI void wait_vm() { asm volatile("s_waitcnt vmcnt(%0)" ::"n"(N) : "memory"); }
; template <int BM, class Epi>
; DI void gemm_dma(const u16* __restrict__ X, long ldx, const u16* __restrict__ W, long ldw, int K, char* smem,
;                  int m0, int n0, const Epi& epi) {
;     ...
;   do {
;     if (kt + D - 2 < nk) wait_vm<PW * (D - 2)>(); else wait_vm<0>();
;     __syncthreads();
;     if (kt + D - 1 < nk) GD_ISSUE(nxt)
;     nxt = (nxt + 1 == D) ? 0 : nxt + 1;
;     const char* base = smem + cur * STG;
;     cur = (cur + 1 == D) ? 0 : cur + 1;
;     bf16x8 xf[MT];
; #pragma unroll
;     for (int i = 0; i < MT; ++i) xf[i] = *(const bf16x8*)(base + (xrow0 + i * 16) * 64 + rd);
; #pragma unroll
;     for (int nh = 0; nh < NT / 4; ++nh) {
;       bf16x8 wf[4];
; #pragma unroll
;       for (int i = 0; i < 4; ++i) wf[i] = *(const bf16x8*)(base + BM * 64 + (wrow0 + (nh * 4 + i) * 16) * 64 + rd);
; #pragma unroll
;       for (int i = 0; i < 4; ++i)
; #pragma unroll
;         for (int mt = 0; mt < MT; ++mt)
;           acc[nh * 4 + i][mt] = __builtin_amdgcn_mfma_f32_16x16x32_bf16(wf[i], xf[mt], acc[nh * 4 + i][mt], 0, 0, 0);
;     }
;   } while (++kt < nk);
	v_mfma_f32_16x16x32_bf16 v[44:47], v[156:159], v[24:27], v[44:47]
	v_mfma_f32_16x16x32_bf16 v[48:51], v[156:159], v[108:111], v[48:51]
	v_mfma_f32_16x16x32_bf16 v[52:55], v[156:159], v[148:151], v[52:55]
	v_mfma_f32_16x16x32_bf16 v[28:31], v[156:159], v[152:155], v[28:31]
	s_waitcnt lgkmcnt(2)
	v_mfma_f32_16x16x32_bf16 v[56:59], v[160:163], v[24:27], v[56:59]
	v_mfma_f32_16x16x32_bf16 v[60:63], v[160:163], v[108:111], v[60:63]
	v_mfma_f32_16x16x32_bf16 v[64:67], v[160:163], v[148:151], v[64:67]
	v_mfma_f32_16x16x32_bf16 v[32:35], v[160:163], v[152:155], v[32:35]
	s_waitcnt lgkmcnt(1)
	v_mfma_f32_16x16x32_bf16 v[68:71], v[164:167], v[24:27], v[68:71]
	v_mfma_f32_16x16x32_bf16 v[72:75], v[164:167], v[108:111], v[72:75]
	v_mfma_f32_16x16x32_bf16 v[76:79], v[164:167], v[148:151], v[76:79]
	v_mfma_f32_16x16x32_bf16 v[36:39], v[164:167], v[152:155], v[36:39]
	s_waitcnt lgkmcnt(0)
	v_mfma_f32_16x16x32_bf16 v[80:83], v[168:171], v[24:27], v[80:83]
	v_mfma_f32_16x16x32_bf16 v[84:87], v[168:171], v[108:111], v[84:87]
	v_mfma_f32_16x16x32_bf16 v[92:95], v[168:171], v[148:151], v[92:95]
	v_mfma_f32_16x16x32_bf16 v[40:43], v[168:171], v[152:155], v[40:43]
	ds_read_b128 v[156:159], v10 offset:20480
	ds_read_b128 v[160:163], v10 offset:21504
	ds_read_b128 v[164:167], v10 offset:22528
	ds_read_b128 v[168:171], v10 offset:23552
	s_waitcnt vmcnt(6)
	s_waitcnt lgkmcnt(0)
	s_barrier
	s_mov_b32 s19, m0
	s_mov_b32 m0, s14
	s_nop 0
	global_load_lds_dwordx4 v[88:89], off
	s_mov_b32 m0, s19
	v_mfma_f32_16x16x32_bf16 v[112:115], v[156:159], v[24:27], v[112:115]
	v_mfma_f32_16x16x32_bf16 v[124:127], v[160:163], v[24:27], v[124:127]
	v_mfma_f32_16x16x32_bf16 v[136:139], v[164:167], v[24:27], v[136:139]
	v_mfma_f32_16x16x32_bf16 v[12:15], v[168:171], v[24:27], v[12:15]
	v_lshl_add_u64 v[24:25], v[6:7], 0, s[20:21]
	s_mov_b32 s14, m0
	s_mov_b32 m0, s15
	s_nop 0
	global_load_lds_dwordx4 v[24:25], off
	s_mov_b32 m0, s14
	s_mov_b64 s[14:15], 0x4180
	v_lshl_add_u64 v[24:25], v[6:7], 0, s[14:15]
	s_mov_b32 s14, m0
	s_mov_b32 m0, s16
	s_nop 0
	global_load_lds_dwordx4 v[24:25], off
	s_mov_b32 m0, s14
	s_mov_b64 s[14:15], 0x6180
	v_lshl_add_u64 v[24:25], v[6:7], 0, s[14:15]
	s_mov_b32 s14, m0
	s_mov_b32 m0, s17
	s_nop 0
	global_load_lds_dwordx4 v[24:25], off
	s_mov_b32 m0, s14
	v_lshl_add_u64 v[24:25], v[8:9], 0, s[20:21]
	s_mov_b32 s14, m0
	s_mov_b32 m0, s13
	s_nop 0
	global_load_lds_dwordx4 v[172:173], off
	s_mov_b32 m0, s14
	s_mov_b32 s13, m0
	s_mov_b32 m0, s18
	s_nop 0
	global_load_lds_dwordx4 v[24:25], off
	s_mov_b32 m0, s13
	v_mfma_f32_16x16x32_bf16 v[116:119], v[156:159], v[108:111], v[116:119]
	s_mov_b64 s[14:15], 0x1c0
	v_lshl_add_u64 v[88:89], v[6:7], 0, s[14:15]
	v_lshl_add_u64 v[172:173], v[8:9], 0, s[14:15]
	v_mfma_f32_16x16x32_bf16 v[120:123], v[156:159], v[148:151], v[120:123]
	s_mov_b64 s[14:15], 0x21c0
	s_mov_b64 s[16:17], 0x41c0
	v_mfma_f32_16x16x32_bf16 v[96:99], v[156:159], v[152:155], v[96:99]
	v_mfma_f32_16x16x32_bf16 v[128:131], v[160:163], v[108:111], v[128:131]
	v_mfma_f32_16x16x32_bf16 v[132:135], v[160:163], v[148:151], v[132:135]
	v_mfma_f32_16x16x32_bf16 v[100:103], v[160:163], v[152:155], v[100:103]
	v_mfma_f32_16x16x32_bf16 v[140:143], v[164:167], v[108:111], v[140:143]
	v_mfma_f32_16x16x32_bf16 v[144:147], v[164:167], v[148:151], v[144:147]
	v_mfma_f32_16x16x32_bf16 v[104:107], v[164:167], v[152:155], v[104:107]
	v_mfma_f32_16x16x32_bf16 v[16:19], v[168:171], v[108:111], v[16:19]
	v_mfma_f32_16x16x32_bf16 v[20:23], v[168:171], v[148:151], v[20:23]
	v_mfma_f32_16x16x32_bf16 v[2:5], v[168:171], v[152:155], v[2:5]
	ds_read_b128 v[24:27], v11 offset:24576
	ds_read_b128 v[108:111], v11 offset:25600
	ds_read_b128 v[148:151], v11 offset:26624
	ds_read_b128 v[152:155], v11 offset:27648
	ds_read_b128 v[156:159], v10 offset:40960
	ds_read_b128 v[160:163], v10 offset:41984
	ds_read_b128 v[164:167], v10 offset:43008
	ds_read_b128 v[168:171], v10 offset:44032
	s_waitcnt lgkmcnt(3)
	v_mfma_f32_16x16x32_bf16 v[44:47], v[156:159], v[24:27], v[44:47]
	v_mfma_f32_16x16x32_bf16 v[48:51], v[156:159], v[108:111], v[48:51]
	v_mfma_f32_16x16x32_bf16 v[52:55], v[156:159], v[148:151], v[52:55]
	v_mfma_f32_16x16x32_bf16 v[28:31], v[156:159], v[152:155], v[28:31]
	s_waitcnt lgkmcnt(2)
	v_mfma_f32_16x16x32_bf16 v[56:59], v[160:163], v[24:27], v[56:59]
	v_mfma_f32_16x16x32_bf16 v[60:63], v[160:163], v[108:111], v[60:63]
	v_mfma_f32_16x16x32_bf16 v[64:67], v[160:163], v[148:151], v[64:67]
	v_mfma_f32_16x16x32_bf16 v[32:35], v[160:163], v[152:155], v[32:35]
	s_waitcnt lgkmcnt(1)
	v_mfma_f32_16x16x32_bf16 v[68:71], v[164:167], v[24:27], v[68:71]
	v_mfma_f32_16x16x32_bf16 v[72:75], v[164:167], v[108:111], v[72:75]
	v_mfma_f32_16x16x32_bf16 v[76:79], v[164:167], v[148:151], v[76:79]
	v_mfma_f32_16x16x32_bf16 v[36:39], v[164:167], v[152:155], v[36:39]
	s_waitcnt lgkmcnt(0)
	v_mfma_f32_16x16x32_bf16 v[80:83], v[168:171], v[24:27], v[80:83]
	v_mfma_f32_16x16x32_bf16 v[84:87], v[168:171], v[108:111], v[84:87]
	v_mfma_f32_16x16x32_bf16 v[92:95], v[168:171], v[148:151], v[92:95]
	v_mfma_f32_16x16x32_bf16 v[40:43], v[168:171], v[152:155], v[40:43]
	ds_read_b128 v[156:159], v10 offset:45056
	ds_read_b128 v[160:163], v10 offset:46080
	ds_read_b128 v[164:167], v10 offset:47104
	ds_read_b128 v[168:171], v10 offset:48128
	s_waitcnt vmcnt(6)
	s_waitcnt lgkmcnt(0)
	s_barrier
; template <int N> DI void wait_vm() { asm volatile("s_waitcnt vmcnt(%0)" ::"n"(N) : "memory"); }
; template <int BM, class Epi>
; DI void gemm_dma(const u16* __restrict__ X, long ldx, const u16* __restrict__ W, long ldw, int K, char* smem,
;                  int m0, int n0, const Epi& epi) {
;     ...
;   do {
;     if (kt + D - 2 < nk) wait_vm<PW * (D - 2)>(); else wait_vm<0>();
;     __syncthreads();
;     if (kt + D - 1 < nk) GD_ISSUE(nxt)
;     nxt = (nxt + 1 == D) ? 0 : nxt + 1;
;     const char* base = smem + cur * STG;
;     cur = (cur + 1 == D) ? 0 : cur + 1;
;     bf16x8 xf[MT];
; #pragma unroll
;     for (int i = 0; i < MT; ++i) xf[i] = *(const bf16x8*)(base + (xrow0 + i * 16) * 64 + rd);
; #pragma unroll
;     for (int nh = 0; nh < NT / 4; ++nh) {
;       bf16x8 wf[4];
; #pragma unroll
;       for (int i = 0; i < 4; ++i) wf[i] = *(const bf16x8*)(base + BM * 64 + (wrow0 + (nh * 4 + i) * 16) * 64 + rd);
; #pragma unroll
;       for (int i = 0; i < 4; ++i)
; #pragma unroll
;         for (int mt = 0; mt < MT; ++mt)
;           acc[nh * 4 + i][mt] = __builtin_amdgcn_mfma_f32_16x16x32_bf16(wf[i], xf[mt], acc[nh * 4 + i][mt], 0, 0, 0);
;     }
;   } while (++kt < nk);
	s_mov_b32 s13, m0
	s_mov_b32 m0, s7
	s_nop 0
	global_load_lds_dwordx4 v[88:89], off
	s_mov_b32 m0, s13
	v_mfma_f32_16x16x32_bf16 v[112:115], v[156:159], v[24:27], v[112:115]
	v_mfma_f32_16x16x32_bf16 v[124:127], v[160:163], v[24:27], v[124:127]
	v_mfma_f32_16x16x32_bf16 v[136:139], v[164:167], v[24:27], v[136:139]
	v_mfma_f32_16x16x32_bf16 v[12:15], v[168:171], v[24:27], v[12:15]
	v_lshl_add_u64 v[24:25], v[6:7], 0, s[14:15]
	s_mov_b32 s7, m0
	s_mov_b32 m0, s8
	s_nop 0
	global_load_lds_dwordx4 v[24:25], off
	s_mov_b32 m0, s7
	v_lshl_add_u64 v[24:25], v[6:7], 0, s[16:17]
	s_mov_b32 s7, m0
	s_mov_b32 m0, s9
	s_nop 0
	global_load_lds_dwordx4 v[24:25], off
	s_mov_b32 m0, s7
	s_mov_b64 s[8:9], 0x61c0
	v_lshl_add_u64 v[6:7], v[6:7], 0, s[8:9]
	s_mov_b32 s7, m0
	s_mov_b32 m0, s10
	s_nop 0
	global_load_lds_dwordx4 v[6:7], off
	s_mov_b32 m0, s7
	v_lshl_add_u64 v[6:7], v[8:9], 0, s[14:15]
	s_mov_b32 s7, m0
	s_mov_b32 m0, s11
	s_nop 0
	global_load_lds_dwordx4 v[172:173], off
	s_mov_b32 m0, s7
	v_mfma_f32_16x16x32_bf16 v[116:119], v[156:159], v[108:111], v[116:119]
	s_mov_b32 s7, m0
	s_mov_b32 m0, s12
	s_nop 0
	global_load_lds_dwordx4 v[6:7], off
	s_mov_b32 m0, s7
	v_mfma_f32_16x16x32_bf16 v[120:123], v[156:159], v[148:151], v[120:123]
	v_mfma_f32_16x16x32_bf16 v[96:99], v[156:159], v[152:155], v[96:99]
	v_mfma_f32_16x16x32_bf16 v[128:131], v[160:163], v[108:111], v[128:131]
	v_mfma_f32_16x16x32_bf16 v[132:135], v[160:163], v[148:151], v[132:135]
	v_mfma_f32_16x16x32_bf16 v[100:103], v[160:163], v[152:155], v[100:103]
	v_mfma_f32_16x16x32_bf16 v[140:143], v[164:167], v[108:111], v[140:143]
	v_mfma_f32_16x16x32_bf16 v[144:147], v[164:167], v[148:151], v[144:147]
	v_mfma_f32_16x16x32_bf16 v[104:107], v[164:167], v[152:155], v[104:107]
	v_mfma_f32_16x16x32_bf16 v[16:19], v[168:171], v[108:111], v[16:19]
	v_mfma_f32_16x16x32_bf16 v[20:23], v[168:171], v[148:151], v[20:23]
	v_mfma_f32_16x16x32_bf16 v[2:5], v[168:171], v[152:155], v[2:5]
	ds_read_b128 v[6:9], v11 offset:49152
	ds_read_b128 v[24:27], v11 offset:50176
	ds_read_b128 v[108:111], v11 offset:51200
	ds_read_b128 v[148:151], v11 offset:52224
	ds_read_b128 v[152:155], v174
	ds_read_b128 v[156:159], v175
	ds_read_b128 v[160:163], v176
	ds_read_b128 v[164:167], v177
	s_waitcnt lgkmcnt(3)
	v_mfma_f32_16x16x32_bf16 v[44:47], v[152:155], v[6:9], v[44:47]
	v_mfma_f32_16x16x32_bf16 v[48:51], v[152:155], v[24:27], v[48:51]
	v_mfma_f32_16x16x32_bf16 v[52:55], v[152:155], v[108:111], v[52:55]
	v_mfma_f32_16x16x32_bf16 v[28:31], v[152:155], v[148:151], v[28:31]
	s_waitcnt lgkmcnt(2)
	v_mfma_f32_16x16x32_bf16 v[56:59], v[156:159], v[6:9], v[56:59]
	v_mfma_f32_16x16x32_bf16 v[60:63], v[156:159], v[24:27], v[60:63]
	v_mfma_f32_16x16x32_bf16 v[64:67], v[156:159], v[108:111], v[64:67]
	v_mfma_f32_16x16x32_bf16 v[32:35], v[156:159], v[148:151], v[32:35]
	s_waitcnt lgkmcnt(1)
	v_mfma_f32_16x16x32_bf16 v[68:71], v[160:163], v[6:9], v[68:71]
	v_mfma_f32_16x16x32_bf16 v[72:75], v[160:163], v[24:27], v[72:75]
	v_mfma_f32_16x16x32_bf16 v[76:79], v[160:163], v[108:111], v[76:79]
	v_mfma_f32_16x16x32_bf16 v[36:39], v[160:163], v[148:151], v[36:39]
	s_waitcnt lgkmcnt(0)
	v_mfma_f32_16x16x32_bf16 v[80:83], v[164:167], v[6:9], v[80:83]
	v_mfma_f32_16x16x32_bf16 v[84:87], v[164:167], v[24:27], v[84:87]
	v_mfma_f32_16x16x32_bf16 v[92:95], v[164:167], v[108:111], v[92:95]
	v_mfma_f32_16x16x32_bf16 v[40:43], v[164:167], v[148:151], v[40:43]
	ds_read_b128 v[152:155], v178
	ds_read_b128 v[156:159], v179
	ds_read_b128 v[160:163], v180
	ds_read_b128 v[164:167], v181
	s_waitcnt vmcnt(6)
	s_waitcnt lgkmcnt(0)
	v_mfma_f32_16x16x32_bf16 v[112:115], v[152:155], v[6:9], v[112:115]
	s_barrier
	v_mfma_f32_16x16x32_bf16 v[116:119], v[152:155], v[24:27], v[116:119]
	v_mfma_f32_16x16x32_bf16 v[120:123], v[152:155], v[108:111], v[120:123]
	v_mfma_f32_16x16x32_bf16 v[96:99], v[152:155], v[148:151], v[96:99]
	v_mfma_f32_16x16x32_bf16 v[124:127], v[156:159], v[6:9], v[124:127]
	v_mfma_f32_16x16x32_bf16 v[128:131], v[156:159], v[24:27], v[128:131]
	v_mfma_f32_16x16x32_bf16 v[132:135], v[156:159], v[108:111], v[132:135]
	v_mfma_f32_16x16x32_bf16 v[100:103], v[156:159], v[148:151], v[100:103]
	v_mfma_f32_16x16x32_bf16 v[136:139], v[160:163], v[6:9], v[136:139]
	v_mfma_f32_16x16x32_bf16 v[140:143], v[160:163], v[24:27], v[140:143]
	v_mfma_f32_16x16x32_bf16 v[144:147], v[160:163], v[108:111], v[144:147]
	v_mfma_f32_16x16x32_bf16 v[104:107], v[160:163], v[148:151], v[104:107]
	v_mfma_f32_16x16x32_bf16 v[6:9], v[164:167], v[6:9], v[12:15]
	v_mfma_f32_16x16x32_bf16 v[12:15], v[164:167], v[24:27], v[16:19]
	v_mfma_f32_16x16x32_bf16 v[16:19], v[164:167], v[108:111], v[20:23]
	v_mfma_f32_16x16x32_bf16 v[2:5], v[164:167], v[148:151], v[2:5]
	s_nop 1
	ds_read_b128 v[20:23], v10 offset:23552
	ds_read_b128 v[24:27], v10 offset:22528
	ds_read_b128 v[108:111], v10 offset:21504
	ds_read_b128 v[148:151], v10 offset:20480
	ds_read_b128 v[152:155], v10 offset:19456
	ds_read_b128 v[156:159], v10 offset:18432
	ds_read_b128 v[160:163], v10 offset:17408
	ds_read_b128 v[164:167], v10 offset:16384
	ds_read_b128 v[168:171], v11 offset:3072
	ds_read_b128 v[172:175], v11 offset:2048
	ds_read_b128 v[176:179], v11 offset:1024
	ds_read_b128 v[186:189], v11
	s_waitcnt vmcnt(0)
	s_waitcnt lgkmcnt(0)
	v_mfma_f32_16x16x32_bf16 v[44:47], v[164:167], v[186:189], v[44:47]
	s_barrier
; template <int N> DI void wait_vm() { asm volatile("s_waitcnt vmcnt(%0)" ::"n"(N) : "memory"); }
; DI void st_bf4(u16* p, float a, float b, float c, float d) { *(uint2*)p = make_uint2(pk2(a, b), pk2(c, d)); }
; template <int BM, class Epi>
; DI void gemm_dma(const u16* __restrict__ X, long ldx, const u16* __restrict__ W, long ldw, int K, char* smem,
;                  int m0, int n0, const Epi& epi) {
;     ...
;   do {
;     if (kt + D - 2 < nk) wait_vm<PW * (D - 2)>(); else wait_vm<0>();
;     __syncthreads();
;     if (kt + D - 1 < nk) GD_ISSUE(nxt)
;     nxt = (nxt + 1 == D) ? 0 : nxt + 1;
;     const char* base = smem + cur * STG;
;     cur = (cur + 1 == D) ? 0 : cur + 1;
;     bf16x8 xf[MT];
; #pragma unroll
;     for (int i = 0; i < MT; ++i) xf[i] = *(const bf16x8*)(base + (xrow0 + i * 16) * 64 + rd);
; #pragma unroll
;     for (int nh = 0; nh < NT / 4; ++nh) {
;       bf16x8 wf[4];
; #pragma unroll
;       for (int i = 0; i < 4; ++i) wf[i] = *(const bf16x8*)(base + BM * 64 + (wrow0 + (nh * 4 + i) * 16) * 64 + rd);
; #pragma unroll
;       for (int i = 0; i < 4; ++i)
; #pragma unroll
;         for (int mt = 0; mt < MT; ++mt)
;           acc[nh * 4 + i][mt] = __builtin_amdgcn_mfma_f32_16x16x32_bf16(wf[i], xf[mt], acc[nh * 4 + i][mt], 0, 0, 0);
;     }
;   } while (++kt < nk);
;   template <int NT, int MT> DI void run(f32x4 (&acc)[NT][MT], int mb, int nb) const {
; #pragma unroll
;     for (int nt = 0; nt < NT; ++nt)
; #pragma unroll
;       for (int mt = 0; mt < MT; ++mt) {
;         f32x4 v = acc[nt][mt];
;         st_bf4(C + (size_t)(mb + mt * 16) * ldc + nb + nt * 16, v[0], v[1], v[2], v[3]);
;       }
;   }
	v_mfma_f32_16x16x32_bf16 v[48:51], v[164:167], v[176:179], v[48:51]
	v_mfma_f32_16x16x32_bf16 v[52:55], v[164:167], v[172:175], v[52:55]
	v_mfma_f32_16x16x32_bf16 v[28:31], v[164:167], v[168:171], v[28:31]
	v_mfma_f32_16x16x32_bf16 v[56:59], v[160:163], v[186:189], v[56:59]
	v_mfma_f32_16x16x32_bf16 v[60:63], v[160:163], v[176:179], v[60:63]
	v_mfma_f32_16x16x32_bf16 v[64:67], v[160:163], v[172:175], v[64:67]
	v_mfma_f32_16x16x32_bf16 v[32:35], v[160:163], v[168:171], v[32:35]
	v_mfma_f32_16x16x32_bf16 v[68:71], v[156:159], v[186:189], v[68:71]
	v_mfma_f32_16x16x32_bf16 v[72:75], v[156:159], v[176:179], v[72:75]
	v_mfma_f32_16x16x32_bf16 v[76:79], v[156:159], v[172:175], v[76:79]
	v_mfma_f32_16x16x32_bf16 v[36:39], v[156:159], v[168:171], v[36:39]
	v_mfma_f32_16x16x32_bf16 v[156:159], v[152:155], v[186:189], v[80:83]
	v_mfma_f32_16x16x32_bf16 v[86:89], v[152:155], v[176:179], v[84:87]
	v_mfma_f32_16x16x32_bf16 v[92:95], v[152:155], v[172:175], v[92:95]
	v_mfma_f32_16x16x32_bf16 v[152:155], v[152:155], v[168:171], v[40:43]
	v_mfma_f32_16x16x32_bf16 v[112:115], v[148:151], v[186:189], v[112:115]
	v_mfma_f32_16x16x32_bf16 v[116:119], v[148:151], v[176:179], v[116:119]
	v_mfma_f32_16x16x32_bf16 v[120:123], v[148:151], v[172:175], v[120:123]
	v_mfma_f32_16x16x32_bf16 v[96:99], v[148:151], v[168:171], v[96:99]
	v_mfma_f32_16x16x32_bf16 v[124:127], v[108:111], v[186:189], v[124:127]
	v_mfma_f32_16x16x32_bf16 v[128:131], v[108:111], v[176:179], v[128:131]
	v_mfma_f32_16x16x32_bf16 v[132:135], v[108:111], v[172:175], v[132:135]
	v_mfma_f32_16x16x32_bf16 v[100:103], v[108:111], v[168:171], v[100:103]
	v_mfma_f32_16x16x32_bf16 v[108:111], v[24:27], v[186:189], v[136:139]
	v_mfma_f32_16x16x32_bf16 v[136:139], v[24:27], v[176:179], v[140:143]
	v_mfma_f32_16x16x32_bf16 v[140:143], v[24:27], v[172:175], v[144:147]
	v_mfma_f32_16x16x32_bf16 v[104:107], v[24:27], v[168:171], v[104:107]
	v_mfma_f32_16x16x32_bf16 v[6:9], v[20:23], v[186:189], v[6:9]
	v_mfma_f32_16x16x32_bf16 v[144:147], v[20:23], v[176:179], v[12:15]
	v_mfma_f32_16x16x32_bf16 v[148:151], v[20:23], v[172:175], v[16:19]
	v_mfma_f32_16x16x32_bf16 v[2:5], v[20:23], v[168:171], v[2:5]
	s_nop 0
	ds_read_b128 v[12:15], v11 offset:24576
	ds_read_b128 v[160:163], v11 offset:25600
	ds_read_b128 v[164:167], v11 offset:26624
	ds_read_b128 v[168:171], v11 offset:27648
	ds_read_b128 v[16:19], v10 offset:40960
	ds_read_b128 v[20:23], v10 offset:41984
	ds_read_b128 v[24:27], v10 offset:43008
	ds_read_b128 v[172:175], v10 offset:44032
	s_waitcnt lgkmcnt(3)
	v_mfma_f32_16x16x32_bf16 v[176:179], v[16:19], v[12:15], v[44:47]
	v_mfma_f32_16x16x32_bf16 v[186:189], v[16:19], v[160:163], v[48:51]
	v_mfma_f32_16x16x32_bf16 v[190:193], v[16:19], v[164:167], v[52:55]
	v_mfma_f32_16x16x32_bf16 v[194:197], v[16:19], v[168:171], v[28:31]
	s_waitcnt lgkmcnt(2)
	v_mfma_f32_16x16x32_bf16 v[224:227], v[20:23], v[12:15], v[56:59]
	v_mfma_f32_16x16x32_bf16 v[228:231], v[20:23], v[160:163], v[60:63]
	v_mfma_f32_16x16x32_bf16 v[232:235], v[20:23], v[164:167], v[64:67]
	v_mfma_f32_16x16x32_bf16 v[236:239], v[20:23], v[168:171], v[32:35]
	s_waitcnt lgkmcnt(1)
	v_mfma_f32_16x16x32_bf16 v[240:243], v[24:27], v[12:15], v[68:71]
	v_mfma_f32_16x16x32_bf16 v[66:69], v[24:27], v[168:171], v[36:39]
	s_waitcnt lgkmcnt(0)
	v_mfma_f32_16x16x32_bf16 v[42:45], v[172:175], v[164:167], v[92:95]
	v_mfma_f32_16x16x32_bf16 v[34:37], v[172:175], v[168:171], v[152:155]
	ds_read_b128 v[16:19], v10 offset:45056
	ds_read_b128 v[20:23], v10 offset:46080
	ds_read_b128 v[92:95], v10 offset:47104
	ds_read_b128 v[152:155], v10 offset:48128
	s_nop 0
	v_cvt_pk_bf16_f32 v66, v66, v67
	v_cvt_pk_bf16_f32 v67, v68, v69
	v_mfma_f32_16x16x32_bf16 v[82:85], v[24:27], v[160:163], v[72:75]
	v_cvt_pk_bf16_f32 v34, v34, v35
	v_cvt_pk_bf16_f32 v35, v36, v37
	v_cvt_pk_bf16_f32 v42, v42, v43
	v_mfma_f32_16x16x32_bf16 v[74:77], v[24:27], v[164:167], v[76:79]
	v_cvt_pk_bf16_f32 v43, v44, v45
	s_nop 2
	v_cvt_pk_bf16_f32 v82, v82, v83
	v_cvt_pk_bf16_f32 v83, v84, v85
	v_mfma_f32_16x16x32_bf16 v[50:53], v[172:175], v[160:163], v[86:89]
	s_waitcnt lgkmcnt(3)
	v_mfma_f32_16x16x32_bf16 v[112:115], v[16:19], v[12:15], v[112:115]
	v_cvt_pk_bf16_f32 v74, v74, v75
	v_cvt_pk_bf16_f32 v75, v76, v77
	s_nop 3
	v_cvt_pk_bf16_f32 v50, v50, v51
	v_mfma_f32_16x16x32_bf16 v[86:89], v[16:19], v[160:163], v[116:119]
	v_cvt_pk_bf16_f32 v51, v52, v53
	v_mfma_f32_16x16x32_bf16 v[78:81], v[16:19], v[164:167], v[120:123]
	v_mfma_f32_16x16x32_bf16 v[70:73], v[16:19], v[168:171], v[96:99]
	s_waitcnt lgkmcnt(2)
	v_mfma_f32_16x16x32_bf16 v[62:65], v[20:23], v[12:15], v[124:127]
	s_nop 0
	v_cvt_pk_bf16_f32 v96, v186, v187
	v_cvt_pk_bf16_f32 v97, v188, v189
	v_cvt_pk_bf16_f32 v98, v190, v191
	v_mfma_f32_16x16x32_bf16 v[54:57], v[20:23], v[160:163], v[128:131]
	v_cvt_pk_bf16_f32 v99, v192, v193
	v_mfma_f32_16x16x32_bf16 v[46:49], v[20:23], v[164:167], v[132:135]
	v_mfma_f32_16x16x32_bf16 v[38:41], v[20:23], v[168:171], v[100:103]
	s_waitcnt lgkmcnt(1)
; DI void st_bf4(u16* p, float a, float b, float c, float d) { *(uint2*)p = make_uint2(pk2(a, b), pk2(c, d)); }
; template <int BM, class Epi>
; DI void gemm_dma(const u16* __restrict__ X, long ldx, const u16* __restrict__ W, long ldw, int K, char* smem,
;                  int m0, int n0, const Epi& epi) {
;     ...
;       for (int i = 0; i < 4; ++i)
; #pragma unroll
;         for (int mt = 0; mt < MT; ++mt)
;           acc[nh * 4 + i][mt] = __builtin_amdgcn_mfma_f32_16x16x32_bf16(wf[i], xf[mt], acc[nh * 4 + i][mt], 0, 0, 0);
;     }
;   } while (++kt < nk);
;     ...
;   epi.run(acc, m0 + xrow0 + lr, n0 + wrow0 + 4 * g);
;   template <int NT, int MT> DI void run(f32x4 (&acc)[NT][MT], int mb, int nb) const {
; #pragma unroll
;     for (int nt = 0; nt < NT; ++nt)
; #pragma unroll
;       for (int mt = 0; mt < MT; ++mt) {
;         f32x4 v = acc[nt][mt];
;         st_bf4(C + (size_t)(mb + mt * 16) * ldc + nb + nt * 16, v[0], v[1], v[2], v[3]);
;       }
;   }
	v_mfma_f32_16x16x32_bf16 v[30:33], v[92:95], v[12:15], v[108:111]
	v_mfma_f32_16x16x32_bf16 v[26:29], v[92:95], v[160:163], v[136:139]
	v_mfma_f32_16x16x32_bf16 v[22:25], v[92:95], v[164:167], v[140:143]
	s_nop 5
	v_cvt_pk_bf16_f32 v30, v30, v31
	v_cvt_pk_bf16_f32 v31, v32, v33
	v_cvt_pk_bf16_f32 v26, v26, v27
	v_mfma_f32_16x16x32_bf16 v[18:21], v[92:95], v[168:171], v[104:107]
	v_or_b32_e32 v94, v91, v90
	v_ashrrev_i32_e32 v95, 31, v94
	v_lshlrev_b64 v[90:91], 11, v[94:95]
	v_lshl_add_u64 v[90:91], s[92:93], 0, v[90:91]
	v_lshl_add_u64 v[90:91], v[90:91], 0, v[182:183]
	v_cvt_pk_bf16_f32 v92, v176, v177
	v_cvt_pk_bf16_f32 v93, v178, v179
	global_store_dwordx2 v[90:91], v[92:93], off
	v_or_b32_e32 v92, 16, v94
	v_ashrrev_i32_e32 v93, 31, v92
	v_lshlrev_b64 v[92:93], 11, v[92:93]
	v_lshl_add_u64 v[92:93], s[92:93], 0, v[92:93]
	v_lshl_add_u64 v[92:93], v[92:93], 0, v[182:183]
	global_store_dwordx2 v[92:93], v[96:97], off
	v_or_b32_e32 v96, 32, v94
	v_or_b32_e32 v94, 48, v94
	v_ashrrev_i32_e32 v95, 31, v94
	v_lshlrev_b64 v[94:95], 11, v[94:95]
	v_ashrrev_i32_e32 v97, 31, v96
	v_lshl_add_u64 v[94:95], s[92:93], 0, v[94:95]
	v_lshlrev_b64 v[96:97], 11, v[96:97]
	v_lshl_add_u64 v[94:95], v[94:95], 0, v[182:183]
	v_lshl_add_u64 v[96:97], s[92:93], 0, v[96:97]
	global_store_dwordx2 v[94:95], v[34:35], off offset:96
	v_cvt_pk_bf16_f32 v34, v112, v113
	v_cvt_pk_bf16_f32 v35, v114, v115
	v_lshl_add_u64 v[96:97], v[96:97], 0, v[182:183]
	global_store_dwordx2 v[90:91], v[34:35], off offset:128
	v_cvt_pk_bf16_f32 v34, v86, v87
	v_cvt_pk_bf16_f32 v35, v88, v89
	global_store_dwordx2 v[96:97], v[98:99], off
	v_cvt_pk_bf16_f32 v98, v194, v195
	v_cvt_pk_bf16_f32 v99, v196, v197
	global_store_dwordx2 v[92:93], v[34:35], off offset:128
	v_cvt_pk_bf16_f32 v34, v78, v79
	v_cvt_pk_bf16_f32 v35, v80, v81
	v_mfma_f32_16x16x32_bf16 v[58:61], v[172:175], v[12:15], v[156:159]
	global_store_dwordx2 v[94:95], v[98:99], off
	v_cvt_pk_bf16_f32 v98, v224, v225
	v_cvt_pk_bf16_f32 v99, v226, v227
	s_waitcnt lgkmcnt(0)
	v_mfma_f32_16x16x32_bf16 v[14:17], v[152:155], v[12:15], v[6:9]
	global_store_dwordx2 v[96:97], v[34:35], off offset:128
	v_cvt_pk_bf16_f32 v34, v70, v71
	v_cvt_pk_bf16_f32 v35, v72, v73
	v_mfma_f32_16x16x32_bf16 v[10:13], v[152:155], v[160:163], v[144:147]
	global_store_dwordx2 v[90:91], v[98:99], off offset:32
	v_cvt_pk_bf16_f32 v98, v228, v229
	v_cvt_pk_bf16_f32 v99, v230, v231
	v_mfma_f32_16x16x32_bf16 v[6:9], v[152:155], v[164:167], v[148:151]
	global_store_dwordx2 v[94:95], v[34:35], off offset:128
	v_cvt_pk_bf16_f32 v34, v62, v63
	v_cvt_pk_bf16_f32 v35, v64, v65
	v_mfma_f32_16x16x32_bf16 v[2:5], v[152:155], v[168:171], v[2:5]
	global_store_dwordx2 v[92:93], v[98:99], off offset:32
	v_cvt_pk_bf16_f32 v98, v232, v233
	v_cvt_pk_bf16_f32 v99, v234, v235
	global_store_dwordx2 v[90:91], v[34:35], off offset:160
	v_cvt_pk_bf16_f32 v34, v54, v55
	v_cvt_pk_bf16_f32 v35, v56, v57
	global_store_dwordx2 v[96:97], v[98:99], off offset:32
	v_cvt_pk_bf16_f32 v98, v236, v237
	v_cvt_pk_bf16_f32 v99, v238, v239
	global_store_dwordx2 v[92:93], v[34:35], off offset:160
	v_cvt_pk_bf16_f32 v34, v46, v47
	v_cvt_pk_bf16_f32 v35, v48, v49
	global_store_dwordx2 v[94:95], v[98:99], off offset:32
	v_cvt_pk_bf16_f32 v98, v240, v241
	v_cvt_pk_bf16_f32 v99, v242, v243
	v_cvt_pk_bf16_f32 v58, v58, v59
	v_cvt_pk_bf16_f32 v59, v60, v61
	global_store_dwordx2 v[96:97], v[34:35], off offset:160
	v_cvt_pk_bf16_f32 v34, v38, v39
	v_cvt_pk_bf16_f32 v35, v40, v41
	v_cvt_pk_bf16_f32 v27, v28, v29
	v_cvt_pk_bf16_f32 v22, v22, v23
	v_cvt_pk_bf16_f32 v23, v24, v25
	v_cvt_pk_bf16_f32 v18, v18, v19
	v_cvt_pk_bf16_f32 v19, v20, v21
	v_cvt_pk_bf16_f32 v14, v14, v15
	v_cvt_pk_bf16_f32 v15, v16, v17
	v_cvt_pk_bf16_f32 v10, v10, v11
	v_cvt_pk_bf16_f32 v11, v12, v13
	v_cvt_pk_bf16_f32 v6, v6, v7
	v_cvt_pk_bf16_f32 v7, v8, v9
	v_cvt_pk_bf16_f32 v2, v2, v3
	v_cvt_pk_bf16_f32 v3, v4, v5
	global_store_dwordx2 v[90:91], v[98:99], off offset:64
	global_store_dwordx2 v[92:93], v[82:83], off offset:64
	global_store_dwordx2 v[96:97], v[74:75], off offset:64
	global_store_dwordx2 v[94:95], v[66:67], off offset:64
	global_store_dwordx2 v[90:91], v[58:59], off offset:96
	global_store_dwordx2 v[92:93], v[50:51], off offset:96
	global_store_dwordx2 v[96:97], v[42:43], off offset:96
	global_store_dwordx2 v[94:95], v[34:35], off offset:160
	global_store_dwordx2 v[90:91], v[30:31], off offset:192
	global_store_dwordx2 v[92:93], v[26:27], off offset:192
	global_store_dwordx2 v[96:97], v[22:23], off offset:192
	global_store_dwordx2 v[94:95], v[18:19], off offset:192
	global_store_dwordx2 v[90:91], v[14:15], off offset:224
	global_store_dwordx2 v[92:93], v[10:11], off offset:224
	global_store_dwordx2 v[96:97], v[6:7], off offset:224
	global_store_dwordx2 v[94:95], v[2:3], off offset:224

; DI int get_tid() { int t = threadIdx.x; asm volatile("" : "+v"(t)); return t; }
; DI float zero_f() { float z = 0.f; asm volatile("" : "+v"(z)); return z; }
; template <int N> DI void wait_vm() { asm volatile("s_waitcnt vmcnt(%0)" ::"n"(N) : "memory"); }
; template <int BM, class Epi>
; DI void gemm_dma(const u16* __restrict__ X, long ldx, const u16* __restrict__ W, long ldw, int K, char* smem,
;                  int m0, int n0, const Epi& epi) {
;     ...
;   const int tid = get_tid(), lane = tid & 63, wave = tid >> 6;
;   const int lr = lane & 15, g = lane >> 4;
;   const int rd = lr * 64 + ((g ^ ((4 - (lr >> 2)) & 3)) << 4);
;   const int xrow0 = BIG ? wave * 64 : (wave & 1) * (BM / 2);
;   const int wrow0 = BIG ? 0 : (wave >> 1) * 64;
;   f32x4 acc[NT][MT];
;   { const float z = zero_f();
; #pragma unroll
;   for (int a = 0; a < NT; ++a)
; #pragma unroll
;     for (int b = 0; b < MT; ++b) acc[a][b] = (f32x4){z, z, z, z}; }
;   const int wu = __builtin_amdgcn_readfirstlane(wave);
;   const unsigned sbase = (unsigned)__builtin_amdgcn_readfirstlane((int)(unsigned)(size_t)smem);
;   const int r16 = lane >> 2, chunk = (lane & 3) ^ ((4 - (r16 >> 2)) & 3);
;   const u16* xs = X + (long)(wu * XD * 16 + r16) * ldx + (chunk << 3);
;   const u16* ws = W + (long)(wu * 32 + r16) * ldw + (chunk << 3);
;   const long ldx16 = 16 * ldx, ldw16 = 16 * ldw;
;   const unsigned xdst = sbase + wu * XD * 1024, wdst = sbase + BM * 64 + wu * 2048;
;     ...
;   const int nk = K >> 5;
;   __syncthreads();
; #pragma unroll
;   for (int s = 0; s < D - 1; ++s) GD_ISSUE(s)
;   int cur = 0, nxt = D - 1, kt = 0;
;   do {
;     if (kt + D - 2 < nk) wait_vm<PW * (D - 2)>(); else wait_vm<0>();
;     __syncthreads();
;     if (kt + D - 1 < nk) GD_ISSUE(nxt)
;     nxt = (nxt + 1 == D) ? 0 : nxt + 1;
;     const char* base = smem + cur * STG;
;     cur = (cur + 1 == D) ? 0 : cur + 1;
;     bf16x8 xf[MT];
; #pragma unroll
;     for (int i = 0; i < MT; ++i) xf[i] = *(const bf16x8*)(base + (xrow0 + i * 16) * 64 + rd);
; DI void knope_tile(const Params& p, int u, char* smem) {
;   const u16* W = (const u16*)(p.ws + OFF_W);
;   const u16* ckvb = (const u16*)(p.ws + OFF_CKVB);
;   EpiBF16 ek{(u16*)(p.ws + OFF_KN), 1024};
;   const int tm = u >> 3, tn = u & 7;
;   gemm_dma<256>(ckvb + (size_t)tm * 256 * 256, 256, W + WO_KV + (size_t)tn * 128 * 256, 256, 256, smem, tm * 256, tn * 128, ek);
.LBB0_99:
	s_cmpk_gt_i32 s5, 0x62f
	s_mov_b64 s[38:39], -1
	s_cbranch_scc0 .LBB0_101
	s_add_i32 s4, s5, 0xfffff9d0
	s_bfe_u32 s98, s4, 0x30003
	s_and_b32 s99, s4, 7
	s_lshl_b32 s99, s99, 3
	s_andn2_b32 s4, s4, 63
	s_or_b32 s4, s4, s99
	s_or_b32 s4, s4, s98
	s_lshr_b32 s6, s4, 3
	s_and_b32 s4, s4, 7
	s_lshl_b32 s7, s6, 17
	s_add_u32 s8, s0, s7
	s_addc_u32 s9, s1, 0
	s_lshl_b32 s7, s4, 16
	v_mov_b32_e32 v11, v185
	s_add_u32 s10, s87, s7
	s_addc_u32 s11, s90, 0
	v_readfirstlane_b32 s7, v11
	v_lshrrev_b32_e32 v6, 4, v11
	s_ashr_i32 s12, s7, 6
	v_bfe_u32 v8, v11, 2, 4
	v_sub_u32_e32 v6, 0, v6
	s_andn2_b32 s7, s7, 63
	v_lshrrev_b32_e32 v3, 2, v11
	v_xor_b32_e32 v9, v11, v6
	v_or_b32_e32 v6, s7, v8
	v_and_b32_e32 v90, 15, v11
	v_bfe_u32 v1, v11, 4, 2
	v_sub_u32_e32 v3, 0, v3
	v_ashrrev_i32_e32 v7, 31, v6
	v_lshlrev_b32_e32 v2, 6, v90
	v_bitop3_b32 v3, v1, v3, 3 bitop3:0x78
	v_lshlrev_b64 v[6:7], 9, v[6:7]
	v_lshlrev_b32_e32 v9, 4, v9
	v_lshl_or_b32 v8, s12, 5, v8
	v_lshl_or_b32 v10, v3, 4, v2
	v_mov_b32_e32 v2, v183
	v_lshl_add_u64 v[6:7], s[8:9], 0, v[6:7]
	v_and_b32_e32 v182, 48, v9
	v_ashrrev_i32_e32 v9, 31, v8
	v_lshl_add_u64 v[6:7], v[6:7], 0, v[182:183]
	v_lshlrev_b64 v[8:9], 9, v[8:9]
	s_lshl_b32 s14, s12, 12
	s_barrier
	s_mov_b32 s7, m0
	s_mov_b32 m0, s14
	s_nop 0
	global_load_lds_dwordx4 v[6:7], off
	s_mov_b32 m0, s7
	s_mov_b64 s[8:9], 0x2000
	v_lshl_add_u64 v[8:9], s[10:11], 0, v[8:9]
	v_lshl_add_u64 v[12:13], v[6:7], 0, s[8:9]
	s_or_b32 s15, s14, 0x400
	s_mov_b32 s7, m0
	s_mov_b32 m0, s15
	s_nop 0
	global_load_lds_dwordx4 v[12:13], off
	s_mov_b32 m0, s7
	s_mov_b64 s[10:11], 0x4000
	v_lshl_add_u64 v[12:13], v[6:7], 0, s[10:11]
	s_or_b32 s16, s14, 0x800
	s_mov_b32 s7, m0
	s_mov_b32 m0, s16
	s_nop 0
	global_load_lds_dwordx4 v[12:13], off
	s_mov_b32 m0, s7
	s_mov_b64 s[10:11], 0x6000
	s_lshl_b32 s42, s12, 11
	v_lshl_add_u64 v[12:13], v[6:7], 0, s[10:11]
	s_or_b32 s17, s14, 0xc00
	s_mov_b32 s7, m0
	s_mov_b32 m0, s17
	s_nop 0
	global_load_lds_dwordx4 v[12:13], off
	s_mov_b32 m0, s7
	v_lshl_add_u64 v[8:9], v[8:9], 0, v[182:183]
	s_add_i32 s13, s42, 0x4000
	s_mov_b32 s7, m0
	s_mov_b32 m0, s13
	s_nop 0
	global_load_lds_dwordx4 v[8:9], off
	s_mov_b32 m0, s7
	v_lshl_add_u64 v[12:13], v[8:9], 0, s[8:9]
	s_add_i32 s18, s42, 0x4400
	s_mov_b32 s7, m0
	s_mov_b32 m0, s18
	s_nop 0
	global_load_lds_dwordx4 v[12:13], off
	s_mov_b32 m0, s7
	v_lshl_add_u64 v[12:13], v[6:7], 0, 64
	s_add_i32 s7, s14, 0x6000
	s_mov_b32 s8, m0
	s_mov_b32 m0, s7
	s_nop 0
	global_load_lds_dwordx4 v[12:13], off
	s_mov_b32 m0, s8
	s_mov_b64 s[20:21], 0x2040
	v_lshl_add_u64 v[12:13], v[6:7], 0, s[20:21]
	s_add_i32 s8, s14, 0x6400
	s_mov_b32 s9, m0
	s_mov_b32 m0, s8
	s_nop 0
	global_load_lds_dwordx4 v[12:13], off
	s_mov_b32 m0, s9
	s_mov_b64 s[10:11], 0x4040
	v_lshl_add_u64 v[12:13], v[6:7], 0, s[10:11]
	s_add_i32 s9, s14, 0x6800
	s_mov_b32 s10, m0
	s_mov_b32 m0, s9
	s_nop 0
	global_load_lds_dwordx4 v[12:13], off
	s_mov_b32 m0, s10
	s_mov_b64 s[10:11], 0x6040
	v_lshl_add_u64 v[12:13], v[6:7], 0, s[10:11]
	s_add_i32 s10, s14, 0x6c00
	s_mov_b32 s11, m0
	s_mov_b32 m0, s10
	s_nop 0
	global_load_lds_dwordx4 v[12:13], off
	s_mov_b32 m0, s11
	v_lshl_add_u64 v[14:15], v[8:9], 0, 64
	s_add_i32 s11, s42, 0xa000
	s_mov_b32 s12, m0
	s_mov_b32 m0, s11
	s_nop 0
	global_load_lds_dwordx4 v[14:15], off
	s_mov_b32 m0, s12
	v_lshl_add_u64 v[12:13], v[8:9], 0, s[20:21]
	s_add_i32 s12, s42, 0xa400
	s_mov_b32 s19, m0
	s_mov_b32 m0, s12
	s_nop 0
	global_load_lds_dwordx4 v[12:13], off
	s_mov_b32 m0, s19
	s_waitcnt vmcnt(6)
	s_barrier
	v_lshl_add_u64 v[14:15], v[6:7], 0, s[28:29]
	s_add_i32 s19, s14, 0xc000
	s_mov_b32 s34, m0
	s_mov_b32 m0, s19
	s_nop 0
	global_load_lds_dwordx4 v[14:15], off
	s_mov_b32 m0, s34
	s_mov_b64 s[20:21], 0x2080
	v_lshl_add_u64 v[14:15], v[6:7], 0, s[20:21]
	s_add_i32 s34, s14, 0xc400
	s_mov_b32 s38, m0
	s_mov_b32 m0, s34
	s_nop 0
	global_load_lds_dwordx4 v[14:15], off
	s_mov_b32 m0, s38
	v_lshl_add_u64 v[14:15], v[6:7], 0, s[94:95]
	s_add_i32 s38, s14, 0xc800
	s_mov_b32 s39, m0
	s_mov_b32 m0, s38
	s_nop 0
	global_load_lds_dwordx4 v[14:15], off
	s_mov_b32 m0, s39
	s_mov_b64 s[22:23], 0x6080
	v_lshl_add_u64 v[14:15], v[6:7], 0, s[22:23]
	s_add_i32 s43, s14, 0xcc00
	s_mov_b32 s39, m0
	s_mov_b32 m0, s43
	s_nop 0
	global_load_lds_dwordx4 v[14:15], off
	s_mov_b32 m0, s39
	v_and_b32_e32 v91, 0xffffffc0, v11
	v_lshl_add_u64 v[12:13], v[8:9], 0, s[28:29]
	s_add_i32 s39, s42, 0x10000
	s_mov_b32 s44, m0
	s_mov_b32 m0, s39
	s_nop 0
	global_load_lds_dwordx4 v[12:13], off
	s_mov_b32 m0, s44
	v_lshl_add_u64 v[12:13], v[8:9], 0, s[20:21]
	s_add_i32 s42, s42, 0x10400
	s_mov_b32 s44, m0
	s_mov_b32 m0, s42
	s_nop 0
	global_load_lds_dwordx4 v[12:13], off
	s_mov_b32 m0, s44
	v_lshl_or_b32 v11, v91, 6, v10
	ds_read_b128 v[12:15], v11
	s_waitcnt vmcnt(7)
	ds_read_b128 v[16:19], v11 offset:1024
	s_waitcnt vmcnt(5)
	ds_read_b128 v[20:23], v11 offset:2048
	ds_read_b128 v[24:27], v11 offset:3072
	s_waitcnt vmcnt(4)
	ds_read_b128 v[28:31], v10 offset:16384
	ds_read_b128 v[32:35], v10 offset:17408
	ds_read_b128 v[36:39], v10 offset:18432
	ds_read_b128 v[40:43], v10 offset:19456
	s_waitcnt vmcnt(0)
	ds_read_b128 v[96:99], v10 offset:20480
	ds_read_b128 v[100:103], v10 offset:21504
	ds_read_b128 v[104:107], v10 offset:22528
	ds_read_b128 v[108:111], v10 offset:23552
	s_mov_b64 s[20:21], 0xc0
	v_mov_b32_e32 v3, v2
	v_mov_b32_e32 v4, v2
	v_mov_b32_e32 v5, v2
	v_lshl_add_u64 v[88:89], v[6:7], 0, s[20:21]
	v_lshl_add_u64 v[148:149], v[8:9], 0, s[20:21]
	s_waitcnt vmcnt(6)
	s_waitcnt lgkmcnt(0)
	s_barrier
; template <int N> DI void wait_vm() { asm volatile("s_waitcnt vmcnt(%0)" ::"n"(N) : "memory"); }
; template <int BM, class Epi>
; DI void gemm_dma(const u16* __restrict__ X, long ldx, const u16* __restrict__ W, long ldw, int K, char* smem,
;                  int m0, int n0, const Epi& epi) {
;     ...
;   do {
;     if (kt + D - 2 < nk) wait_vm<PW * (D - 2)>(); else wait_vm<0>();
;     __syncthreads();
;     if (kt + D - 1 < nk) GD_ISSUE(nxt)
;     nxt = (nxt + 1 == D) ? 0 : nxt + 1;
;     const char* base = smem + cur * STG;
;     cur = (cur + 1 == D) ? 0 : cur + 1;
;     bf16x8 xf[MT];
; #pragma unroll
;     for (int i = 0; i < MT; ++i) xf[i] = *(const bf16x8*)(base + (xrow0 + i * 16) * 64 + rd);
; #pragma unroll
;     for (int nh = 0; nh < NT / 4; ++nh) {
;       bf16x8 wf[4];
; #pragma unroll
;       for (int i = 0; i < 4; ++i) wf[i] = *(const bf16x8*)(base + BM * 64 + (wrow0 + (nh * 4 + i) * 16) * 64 + rd);
; #pragma unroll
;       for (int i = 0; i < 4; ++i)
; #pragma unroll
;         for (int mt = 0; mt < MT; ++mt)
;           acc[nh * 4 + i][mt] = __builtin_amdgcn_mfma_f32_16x16x32_bf16(wf[i], xf[mt], acc[nh * 4 + i][mt], 0, 0, 0);
;     }
;   } while (++kt < nk);
	s_mov_b32 s44, m0
	s_mov_b32 m0, s14
	s_nop 0
	global_load_lds_dwordx4 v[88:89], off
	s_mov_b32 m0, s44
	s_mov_b64 s[20:21], 0x20c0
	v_mfma_f32_16x16x32_bf16 v[44:47], v[28:31], v[12:15], v[2:5]
	s_mov_b64 s[22:23], 0x40c0
	v_or_b32_e32 v174, 0x10000, v10
	v_or_b32_e32 v175, 0x10400, v10
	v_mfma_f32_16x16x32_bf16 v[48:51], v[28:31], v[16:19], v[2:5]
	v_or_b32_e32 v176, 0x10800, v10
	v_or_b32_e32 v177, 0x10c00, v10
	v_or_b32_e32 v178, 0x11000, v10
	v_mfma_f32_16x16x32_bf16 v[52:55], v[28:31], v[20:23], v[2:5]
	v_or_b32_e32 v179, 0x11400, v10
	v_or_b32_e32 v180, 0x11800, v10
	v_or_b32_e32 v181, 0x11c00, v10
	v_mfma_f32_16x16x32_bf16 v[28:31], v[28:31], v[24:27], v[2:5]
	v_lshl_add_u32 v91, s6, 8, v91
	s_lshl_b32 s4, s4, 8
	v_lshl_or_b32 v182, v1, 3, s4
	v_mfma_f32_16x16x32_bf16 v[56:59], v[32:35], v[12:15], v[2:5]
	v_mfma_f32_16x16x32_bf16 v[60:63], v[32:35], v[16:19], v[2:5]
	v_mfma_f32_16x16x32_bf16 v[64:67], v[32:35], v[20:23], v[2:5]
	v_mfma_f32_16x16x32_bf16 v[32:35], v[32:35], v[24:27], v[2:5]
	v_mfma_f32_16x16x32_bf16 v[68:71], v[36:39], v[12:15], v[2:5]
	v_mfma_f32_16x16x32_bf16 v[72:75], v[36:39], v[16:19], v[2:5]
	v_mfma_f32_16x16x32_bf16 v[76:79], v[36:39], v[20:23], v[2:5]
	v_mfma_f32_16x16x32_bf16 v[36:39], v[36:39], v[24:27], v[2:5]
	v_mfma_f32_16x16x32_bf16 v[80:83], v[40:43], v[12:15], v[2:5]
	v_mfma_f32_16x16x32_bf16 v[84:87], v[40:43], v[16:19], v[2:5]
	v_mfma_f32_16x16x32_bf16 v[92:95], v[40:43], v[20:23], v[2:5]
	v_mfma_f32_16x16x32_bf16 v[40:43], v[40:43], v[24:27], v[2:5]
	v_mfma_f32_16x16x32_bf16 v[112:115], v[96:99], v[12:15], v[2:5]
	v_mfma_f32_16x16x32_bf16 v[116:119], v[96:99], v[16:19], v[2:5]
	v_mfma_f32_16x16x32_bf16 v[120:123], v[96:99], v[20:23], v[2:5]
	v_mfma_f32_16x16x32_bf16 v[96:99], v[96:99], v[24:27], v[2:5]
	v_mfma_f32_16x16x32_bf16 v[124:127], v[100:103], v[12:15], v[2:5]
	v_mfma_f32_16x16x32_bf16 v[128:131], v[100:103], v[16:19], v[2:5]
	v_mfma_f32_16x16x32_bf16 v[132:135], v[100:103], v[20:23], v[2:5]
	v_mfma_f32_16x16x32_bf16 v[100:103], v[100:103], v[24:27], v[2:5]
	v_mfma_f32_16x16x32_bf16 v[136:139], v[104:107], v[12:15], v[2:5]
	v_mfma_f32_16x16x32_bf16 v[140:143], v[104:107], v[16:19], v[2:5]
	v_mfma_f32_16x16x32_bf16 v[144:147], v[104:107], v[20:23], v[2:5]
	v_mfma_f32_16x16x32_bf16 v[104:107], v[104:107], v[24:27], v[2:5]
	v_mfma_f32_16x16x32_bf16 v[12:15], v[108:111], v[12:15], v[2:5]
	v_mfma_f32_16x16x32_bf16 v[16:19], v[108:111], v[16:19], v[2:5]
	v_mfma_f32_16x16x32_bf16 v[20:23], v[108:111], v[20:23], v[2:5]
	v_mfma_f32_16x16x32_bf16 v[2:5], v[108:111], v[24:27], v[2:5]
	v_lshl_add_u64 v[24:25], v[6:7], 0, s[20:21]
	s_mov_b32 s44, m0
	s_mov_b32 m0, s15
	s_nop 0
	global_load_lds_dwordx4 v[24:25], off
	s_mov_b32 m0, s44
	v_lshl_add_u64 v[24:25], v[6:7], 0, s[22:23]
	s_mov_b32 s44, m0
	s_mov_b32 m0, s16
	s_nop 0
	global_load_lds_dwordx4 v[24:25], off
	s_mov_b32 m0, s44
	s_mov_b64 s[22:23], 0x60c0
	v_lshl_add_u64 v[24:25], v[6:7], 0, s[22:23]
	s_mov_b32 s44, m0
	s_mov_b32 m0, s17
	s_nop 0
	global_load_lds_dwordx4 v[24:25], off
	s_mov_b32 m0, s44
	v_lshl_add_u64 v[24:25], v[8:9], 0, s[20:21]
	s_mov_b32 s44, m0
	s_mov_b32 m0, s13
	s_nop 0
	global_load_lds_dwordx4 v[148:149], off
	s_mov_b32 m0, s44
	s_mov_b64 s[20:21], 0x100
	s_mov_b32 s44, m0
	s_mov_b32 m0, s18
	s_nop 0
	global_load_lds_dwordx4 v[24:25], off
	s_mov_b32 m0, s44
	ds_read_b128 v[24:27], v11 offset:24576
	ds_read_b128 v[108:111], v11 offset:25600
	ds_read_b128 v[148:151], v11 offset:26624
	ds_read_b128 v[152:155], v11 offset:27648
	ds_read_b128 v[156:159], v10 offset:40960
	ds_read_b128 v[160:163], v10 offset:41984
	ds_read_b128 v[164:167], v10 offset:43008
	ds_read_b128 v[168:171], v10 offset:44032
	s_waitcnt lgkmcnt(3)
	v_mfma_f32_16x16x32_bf16 v[44:47], v[156:159], v[24:27], v[44:47]
	v_lshl_add_u64 v[88:89], v[6:7], 0, s[20:21]
	v_lshl_add_u64 v[172:173], v[8:9], 0, s[20:21]
	s_mov_b64 s[20:21], 0x2100
	v_mfma_f32_16x16x32_bf16 v[48:51], v[156:159], v[108:111], v[48:51]
	s_mov_b64 s[22:23], 0x4100
	v_mfma_f32_16x16x32_bf16 v[52:55], v[156:159], v[148:151], v[52:55]
	v_mfma_f32_16x16x32_bf16 v[28:31], v[156:159], v[152:155], v[28:31]
	s_waitcnt lgkmcnt(2)
	v_mfma_f32_16x16x32_bf16 v[56:59], v[160:163], v[24:27], v[56:59]
	v_mfma_f32_16x16x32_bf16 v[60:63], v[160:163], v[108:111], v[60:63]
	v_mfma_f32_16x16x32_bf16 v[64:67], v[160:163], v[148:151], v[64:67]
	v_mfma_f32_16x16x32_bf16 v[32:35], v[160:163], v[152:155], v[32:35]
	s_waitcnt lgkmcnt(1)
	v_mfma_f32_16x16x32_bf16 v[68:71], v[164:167], v[24:27], v[68:71]
	v_mfma_f32_16x16x32_bf16 v[72:75], v[164:167], v[108:111], v[72:75]
	v_mfma_f32_16x16x32_bf16 v[76:79], v[164:167], v[148:151], v[76:79]
	v_mfma_f32_16x16x32_bf16 v[36:39], v[164:167], v[152:155], v[36:39]
	s_waitcnt lgkmcnt(0)
	v_mfma_f32_16x16x32_bf16 v[80:83], v[168:171], v[24:27], v[80:83]
	v_mfma_f32_16x16x32_bf16 v[84:87], v[168:171], v[108:111], v[84:87]
	v_mfma_f32_16x16x32_bf16 v[92:95], v[168:171], v[148:151], v[92:95]
	v_mfma_f32_16x16x32_bf16 v[40:43], v[168:171], v[152:155], v[40:43]
	ds_read_b128 v[156:159], v10 offset:45056
	ds_read_b128 v[160:163], v10 offset:46080
	ds_read_b128 v[164:167], v10 offset:47104
	ds_read_b128 v[168:171], v10 offset:48128
	s_waitcnt vmcnt(6)
	s_waitcnt lgkmcnt(0)
	s_barrier
; template <int N> DI void wait_vm() { asm volatile("s_waitcnt vmcnt(%0)" ::"n"(N) : "memory"); }
; template <int BM, class Epi>
; DI void gemm_dma(const u16* __restrict__ X, long ldx, const u16* __restrict__ W, long ldw, int K, char* smem,
;                  int m0, int n0, const Epi& epi) {
;     ...
;   do {
;     if (kt + D - 2 < nk) wait_vm<PW * (D - 2)>(); else wait_vm<0>();
;     __syncthreads();
;     if (kt + D - 1 < nk) GD_ISSUE(nxt)
;     nxt = (nxt + 1 == D) ? 0 : nxt + 1;
;     const char* base = smem + cur * STG;
;     cur = (cur + 1 == D) ? 0 : cur + 1;
;     bf16x8 xf[MT];
; #pragma unroll
;     for (int i = 0; i < MT; ++i) xf[i] = *(const bf16x8*)(base + (xrow0 + i * 16) * 64 + rd);
; #pragma unroll
;     for (int nh = 0; nh < NT / 4; ++nh) {
;       bf16x8 wf[4];
; #pragma unroll
;       for (int i = 0; i < 4; ++i) wf[i] = *(const bf16x8*)(base + BM * 64 + (wrow0 + (nh * 4 + i) * 16) * 64 + rd);
; #pragma unroll
;       for (int i = 0; i < 4; ++i)
; #pragma unroll
;         for (int mt = 0; mt < MT; ++mt)
;           acc[nh * 4 + i][mt] = __builtin_amdgcn_mfma_f32_16x16x32_bf16(wf[i], xf[mt], acc[nh * 4 + i][mt], 0, 0, 0);
;     }
;   } while (++kt < nk);
	s_mov_b32 s44, m0
	s_mov_b32 m0, s7
	s_nop 0
	global_load_lds_dwordx4 v[88:89], off
	s_mov_b32 m0, s44
	v_mfma_f32_16x16x32_bf16 v[112:115], v[156:159], v[24:27], v[112:115]
	v_mfma_f32_16x16x32_bf16 v[124:127], v[160:163], v[24:27], v[124:127]
	v_mfma_f32_16x16x32_bf16 v[136:139], v[164:167], v[24:27], v[136:139]
	v_mfma_f32_16x16x32_bf16 v[12:15], v[168:171], v[24:27], v[12:15]
	v_lshl_add_u64 v[24:25], v[6:7], 0, s[20:21]
	s_mov_b32 s44, m0
	s_mov_b32 m0, s8
	s_nop 0
	global_load_lds_dwordx4 v[24:25], off
	s_mov_b32 m0, s44
	v_lshl_add_u64 v[24:25], v[6:7], 0, s[22:23]
	s_mov_b32 s44, m0
	s_mov_b32 m0, s9
	s_nop 0
	global_load_lds_dwordx4 v[24:25], off
	s_mov_b32 m0, s44
	s_mov_b64 s[22:23], 0x6100
	v_lshl_add_u64 v[24:25], v[6:7], 0, s[22:23]
	s_mov_b32 s44, m0
	s_mov_b32 m0, s10
	s_nop 0
	global_load_lds_dwordx4 v[24:25], off
	s_mov_b32 m0, s44
	v_lshl_add_u64 v[24:25], v[8:9], 0, s[20:21]
	s_mov_b32 s44, m0
	s_mov_b32 m0, s11
	s_nop 0
	global_load_lds_dwordx4 v[172:173], off
	s_mov_b32 m0, s44
	v_mfma_f32_16x16x32_bf16 v[116:119], v[156:159], v[108:111], v[116:119]
	s_mov_b32 s44, m0
	s_mov_b32 m0, s12
	s_nop 0
	global_load_lds_dwordx4 v[24:25], off
	s_mov_b32 m0, s44
	s_mov_b64 s[20:21], 0x140
	v_lshl_add_u64 v[88:89], v[6:7], 0, s[20:21]
	v_mfma_f32_16x16x32_bf16 v[120:123], v[156:159], v[148:151], v[120:123]
	v_lshl_add_u64 v[172:173], v[8:9], 0, s[20:21]
	s_mov_b64 s[20:21], 0x2140
	s_mov_b64 s[22:23], 0x4140
	v_mfma_f32_16x16x32_bf16 v[96:99], v[156:159], v[152:155], v[96:99]
	v_mfma_f32_16x16x32_bf16 v[128:131], v[160:163], v[108:111], v[128:131]
	v_mfma_f32_16x16x32_bf16 v[132:135], v[160:163], v[148:151], v[132:135]
	v_mfma_f32_16x16x32_bf16 v[100:103], v[160:163], v[152:155], v[100:103]
	v_mfma_f32_16x16x32_bf16 v[140:143], v[164:167], v[108:111], v[140:143]
	v_mfma_f32_16x16x32_bf16 v[144:147], v[164:167], v[148:151], v[144:147]
	v_mfma_f32_16x16x32_bf16 v[104:107], v[164:167], v[152:155], v[104:107]
	v_mfma_f32_16x16x32_bf16 v[16:19], v[168:171], v[108:111], v[16:19]
	v_mfma_f32_16x16x32_bf16 v[20:23], v[168:171], v[148:151], v[20:23]
	v_mfma_f32_16x16x32_bf16 v[2:5], v[168:171], v[152:155], v[2:5]
	ds_read_b128 v[24:27], v11 offset:49152
	ds_read_b128 v[108:111], v11 offset:50176
	ds_read_b128 v[148:151], v11 offset:51200
	ds_read_b128 v[152:155], v11 offset:52224
	ds_read_b128 v[156:159], v174
	ds_read_b128 v[160:163], v175
	ds_read_b128 v[164:167], v176
	ds_read_b128 v[168:171], v177
	s_waitcnt lgkmcnt(3)
	v_mfma_f32_16x16x32_bf16 v[44:47], v[156:159], v[24:27], v[44:47]
	v_mfma_f32_16x16x32_bf16 v[48:51], v[156:159], v[108:111], v[48:51]
	v_mfma_f32_16x16x32_bf16 v[52:55], v[156:159], v[148:151], v[52:55]
	v_mfma_f32_16x16x32_bf16 v[28:31], v[156:159], v[152:155], v[28:31]
	ds_read_b128 v[156:159], v178
	s_waitcnt lgkmcnt(3)
	v_mfma_f32_16x16x32_bf16 v[56:59], v[160:163], v[24:27], v[56:59]
	v_mfma_f32_16x16x32_bf16 v[60:63], v[160:163], v[108:111], v[60:63]
	v_mfma_f32_16x16x32_bf16 v[64:67], v[160:163], v[148:151], v[64:67]
	v_mfma_f32_16x16x32_bf16 v[32:35], v[160:163], v[152:155], v[32:35]
	ds_read_b128 v[160:163], v179
	s_waitcnt lgkmcnt(3)
	v_mfma_f32_16x16x32_bf16 v[68:71], v[164:167], v[24:27], v[68:71]
	v_mfma_f32_16x16x32_bf16 v[72:75], v[164:167], v[108:111], v[72:75]
	v_mfma_f32_16x16x32_bf16 v[76:79], v[164:167], v[148:151], v[76:79]
	v_mfma_f32_16x16x32_bf16 v[36:39], v[164:167], v[152:155], v[36:39]
	ds_read_b128 v[164:167], v180
	s_waitcnt lgkmcnt(3)
	v_mfma_f32_16x16x32_bf16 v[80:83], v[168:171], v[24:27], v[80:83]
	v_mfma_f32_16x16x32_bf16 v[84:87], v[168:171], v[108:111], v[84:87]
	v_mfma_f32_16x16x32_bf16 v[92:95], v[168:171], v[148:151], v[92:95]
	v_mfma_f32_16x16x32_bf16 v[40:43], v[168:171], v[152:155], v[40:43]
	ds_read_b128 v[168:171], v181
	s_waitcnt vmcnt(6)
	s_waitcnt lgkmcnt(0)
	s_barrier
	s_mov_b32 s44, m0
	s_mov_b32 m0, s19
	s_nop 0
	global_load_lds_dwordx4 v[88:89], off
	s_mov_b32 m0, s44
	v_mfma_f32_16x16x32_bf16 v[112:115], v[156:159], v[24:27], v[112:115]
	v_mfma_f32_16x16x32_bf16 v[124:127], v[160:163], v[24:27], v[124:127]
	v_mfma_f32_16x16x32_bf16 v[136:139], v[164:167], v[24:27], v[136:139]
	v_mfma_f32_16x16x32_bf16 v[12:15], v[168:171], v[24:27], v[12:15]
	v_lshl_add_u64 v[24:25], v[6:7], 0, s[20:21]
	s_mov_b32 s19, m0
	s_mov_b32 m0, s34
	s_nop 0
	global_load_lds_dwordx4 v[24:25], off
	s_mov_b32 m0, s19
	v_lshl_add_u64 v[24:25], v[6:7], 0, s[22:23]
	s_mov_b32 s19, m0
	s_mov_b32 m0, s38
	s_nop 0
	global_load_lds_dwordx4 v[24:25], off
	s_mov_b32 m0, s19
	s_mov_b64 s[22:23], 0x6140
	v_lshl_add_u64 v[24:25], v[6:7], 0, s[22:23]
	s_mov_b32 s19, m0
	s_mov_b32 m0, s43
	s_nop 0
	global_load_lds_dwordx4 v[24:25], off
	s_mov_b32 m0, s19
	v_lshl_add_u64 v[24:25], v[8:9], 0, s[20:21]
	s_mov_b32 s19, m0
	s_mov_b32 m0, s39
	s_nop 0
	global_load_lds_dwordx4 v[172:173], off
	s_mov_b32 m0, s19
	v_mfma_f32_16x16x32_bf16 v[116:119], v[156:159], v[108:111], v[116:119]
	s_mov_b32 s19, m0
	s_mov_b32 m0, s42
	s_nop 0
	global_load_lds_dwordx4 v[24:25], off
	s_mov_b32 m0, s19
	s_mov_b64 s[20:21], 0x180
	v_lshl_add_u64 v[88:89], v[6:7], 0, s[20:21]
	v_mfma_f32_16x16x32_bf16 v[120:123], v[156:159], v[148:151], v[120:123]
	v_lshl_add_u64 v[172:173], v[8:9], 0, s[20:21]
	s_mov_b64 s[20:21], 0x2180
	s_mov_b64 s[38:39], 0
	v_mfma_f32_16x16x32_bf16 v[96:99], v[156:159], v[152:155], v[96:99]
	v_mfma_f32_16x16x32_bf16 v[128:131], v[160:163], v[108:111], v[128:131]
	v_mfma_f32_16x16x32_bf16 v[132:135], v[160:163], v[148:151], v[132:135]
	v_mfma_f32_16x16x32_bf16 v[100:103], v[160:163], v[152:155], v[100:103]
	v_mfma_f32_16x16x32_bf16 v[140:143], v[164:167], v[108:111], v[140:143]
	v_mfma_f32_16x16x32_bf16 v[144:147], v[164:167], v[148:151], v[144:147]
	v_mfma_f32_16x16x32_bf16 v[104:107], v[164:167], v[152:155], v[104:107]
	v_mfma_f32_16x16x32_bf16 v[16:19], v[168:171], v[108:111], v[16:19]
	v_mfma_f32_16x16x32_bf16 v[20:23], v[168:171], v[148:151], v[20:23]
	v_mfma_f32_16x16x32_bf16 v[2:5], v[168:171], v[152:155], v[2:5]
	ds_read_b128 v[24:27], v11
	ds_read_b128 v[108:111], v11 offset:1024
	ds_read_b128 v[148:151], v11 offset:2048
	ds_read_b128 v[152:155], v11 offset:3072
	ds_read_b128 v[156:159], v10 offset:16384
	ds_read_b128 v[160:163], v10 offset:17408
	ds_read_b128 v[164:167], v10 offset:18432
	ds_read_b128 v[168:171], v10 offset:19456
	s_waitcnt lgkmcnt(3)
; template <int N> DI void wait_vm() { asm volatile("s_waitcnt vmcnt(%0)" ::"n"(N) : "memory"); }
; template <int BM, class Epi>
; DI void gemm_dma(const u16* __restrict__ X, long ldx, const u16* __restrict__ W, long ldw, int K, char* smem,
;                  int m0, int n0, const Epi& epi) {
;     ...
;   do {
;     if (kt + D - 2 < nk) wait_vm<PW * (D - 2)>(); else wait_vm<0>();
;     __syncthreads();
;     if (kt + D - 1 < nk) GD_ISSUE(nxt)
;     nxt = (nxt + 1 == D) ? 0 : nxt + 1;
;     const char* base = smem + cur * STG;
;     cur = (cur + 1 == D) ? 0 : cur + 1;
;     bf16x8 xf[MT];
; #pragma unroll
;     for (int i = 0; i < MT; ++i) xf[i] = *(const bf16x8*)(base + (xrow0 + i * 16) * 64 + rd);
; #pragma unroll
;     for (int nh = 0; nh < NT / 4; ++nh) {
;       bf16x8 wf[4];
; #pragma unroll
;       for (int i = 0; i < 4; ++i) wf[i] = *(const bf16x8*)(base + BM * 64 + (wrow0 + (nh * 4 + i) * 16) * 64 + rd);
; #pragma unroll
;       for (int i = 0; i < 4; ++i)
; #pragma unroll
;         for (int mt = 0; mt < MT; ++mt)
;           acc[nh * 4 + i][mt] = __builtin_amdgcn_mfma_f32_16x16x32_bf16(wf[i], xf[mt], acc[nh * 4 + i][mt], 0, 0, 0);
;     }
;   } while (++kt < nk);
	v_mfma_f32_16x16x32_bf16 v[44:47], v[156:159], v[24:27], v[44:47]
	v_mfma_f32_16x16x32_bf16 v[48:51], v[156:159], v[108:111], v[48:51]
	v_mfma_f32_16x16x32_bf16 v[52:55], v[156:159], v[148:151], v[52:55]
	v_mfma_f32_16x16x32_bf16 v[28:31], v[156:159], v[152:155], v[28:31]
	s_waitcnt lgkmcnt(2)
	v_mfma_f32_16x16x32_bf16 v[56:59], v[160:163], v[24:27], v[56:59]
	v_mfma_f32_16x16x32_bf16 v[60:63], v[160:163], v[108:111], v[60:63]
	v_mfma_f32_16x16x32_bf16 v[64:67], v[160:163], v[148:151], v[64:67]
	v_mfma_f32_16x16x32_bf16 v[32:35], v[160:163], v[152:155], v[32:35]
	s_waitcnt lgkmcnt(1)
	v_mfma_f32_16x16x32_bf16 v[68:71], v[164:167], v[24:27], v[68:71]
	v_mfma_f32_16x16x32_bf16 v[72:75], v[164:167], v[108:111], v[72:75]
	v_mfma_f32_16x16x32_bf16 v[76:79], v[164:167], v[148:151], v[76:79]
	v_mfma_f32_16x16x32_bf16 v[36:39], v[164:167], v[152:155], v[36:39]
	s_waitcnt lgkmcnt(0)
	v_mfma_f32_16x16x32_bf16 v[80:83], v[168:171], v[24:27], v[80:83]
	v_mfma_f32_16x16x32_bf16 v[84:87], v[168:171], v[108:111], v[84:87]
	v_mfma_f32_16x16x32_bf16 v[92:95], v[168:171], v[148:151], v[92:95]
	v_mfma_f32_16x16x32_bf16 v[40:43], v[168:171], v[152:155], v[40:43]
	ds_read_b128 v[156:159], v10 offset:20480
	ds_read_b128 v[160:163], v10 offset:21504
	ds_read_b128 v[164:167], v10 offset:22528
	ds_read_b128 v[168:171], v10 offset:23552
	s_waitcnt vmcnt(6)
	s_waitcnt lgkmcnt(0)
	s_barrier
	s_mov_b32 s19, m0
	s_mov_b32 m0, s14
	s_nop 0
	global_load_lds_dwordx4 v[88:89], off
	s_mov_b32 m0, s19
	v_mfma_f32_16x16x32_bf16 v[112:115], v[156:159], v[24:27], v[112:115]
	v_mfma_f32_16x16x32_bf16 v[124:127], v[160:163], v[24:27], v[124:127]
	v_mfma_f32_16x16x32_bf16 v[136:139], v[164:167], v[24:27], v[136:139]
	v_mfma_f32_16x16x32_bf16 v[12:15], v[168:171], v[24:27], v[12:15]
	v_lshl_add_u64 v[24:25], v[6:7], 0, s[20:21]
	s_mov_b32 s14, m0
	s_mov_b32 m0, s15
	s_nop 0
	global_load_lds_dwordx4 v[24:25], off
	s_mov_b32 m0, s14
	s_mov_b64 s[14:15], 0x4180
	v_lshl_add_u64 v[24:25], v[6:7], 0, s[14:15]
	s_mov_b32 s14, m0
	s_mov_b32 m0, s16
	s_nop 0
	global_load_lds_dwordx4 v[24:25], off
	s_mov_b32 m0, s14
	s_mov_b64 s[14:15], 0x6180
	v_lshl_add_u64 v[24:25], v[6:7], 0, s[14:15]
	s_mov_b32 s14, m0
	s_mov_b32 m0, s17
	s_nop 0
	global_load_lds_dwordx4 v[24:25], off
	s_mov_b32 m0, s14
	v_lshl_add_u64 v[24:25], v[8:9], 0, s[20:21]
	s_mov_b32 s14, m0
	s_mov_b32 m0, s13
	s_nop 0
	global_load_lds_dwordx4 v[172:173], off
	s_mov_b32 m0, s14
	s_mov_b32 s13, m0
	s_mov_b32 m0, s18
	s_nop 0
	global_load_lds_dwordx4 v[24:25], off
	s_mov_b32 m0, s13
	v_mfma_f32_16x16x32_bf16 v[116:119], v[156:159], v[108:111], v[116:119]
	s_mov_b64 s[14:15], 0x1c0
	v_lshl_add_u64 v[88:89], v[6:7], 0, s[14:15]
	v_lshl_add_u64 v[172:173], v[8:9], 0, s[14:15]
	v_mfma_f32_16x16x32_bf16 v[120:123], v[156:159], v[148:151], v[120:123]
	s_mov_b64 s[14:15], 0x21c0
	s_mov_b64 s[16:17], 0x41c0
	v_mfma_f32_16x16x32_bf16 v[96:99], v[156:159], v[152:155], v[96:99]
	v_mfma_f32_16x16x32_bf16 v[128:131], v[160:163], v[108:111], v[128:131]
	v_mfma_f32_16x16x32_bf16 v[132:135], v[160:163], v[148:151], v[132:135]
	v_mfma_f32_16x16x32_bf16 v[100:103], v[160:163], v[152:155], v[100:103]
	v_mfma_f32_16x16x32_bf16 v[140:143], v[164:167], v[108:111], v[140:143]
	v_mfma_f32_16x16x32_bf16 v[144:147], v[164:167], v[148:151], v[144:147]
	v_mfma_f32_16x16x32_bf16 v[104:107], v[164:167], v[152:155], v[104:107]
	v_mfma_f32_16x16x32_bf16 v[16:19], v[168:171], v[108:111], v[16:19]
	v_mfma_f32_16x16x32_bf16 v[20:23], v[168:171], v[148:151], v[20:23]
	v_mfma_f32_16x16x32_bf16 v[2:5], v[168:171], v[152:155], v[2:5]
	ds_read_b128 v[24:27], v11 offset:24576
	ds_read_b128 v[108:111], v11 offset:25600
	ds_read_b128 v[148:151], v11 offset:26624
	ds_read_b128 v[152:155], v11 offset:27648
	ds_read_b128 v[156:159], v10 offset:40960
	ds_read_b128 v[160:163], v10 offset:41984
	ds_read_b128 v[164:167], v10 offset:43008
	ds_read_b128 v[168:171], v10 offset:44032
	s_waitcnt lgkmcnt(3)
	v_mfma_f32_16x16x32_bf16 v[44:47], v[156:159], v[24:27], v[44:47]
	v_mfma_f32_16x16x32_bf16 v[48:51], v[156:159], v[108:111], v[48:51]
	v_mfma_f32_16x16x32_bf16 v[52:55], v[156:159], v[148:151], v[52:55]
	v_mfma_f32_16x16x32_bf16 v[28:31], v[156:159], v[152:155], v[28:31]
	s_waitcnt lgkmcnt(2)
	v_mfma_f32_16x16x32_bf16 v[56:59], v[160:163], v[24:27], v[56:59]
	v_mfma_f32_16x16x32_bf16 v[60:63], v[160:163], v[108:111], v[60:63]
	v_mfma_f32_16x16x32_bf16 v[64:67], v[160:163], v[148:151], v[64:67]
	v_mfma_f32_16x16x32_bf16 v[32:35], v[160:163], v[152:155], v[32:35]
	s_waitcnt lgkmcnt(1)
	v_mfma_f32_16x16x32_bf16 v[68:71], v[164:167], v[24:27], v[68:71]
	v_mfma_f32_16x16x32_bf16 v[72:75], v[164:167], v[108:111], v[72:75]
	v_mfma_f32_16x16x32_bf16 v[76:79], v[164:167], v[148:151], v[76:79]
	v_mfma_f32_16x16x32_bf16 v[36:39], v[164:167], v[152:155], v[36:39]
	s_waitcnt lgkmcnt(0)
	v_mfma_f32_16x16x32_bf16 v[80:83], v[168:171], v[24:27], v[80:83]
	v_mfma_f32_16x16x32_bf16 v[84:87], v[168:171], v[108:111], v[84:87]
	v_mfma_f32_16x16x32_bf16 v[92:95], v[168:171], v[148:151], v[92:95]
	v_mfma_f32_16x16x32_bf16 v[40:43], v[168:171], v[152:155], v[40:43]
	ds_read_b128 v[156:159], v10 offset:45056
	ds_read_b128 v[160:163], v10 offset:46080
	ds_read_b128 v[164:167], v10 offset:47104
	ds_read_b128 v[168:171], v10 offset:48128
	s_waitcnt vmcnt(6)
	s_waitcnt lgkmcnt(0)
	s_barrier
; template <int N> DI void wait_vm() { asm volatile("s_waitcnt vmcnt(%0)" ::"n"(N) : "memory"); }
; template <int BM, class Epi>
; DI void gemm_dma(const u16* __restrict__ X, long ldx, const u16* __restrict__ W, long ldw, int K, char* smem,
;                  int m0, int n0, const Epi& epi) {
;     ...
;   do {
;     if (kt + D - 2 < nk) wait_vm<PW * (D - 2)>(); else wait_vm<0>();
;     __syncthreads();
;     if (kt + D - 1 < nk) GD_ISSUE(nxt)
;     nxt = (nxt + 1 == D) ? 0 : nxt + 1;
;     const char* base = smem + cur * STG;
;     cur = (cur + 1 == D) ? 0 : cur + 1;
;     bf16x8 xf[MT];
; #pragma unroll
;     for (int i = 0; i < MT; ++i) xf[i] = *(const bf16x8*)(base + (xrow0 + i * 16) * 64 + rd);
; #pragma unroll
;     for (int nh = 0; nh < NT / 4; ++nh) {
;       bf16x8 wf[4];
; #pragma unroll
;       for (int i = 0; i < 4; ++i) wf[i] = *(const bf16x8*)(base + BM * 64 + (wrow0 + (nh * 4 + i) * 16) * 64 + rd);
; #pragma unroll
;       for (int i = 0; i < 4; ++i)
; #pragma unroll
;         for (int mt = 0; mt < MT; ++mt)
;           acc[nh * 4 + i][mt] = __builtin_amdgcn_mfma_f32_16x16x32_bf16(wf[i], xf[mt], acc[nh * 4 + i][mt], 0, 0, 0);
;     }
;   } while (++kt < nk);
	s_mov_b32 s13, m0
	s_mov_b32 m0, s7
	s_nop 0
	global_load_lds_dwordx4 v[88:89], off
	s_mov_b32 m0, s13
	v_mfma_f32_16x16x32_bf16 v[112:115], v[156:159], v[24:27], v[112:115]
	v_mfma_f32_16x16x32_bf16 v[124:127], v[160:163], v[24:27], v[124:127]
	v_mfma_f32_16x16x32_bf16 v[136:139], v[164:167], v[24:27], v[136:139]
	v_mfma_f32_16x16x32_bf16 v[12:15], v[168:171], v[24:27], v[12:15]
	v_lshl_add_u64 v[24:25], v[6:7], 0, s[14:15]
	s_mov_b32 s7, m0
	s_mov_b32 m0, s8
	s_nop 0
	global_load_lds_dwordx4 v[24:25], off
	s_mov_b32 m0, s7
	v_lshl_add_u64 v[24:25], v[6:7], 0, s[16:17]
	s_mov_b32 s7, m0
	s_mov_b32 m0, s9
	s_nop 0
	global_load_lds_dwordx4 v[24:25], off
	s_mov_b32 m0, s7
	s_mov_b64 s[8:9], 0x61c0
	v_lshl_add_u64 v[6:7], v[6:7], 0, s[8:9]
	s_mov_b32 s7, m0
	s_mov_b32 m0, s10
	s_nop 0
	global_load_lds_dwordx4 v[6:7], off
	s_mov_b32 m0, s7
	v_lshl_add_u64 v[6:7], v[8:9], 0, s[14:15]
	s_mov_b32 s7, m0
	s_mov_b32 m0, s11
	s_nop 0
	global_load_lds_dwordx4 v[172:173], off
	s_mov_b32 m0, s7
	v_mfma_f32_16x16x32_bf16 v[116:119], v[156:159], v[108:111], v[116:119]
	s_mov_b32 s7, m0
	s_mov_b32 m0, s12
	s_nop 0
	global_load_lds_dwordx4 v[6:7], off
	s_mov_b32 m0, s7
	v_readlane_b32 s8, v255, 5
	v_readlane_b32 s14, v255, 11
	v_mfma_f32_16x16x32_bf16 v[120:123], v[156:159], v[148:151], v[120:123]
	v_readlane_b32 s9, v255, 6
	v_readlane_b32 s10, v255, 7
	v_readlane_b32 s11, v255, 8
	v_mfma_f32_16x16x32_bf16 v[96:99], v[156:159], v[152:155], v[96:99]
	v_readlane_b32 s12, v255, 9
	v_readlane_b32 s13, v255, 10
	v_readlane_b32 s15, v255, 12
	v_mfma_f32_16x16x32_bf16 v[128:131], v[160:163], v[108:111], v[128:131]
	s_add_i32 s4, s5, s14
	v_mfma_f32_16x16x32_bf16 v[132:135], v[160:163], v[148:151], v[132:135]
	v_mfma_f32_16x16x32_bf16 v[100:103], v[160:163], v[152:155], v[100:103]
	v_mfma_f32_16x16x32_bf16 v[140:143], v[164:167], v[108:111], v[140:143]
	v_mfma_f32_16x16x32_bf16 v[144:147], v[164:167], v[148:151], v[144:147]
	v_mfma_f32_16x16x32_bf16 v[104:107], v[164:167], v[152:155], v[104:107]
	v_mfma_f32_16x16x32_bf16 v[16:19], v[168:171], v[108:111], v[16:19]
	v_mfma_f32_16x16x32_bf16 v[20:23], v[168:171], v[148:151], v[20:23]
	v_mfma_f32_16x16x32_bf16 v[2:5], v[168:171], v[152:155], v[2:5]
	ds_read_b128 v[6:9], v11 offset:49152
	ds_read_b128 v[24:27], v11 offset:50176
	ds_read_b128 v[108:111], v11 offset:51200
	ds_read_b128 v[148:151], v11 offset:52224
	ds_read_b128 v[152:155], v174
	ds_read_b128 v[156:159], v175
	ds_read_b128 v[160:163], v176
	ds_read_b128 v[164:167], v177
	s_waitcnt lgkmcnt(3)
	v_mfma_f32_16x16x32_bf16 v[44:47], v[152:155], v[6:9], v[44:47]
	v_mfma_f32_16x16x32_bf16 v[48:51], v[152:155], v[24:27], v[48:51]
	v_mfma_f32_16x16x32_bf16 v[52:55], v[152:155], v[108:111], v[52:55]
	v_mfma_f32_16x16x32_bf16 v[28:31], v[152:155], v[148:151], v[28:31]
	s_waitcnt lgkmcnt(2)
	v_mfma_f32_16x16x32_bf16 v[56:59], v[156:159], v[6:9], v[56:59]
	v_mfma_f32_16x16x32_bf16 v[60:63], v[156:159], v[24:27], v[60:63]
	v_mfma_f32_16x16x32_bf16 v[64:67], v[156:159], v[108:111], v[64:67]
	v_mfma_f32_16x16x32_bf16 v[32:35], v[156:159], v[148:151], v[32:35]
	s_waitcnt lgkmcnt(1)
	v_mfma_f32_16x16x32_bf16 v[68:71], v[160:163], v[6:9], v[68:71]
	v_mfma_f32_16x16x32_bf16 v[72:75], v[160:163], v[24:27], v[72:75]
	v_mfma_f32_16x16x32_bf16 v[76:79], v[160:163], v[108:111], v[76:79]
	v_mfma_f32_16x16x32_bf16 v[36:39], v[160:163], v[148:151], v[36:39]
	s_waitcnt lgkmcnt(0)
	v_mfma_f32_16x16x32_bf16 v[80:83], v[164:167], v[6:9], v[80:83]
	v_mfma_f32_16x16x32_bf16 v[84:87], v[164:167], v[24:27], v[84:87]
	v_mfma_f32_16x16x32_bf16 v[92:95], v[164:167], v[108:111], v[92:95]
	v_mfma_f32_16x16x32_bf16 v[40:43], v[164:167], v[148:151], v[40:43]
	ds_read_b128 v[152:155], v178
	ds_read_b128 v[156:159], v179
	ds_read_b128 v[160:163], v180
	ds_read_b128 v[164:167], v181
	s_waitcnt vmcnt(6)
	s_waitcnt lgkmcnt(0)
	v_mfma_f32_16x16x32_bf16 v[112:115], v[152:155], v[6:9], v[112:115]
	s_barrier
	v_mfma_f32_16x16x32_bf16 v[116:119], v[152:155], v[24:27], v[116:119]
	v_mfma_f32_16x16x32_bf16 v[120:123], v[152:155], v[108:111], v[120:123]
	v_mfma_f32_16x16x32_bf16 v[96:99], v[152:155], v[148:151], v[96:99]
	v_mfma_f32_16x16x32_bf16 v[124:127], v[156:159], v[6:9], v[124:127]
	v_mfma_f32_16x16x32_bf16 v[128:131], v[156:159], v[24:27], v[128:131]
	v_mfma_f32_16x16x32_bf16 v[132:135], v[156:159], v[108:111], v[132:135]
	v_mfma_f32_16x16x32_bf16 v[100:103], v[156:159], v[148:151], v[100:103]
	v_mfma_f32_16x16x32_bf16 v[136:139], v[160:163], v[6:9], v[136:139]
	v_mfma_f32_16x16x32_bf16 v[140:143], v[160:163], v[24:27], v[140:143]
	v_mfma_f32_16x16x32_bf16 v[144:147], v[160:163], v[108:111], v[144:147]
	v_mfma_f32_16x16x32_bf16 v[104:107], v[160:163], v[148:151], v[104:107]
	v_mfma_f32_16x16x32_bf16 v[6:9], v[164:167], v[6:9], v[12:15]
	v_mfma_f32_16x16x32_bf16 v[12:15], v[164:167], v[24:27], v[16:19]
	v_mfma_f32_16x16x32_bf16 v[16:19], v[164:167], v[108:111], v[20:23]
	v_mfma_f32_16x16x32_bf16 v[2:5], v[164:167], v[148:151], v[2:5]
	s_nop 1
	ds_read_b128 v[20:23], v10 offset:23552
	ds_read_b128 v[24:27], v10 offset:22528
	ds_read_b128 v[108:111], v10 offset:21504
	ds_read_b128 v[148:151], v10 offset:20480
	ds_read_b128 v[152:155], v10 offset:19456
	ds_read_b128 v[156:159], v10 offset:18432
	ds_read_b128 v[160:163], v10 offset:17408
	ds_read_b128 v[164:167], v10 offset:16384
	ds_read_b128 v[168:171], v11 offset:3072
	ds_read_b128 v[172:175], v11 offset:2048
	ds_read_b128 v[176:179], v11 offset:1024
	ds_read_b128 v[186:189], v11
	s_waitcnt vmcnt(0)
	s_waitcnt lgkmcnt(0)
	v_mfma_f32_16x16x32_bf16 v[44:47], v[164:167], v[186:189], v[44:47]
	s_barrier
; template <int N> DI void wait_vm() { asm volatile("s_waitcnt vmcnt(%0)" ::"n"(N) : "memory"); }
; DI void st_bf4(u16* p, float a, float b, float c, float d) { *(uint2*)p = make_uint2(pk2(a, b), pk2(c, d)); }
; template <int BM, class Epi>
; DI void gemm_dma(const u16* __restrict__ X, long ldx, const u16* __restrict__ W, long ldw, int K, char* smem,
;                  int m0, int n0, const Epi& epi) {
;     ...
;   do {
;     if (kt + D - 2 < nk) wait_vm<PW * (D - 2)>(); else wait_vm<0>();
;     __syncthreads();
;     if (kt + D - 1 < nk) GD_ISSUE(nxt)
;     nxt = (nxt + 1 == D) ? 0 : nxt + 1;
;     const char* base = smem + cur * STG;
;     cur = (cur + 1 == D) ? 0 : cur + 1;
;     bf16x8 xf[MT];
; #pragma unroll
;     for (int i = 0; i < MT; ++i) xf[i] = *(const bf16x8*)(base + (xrow0 + i * 16) * 64 + rd);
; #pragma unroll
;     for (int nh = 0; nh < NT / 4; ++nh) {
;       bf16x8 wf[4];
; #pragma unroll
;       for (int i = 0; i < 4; ++i) wf[i] = *(const bf16x8*)(base + BM * 64 + (wrow0 + (nh * 4 + i) * 16) * 64 + rd);
; #pragma unroll
;       for (int i = 0; i < 4; ++i)
; #pragma unroll
;         for (int mt = 0; mt < MT; ++mt)
;           acc[nh * 4 + i][mt] = __builtin_amdgcn_mfma_f32_16x16x32_bf16(wf[i], xf[mt], acc[nh * 4 + i][mt], 0, 0, 0);
;     }
;   } while (++kt < nk);
;   template <int NT, int MT> DI void run(f32x4 (&acc)[NT][MT], int mb, int nb) const {
; #pragma unroll
;     for (int nt = 0; nt < NT; ++nt)
; #pragma unroll
;       for (int mt = 0; mt < MT; ++mt) {
;         f32x4 v = acc[nt][mt];
;         st_bf4(C + (size_t)(mb + mt * 16) * ldc + nb + nt * 16, v[0], v[1], v[2], v[3]);
;       }
;   }
	v_mfma_f32_16x16x32_bf16 v[48:51], v[164:167], v[176:179], v[48:51]
	v_mfma_f32_16x16x32_bf16 v[52:55], v[164:167], v[172:175], v[52:55]
	v_mfma_f32_16x16x32_bf16 v[28:31], v[164:167], v[168:171], v[28:31]
	v_mfma_f32_16x16x32_bf16 v[56:59], v[160:163], v[186:189], v[56:59]
	v_mfma_f32_16x16x32_bf16 v[60:63], v[160:163], v[176:179], v[60:63]
	v_mfma_f32_16x16x32_bf16 v[64:67], v[160:163], v[172:175], v[64:67]
	v_mfma_f32_16x16x32_bf16 v[32:35], v[160:163], v[168:171], v[32:35]
	v_mfma_f32_16x16x32_bf16 v[68:71], v[156:159], v[186:189], v[68:71]
	v_mfma_f32_16x16x32_bf16 v[72:75], v[156:159], v[176:179], v[72:75]
	v_mfma_f32_16x16x32_bf16 v[76:79], v[156:159], v[172:175], v[76:79]
	v_mfma_f32_16x16x32_bf16 v[36:39], v[156:159], v[168:171], v[36:39]
	v_mfma_f32_16x16x32_bf16 v[156:159], v[152:155], v[186:189], v[80:83]
	v_mfma_f32_16x16x32_bf16 v[86:89], v[152:155], v[176:179], v[84:87]
	v_mfma_f32_16x16x32_bf16 v[92:95], v[152:155], v[172:175], v[92:95]
	v_mfma_f32_16x16x32_bf16 v[152:155], v[152:155], v[168:171], v[40:43]
	v_mfma_f32_16x16x32_bf16 v[112:115], v[148:151], v[186:189], v[112:115]
	v_mfma_f32_16x16x32_bf16 v[116:119], v[148:151], v[176:179], v[116:119]
	v_mfma_f32_16x16x32_bf16 v[120:123], v[148:151], v[172:175], v[120:123]
	v_mfma_f32_16x16x32_bf16 v[96:99], v[148:151], v[168:171], v[96:99]
	v_mfma_f32_16x16x32_bf16 v[124:127], v[108:111], v[186:189], v[124:127]
	v_mfma_f32_16x16x32_bf16 v[128:131], v[108:111], v[176:179], v[128:131]
	v_mfma_f32_16x16x32_bf16 v[132:135], v[108:111], v[172:175], v[132:135]
	v_mfma_f32_16x16x32_bf16 v[100:103], v[108:111], v[168:171], v[100:103]
	v_mfma_f32_16x16x32_bf16 v[108:111], v[24:27], v[186:189], v[136:139]
	v_mfma_f32_16x16x32_bf16 v[136:139], v[24:27], v[176:179], v[140:143]
	v_mfma_f32_16x16x32_bf16 v[140:143], v[24:27], v[172:175], v[144:147]
	v_mfma_f32_16x16x32_bf16 v[104:107], v[24:27], v[168:171], v[104:107]
	v_mfma_f32_16x16x32_bf16 v[6:9], v[20:23], v[186:189], v[6:9]
	v_mfma_f32_16x16x32_bf16 v[144:147], v[20:23], v[176:179], v[12:15]
	v_mfma_f32_16x16x32_bf16 v[148:151], v[20:23], v[172:175], v[16:19]
	v_mfma_f32_16x16x32_bf16 v[2:5], v[20:23], v[168:171], v[2:5]
	s_nop 0
	ds_read_b128 v[12:15], v11 offset:24576
	ds_read_b128 v[160:163], v11 offset:25600
	ds_read_b128 v[164:167], v11 offset:26624
	ds_read_b128 v[168:171], v11 offset:27648
	ds_read_b128 v[16:19], v10 offset:40960
	ds_read_b128 v[20:23], v10 offset:41984
	ds_read_b128 v[24:27], v10 offset:43008
	ds_read_b128 v[172:175], v10 offset:44032
	s_waitcnt lgkmcnt(3)
	v_mfma_f32_16x16x32_bf16 v[176:179], v[16:19], v[12:15], v[44:47]
	v_mfma_f32_16x16x32_bf16 v[186:189], v[16:19], v[160:163], v[48:51]
	v_mfma_f32_16x16x32_bf16 v[190:193], v[16:19], v[164:167], v[52:55]
	v_mfma_f32_16x16x32_bf16 v[194:197], v[16:19], v[168:171], v[28:31]
	s_waitcnt lgkmcnt(2)
	v_mfma_f32_16x16x32_bf16 v[224:227], v[20:23], v[12:15], v[56:59]
	v_mfma_f32_16x16x32_bf16 v[228:231], v[20:23], v[160:163], v[60:63]
	v_mfma_f32_16x16x32_bf16 v[232:235], v[20:23], v[164:167], v[64:67]
	v_mfma_f32_16x16x32_bf16 v[236:239], v[20:23], v[168:171], v[32:35]
	s_waitcnt lgkmcnt(1)
	v_mfma_f32_16x16x32_bf16 v[240:243], v[24:27], v[12:15], v[68:71]
	v_mfma_f32_16x16x32_bf16 v[66:69], v[24:27], v[168:171], v[36:39]
	s_waitcnt lgkmcnt(0)
	v_mfma_f32_16x16x32_bf16 v[42:45], v[172:175], v[164:167], v[92:95]
	v_mfma_f32_16x16x32_bf16 v[34:37], v[172:175], v[168:171], v[152:155]
	ds_read_b128 v[16:19], v10 offset:45056
	ds_read_b128 v[20:23], v10 offset:46080
	ds_read_b128 v[92:95], v10 offset:47104
	ds_read_b128 v[152:155], v10 offset:48128
	s_nop 0
	v_cvt_pk_bf16_f32 v66, v66, v67
	v_cvt_pk_bf16_f32 v67, v68, v69
	v_mfma_f32_16x16x32_bf16 v[82:85], v[24:27], v[160:163], v[72:75]
	v_cvt_pk_bf16_f32 v34, v34, v35
	v_cvt_pk_bf16_f32 v35, v36, v37
	v_cvt_pk_bf16_f32 v42, v42, v43
	v_mfma_f32_16x16x32_bf16 v[74:77], v[24:27], v[164:167], v[76:79]
	v_cvt_pk_bf16_f32 v43, v44, v45
	s_nop 2
	v_cvt_pk_bf16_f32 v82, v82, v83
	v_cvt_pk_bf16_f32 v83, v84, v85
	v_mfma_f32_16x16x32_bf16 v[50:53], v[172:175], v[160:163], v[86:89]
	s_waitcnt lgkmcnt(3)
	v_mfma_f32_16x16x32_bf16 v[112:115], v[16:19], v[12:15], v[112:115]
	v_cvt_pk_bf16_f32 v74, v74, v75
	v_cvt_pk_bf16_f32 v75, v76, v77
	s_nop 3
	v_cvt_pk_bf16_f32 v50, v50, v51
	v_mfma_f32_16x16x32_bf16 v[86:89], v[16:19], v[160:163], v[116:119]
	v_cvt_pk_bf16_f32 v51, v52, v53
	v_mfma_f32_16x16x32_bf16 v[78:81], v[16:19], v[164:167], v[120:123]
	v_mfma_f32_16x16x32_bf16 v[70:73], v[16:19], v[168:171], v[96:99]
	s_waitcnt lgkmcnt(2)
	v_mfma_f32_16x16x32_bf16 v[62:65], v[20:23], v[12:15], v[124:127]
	s_nop 0
	v_cvt_pk_bf16_f32 v96, v186, v187
	v_cvt_pk_bf16_f32 v97, v188, v189
	v_cvt_pk_bf16_f32 v98, v190, v191
	v_mfma_f32_16x16x32_bf16 v[54:57], v[20:23], v[160:163], v[128:131]
	v_cvt_pk_bf16_f32 v99, v192, v193
	v_mfma_f32_16x16x32_bf16 v[46:49], v[20:23], v[164:167], v[132:135]
	v_mfma_f32_16x16x32_bf16 v[38:41], v[20:23], v[168:171], v[100:103]
	s_waitcnt lgkmcnt(1)
; DI void st_bf4(u16* p, float a, float b, float c, float d) { *(uint2*)p = make_uint2(pk2(a, b), pk2(c, d)); }
; template <int BM, class Epi>
; DI void gemm_dma(const u16* __restrict__ X, long ldx, const u16* __restrict__ W, long ldw, int K, char* smem,
;                  int m0, int n0, const Epi& epi) {
;     ...
;       for (int i = 0; i < 4; ++i)
; #pragma unroll
;         for (int mt = 0; mt < MT; ++mt)
;           acc[nh * 4 + i][mt] = __builtin_amdgcn_mfma_f32_16x16x32_bf16(wf[i], xf[mt], acc[nh * 4 + i][mt], 0, 0, 0);
;     }
;   } while (++kt < nk);
;     ...
;   epi.run(acc, m0 + xrow0 + lr, n0 + wrow0 + 4 * g);
;   template <int NT, int MT> DI void run(f32x4 (&acc)[NT][MT], int mb, int nb) const {
; #pragma unroll
;     for (int nt = 0; nt < NT; ++nt)
; #pragma unroll
;       for (int mt = 0; mt < MT; ++mt) {
;         f32x4 v = acc[nt][mt];
;         st_bf4(C + (size_t)(mb + mt * 16) * ldc + nb + nt * 16, v[0], v[1], v[2], v[3]);
;       }
;   }
	v_mfma_f32_16x16x32_bf16 v[30:33], v[92:95], v[12:15], v[108:111]
	v_mfma_f32_16x16x32_bf16 v[26:29], v[92:95], v[160:163], v[136:139]
	v_mfma_f32_16x16x32_bf16 v[22:25], v[92:95], v[164:167], v[140:143]
	s_nop 5
	v_cvt_pk_bf16_f32 v30, v30, v31
	v_cvt_pk_bf16_f32 v31, v32, v33
	v_cvt_pk_bf16_f32 v26, v26, v27
	v_mfma_f32_16x16x32_bf16 v[18:21], v[92:95], v[168:171], v[104:107]
	v_or_b32_e32 v94, v91, v90
	v_ashrrev_i32_e32 v95, 31, v94
	v_lshlrev_b64 v[90:91], 11, v[94:95]
	v_lshl_add_u64 v[90:91], s[92:93], 0, v[90:91]
	v_lshl_add_u64 v[90:91], v[90:91], 0, v[182:183]
	v_cvt_pk_bf16_f32 v92, v176, v177
	v_cvt_pk_bf16_f32 v93, v178, v179
	global_store_dwordx2 v[90:91], v[92:93], off
	v_or_b32_e32 v92, 16, v94
	v_ashrrev_i32_e32 v93, 31, v92
	v_lshlrev_b64 v[92:93], 11, v[92:93]
	v_lshl_add_u64 v[92:93], s[92:93], 0, v[92:93]
	v_lshl_add_u64 v[92:93], v[92:93], 0, v[182:183]
	global_store_dwordx2 v[92:93], v[96:97], off
	v_or_b32_e32 v96, 32, v94
	v_or_b32_e32 v94, 48, v94
	v_ashrrev_i32_e32 v95, 31, v94
	v_lshlrev_b64 v[94:95], 11, v[94:95]
	v_ashrrev_i32_e32 v97, 31, v96
	v_lshl_add_u64 v[94:95], s[92:93], 0, v[94:95]
	v_lshlrev_b64 v[96:97], 11, v[96:97]
	v_lshl_add_u64 v[94:95], v[94:95], 0, v[182:183]
	v_lshl_add_u64 v[96:97], s[92:93], 0, v[96:97]
	global_store_dwordx2 v[94:95], v[34:35], off offset:96
	v_cvt_pk_bf16_f32 v34, v112, v113
	v_cvt_pk_bf16_f32 v35, v114, v115
	v_lshl_add_u64 v[96:97], v[96:97], 0, v[182:183]
	global_store_dwordx2 v[90:91], v[34:35], off offset:128
	v_cvt_pk_bf16_f32 v34, v86, v87
	v_cvt_pk_bf16_f32 v35, v88, v89
	global_store_dwordx2 v[96:97], v[98:99], off
	v_cvt_pk_bf16_f32 v98, v194, v195
	v_cvt_pk_bf16_f32 v99, v196, v197
	global_store_dwordx2 v[92:93], v[34:35], off offset:128
	v_cvt_pk_bf16_f32 v34, v78, v79
	v_cvt_pk_bf16_f32 v35, v80, v81
	v_mfma_f32_16x16x32_bf16 v[58:61], v[172:175], v[12:15], v[156:159]
	global_store_dwordx2 v[94:95], v[98:99], off
	v_cvt_pk_bf16_f32 v98, v224, v225
	v_cvt_pk_bf16_f32 v99, v226, v227
	s_waitcnt lgkmcnt(0)
	v_mfma_f32_16x16x32_bf16 v[14:17], v[152:155], v[12:15], v[6:9]
	global_store_dwordx2 v[96:97], v[34:35], off offset:128
	v_cvt_pk_bf16_f32 v34, v70, v71
	v_cvt_pk_bf16_f32 v35, v72, v73
	v_mfma_f32_16x16x32_bf16 v[10:13], v[152:155], v[160:163], v[144:147]
	global_store_dwordx2 v[90:91], v[98:99], off offset:32
	v_cvt_pk_bf16_f32 v98, v228, v229
	v_cvt_pk_bf16_f32 v99, v230, v231
	v_mfma_f32_16x16x32_bf16 v[6:9], v[152:155], v[164:167], v[148:151]
	global_store_dwordx2 v[94:95], v[34:35], off offset:128
	v_cvt_pk_bf16_f32 v34, v62, v63
	v_cvt_pk_bf16_f32 v35, v64, v65
	v_mfma_f32_16x16x32_bf16 v[2:5], v[152:155], v[168:171], v[2:5]
	global_store_dwordx2 v[92:93], v[98:99], off offset:32
	v_cvt_pk_bf16_f32 v98, v232, v233
	v_cvt_pk_bf16_f32 v99, v234, v235
	global_store_dwordx2 v[90:91], v[34:35], off offset:160
	v_cvt_pk_bf16_f32 v34, v54, v55
	v_cvt_pk_bf16_f32 v35, v56, v57
	global_store_dwordx2 v[96:97], v[98:99], off offset:32
	v_cvt_pk_bf16_f32 v98, v236, v237
	v_cvt_pk_bf16_f32 v99, v238, v239
	global_store_dwordx2 v[92:93], v[34:35], off offset:160
	v_cvt_pk_bf16_f32 v34, v46, v47
	v_cvt_pk_bf16_f32 v35, v48, v49
	global_store_dwordx2 v[94:95], v[98:99], off offset:32
	v_cvt_pk_bf16_f32 v98, v240, v241
	v_cvt_pk_bf16_f32 v99, v242, v243
	v_cvt_pk_bf16_f32 v58, v58, v59
	v_cvt_pk_bf16_f32 v59, v60, v61
	global_store_dwordx2 v[96:97], v[34:35], off offset:160
	v_cvt_pk_bf16_f32 v34, v38, v39
	v_cvt_pk_bf16_f32 v35, v40, v41
	v_cvt_pk_bf16_f32 v27, v28, v29
	v_cvt_pk_bf16_f32 v22, v22, v23
	v_cvt_pk_bf16_f32 v23, v24, v25
	v_cvt_pk_bf16_f32 v18, v18, v19
	v_cvt_pk_bf16_f32 v19, v20, v21
	v_cvt_pk_bf16_f32 v14, v14, v15
	v_cvt_pk_bf16_f32 v15, v16, v17
	v_cvt_pk_bf16_f32 v10, v10, v11
	v_cvt_pk_bf16_f32 v11, v12, v13
	v_cvt_pk_bf16_f32 v6, v6, v7
	v_cvt_pk_bf16_f32 v7, v8, v9
	v_cvt_pk_bf16_f32 v2, v2, v3
	v_cvt_pk_bf16_f32 v3, v4, v5
	global_store_dwordx2 v[90:91], v[98:99], off offset:64
	global_store_dwordx2 v[92:93], v[82:83], off offset:64
	global_store_dwordx2 v[96:97], v[74:75], off offset:64
	global_store_dwordx2 v[94:95], v[66:67], off offset:64
	global_store_dwordx2 v[90:91], v[58:59], off offset:96
	global_store_dwordx2 v[92:93], v[50:51], off offset:96
	global_store_dwordx2 v[96:97], v[42:43], off offset:96
	global_store_dwordx2 v[94:95], v[34:35], off offset:160
	global_store_dwordx2 v[90:91], v[30:31], off offset:192
	global_store_dwordx2 v[92:93], v[26:27], off offset:192
	global_store_dwordx2 v[96:97], v[22:23], off offset:192
	global_store_dwordx2 v[94:95], v[18:19], off offset:192
	global_store_dwordx2 v[90:91], v[14:15], off offset:224
	global_store_dwordx2 v[92:93], v[10:11], off offset:224
	global_store_dwordx2 v[96:97], v[6:7], off offset:224
	global_store_dwordx2 v[94:95], v[2:3], off offset:224

; template <int N> DI void wait_vm() { asm volatile("s_waitcnt vmcnt(%0)" ::"n"(N) : "memory"); }
; template <int BM, class Epi>
; DI void gemm_dma(const u16* __restrict__ X, long ldx, const u16* __restrict__ W, long ldw, int K, char* smem,
;                  int m0, int n0, const Epi& epi) {
;     ...
;   const int wu = __builtin_amdgcn_readfirstlane(wave);
;   const unsigned sbase = (unsigned)__builtin_amdgcn_readfirstlane((int)(unsigned)(size_t)smem);
;   const int r16 = lane >> 2, chunk = (lane & 3) ^ ((4 - (r16 >> 2)) & 3);
;   const u16* xs = X + (long)(wu * XD * 16 + r16) * ldx + (chunk << 3);
;   const u16* ws = W + (long)(wu * 32 + r16) * ldw + (chunk << 3);
;   const long ldx16 = 16 * ldx, ldw16 = 16 * ldw;
;   const unsigned xdst = sbase + wu * XD * 1024, wdst = sbase + BM * 64 + wu * 2048;
;     ...
;   const int nk = K >> 5;
;   __syncthreads();
; #pragma unroll
;   for (int s = 0; s < D - 1; ++s) GD_ISSUE(s)
;   int cur = 0, nxt = D - 1, kt = 0;
;   do {
;     if (kt + D - 2 < nk) wait_vm<PW * (D - 2)>(); else wait_vm<0>();
;     __syncthreads();
;     if (kt + D - 1 < nk) GD_ISSUE(nxt)
;     nxt = (nxt + 1 == D) ? 0 : nxt + 1;
;     const char* base = smem + cur * STG;
;     cur = (cur + 1 == D) ? 0 : cur + 1;
;     bf16x8 xf[MT];
; #pragma unroll
;     for (int i = 0; i < MT; ++i) xf[i] = *(const bf16x8*)(base + (xrow0 + i * 16) * 64 + rd);
; #pragma unroll
;     for (int nh = 0; nh < NT / 4; ++nh) {
;       bf16x8 wf[4];
; #pragma unroll
;       for (int i = 0; i < 4; ++i) wf[i] = *(const bf16x8*)(base + BM * 64 + (wrow0 + (nh * 4 + i) * 16) * 64 + rd);
; DI void knope_tile(const Params& p, int u, char* smem) {
;     ...
;   const int tm = u >> 3, tn = u & 7;
;   gemm_dma<256>(ckvb + (size_t)tm * 256 * 256, 256, W + WO_KV + (size_t)tn * 128 * 256, 256, 256, smem, tm * 256, tn * 128, ek);
.LBB0_966:
	s_cmpk_gt_i32 s4, 0x77f
	s_cbranch_scc1 .LBB0_974
	s_cmpk_gt_i32 s4, 0x43f
	s_mov_b64 s[38:39], -1
	s_cbranch_scc0 .LBB0_969
	s_add_i32 s5, s4, 0xfffffcc0
	s_bfe_u32 s98, s5, 0x30003
	s_and_b32 s99, s5, 7
	s_lshl_b32 s99, s99, 3
	s_andn2_b32 s5, s5, 63
	s_or_b32 s5, s5, s99
	s_or_b32 s5, s5, s98
	s_lshr_b32 s6, s5, 3
	s_and_b32 s5, s5, 7
	s_lshl_b32 s7, s6, 17
	s_add_u32 s8, s0, s7
	s_addc_u32 s9, s1, 0
	s_lshl_b32 s7, s5, 16
	v_mov_b32_e32 v9, v185
	s_add_u32 s10, s87, s7
	s_addc_u32 s11, s90, 0
	v_readfirstlane_b32 s7, v9
	v_lshrrev_b32_e32 v4, 4, v9
	s_ashr_i32 s12, s7, 6
	v_bfe_u32 v6, v9, 2, 4
	v_sub_u32_e32 v4, 0, v4
	s_andn2_b32 s7, s7, 63
	v_lshrrev_b32_e32 v1, 2, v9
	v_xor_b32_e32 v7, v9, v4
	v_or_b32_e32 v4, s7, v6
	v_and_b32_e32 v89, 15, v9
	v_bfe_u32 v88, v9, 4, 2
	v_sub_u32_e32 v1, 0, v1
	v_ashrrev_i32_e32 v5, 31, v4
	v_lshlrev_b32_e32 v0, 6, v89
	v_bitop3_b32 v1, v88, v1, 3 bitop3:0x78
	v_lshlrev_b64 v[4:5], 9, v[4:5]
	v_lshlrev_b32_e32 v7, 4, v7
	v_lshl_or_b32 v6, s12, 5, v6
	v_lshl_or_b32 v8, v1, 4, v0
	v_mov_b32_e32 v0, v183
	v_lshl_add_u64 v[4:5], s[8:9], 0, v[4:5]
	v_and_b32_e32 v182, 48, v7
	v_ashrrev_i32_e32 v7, 31, v6
	v_lshl_add_u64 v[4:5], v[4:5], 0, v[182:183]
	v_lshlrev_b64 v[6:7], 9, v[6:7]
	s_lshl_b32 s14, s12, 12
	s_waitcnt lgkmcnt(0)
	s_barrier
	s_mov_b32 s7, m0
	s_mov_b32 m0, s14
	s_nop 0
	global_load_lds_dwordx4 v[4:5], off
	s_mov_b32 m0, s7
	s_mov_b64 s[8:9], 0x2000
	v_lshl_add_u64 v[6:7], s[10:11], 0, v[6:7]
	v_lshl_add_u64 v[10:11], v[4:5], 0, s[8:9]
	s_or_b32 s15, s14, 0x400
	s_mov_b32 s7, m0
	s_mov_b32 m0, s15
	s_nop 0
	global_load_lds_dwordx4 v[10:11], off
	s_mov_b32 m0, s7
	s_mov_b64 s[10:11], 0x4000
	v_lshl_add_u64 v[10:11], v[4:5], 0, s[10:11]
	s_or_b32 s16, s14, 0x800
	s_mov_b32 s7, m0
	s_mov_b32 m0, s16
	s_nop 0
	global_load_lds_dwordx4 v[10:11], off
	s_mov_b32 m0, s7
	s_mov_b64 s[10:11], 0x6000
	s_lshl_b32 s41, s12, 11
	v_lshl_add_u64 v[10:11], v[4:5], 0, s[10:11]
	s_or_b32 s17, s14, 0xc00
	s_mov_b32 s7, m0
	s_mov_b32 m0, s17
	s_nop 0
	global_load_lds_dwordx4 v[10:11], off
	s_mov_b32 m0, s7
	v_lshl_add_u64 v[6:7], v[6:7], 0, v[182:183]
	s_add_i32 s13, s41, 0x4000
	s_mov_b32 s7, m0
	s_mov_b32 m0, s13
	s_nop 0
	global_load_lds_dwordx4 v[6:7], off
	s_mov_b32 m0, s7
	v_lshl_add_u64 v[10:11], v[6:7], 0, s[8:9]
	s_add_i32 s18, s41, 0x4400
	s_mov_b32 s7, m0
	s_mov_b32 m0, s18
	s_nop 0
	global_load_lds_dwordx4 v[10:11], off
	s_mov_b32 m0, s7
	v_lshl_add_u64 v[10:11], v[4:5], 0, 64
	s_add_i32 s7, s14, 0x6000
	s_mov_b32 s8, m0
	s_mov_b32 m0, s7
	s_nop 0
	global_load_lds_dwordx4 v[10:11], off
	s_mov_b32 m0, s8
	s_mov_b64 s[20:21], 0x2040
	v_lshl_add_u64 v[10:11], v[4:5], 0, s[20:21]
	s_add_i32 s8, s14, 0x6400
	s_mov_b32 s9, m0
	s_mov_b32 m0, s8
	s_nop 0
	global_load_lds_dwordx4 v[10:11], off
	s_mov_b32 m0, s9
	s_mov_b64 s[10:11], 0x4040
	v_lshl_add_u64 v[10:11], v[4:5], 0, s[10:11]
	s_add_i32 s9, s14, 0x6800
	s_mov_b32 s10, m0
	s_mov_b32 m0, s9
	s_nop 0
	global_load_lds_dwordx4 v[10:11], off
	s_mov_b32 m0, s10
	s_mov_b64 s[10:11], 0x6040
	v_lshl_add_u64 v[10:11], v[4:5], 0, s[10:11]
	s_add_i32 s10, s14, 0x6c00
	s_mov_b32 s11, m0
	s_mov_b32 m0, s10
	s_nop 0
	global_load_lds_dwordx4 v[10:11], off
	s_mov_b32 m0, s11
	v_lshl_add_u64 v[12:13], v[6:7], 0, 64
	s_add_i32 s11, s41, 0xa000
	s_mov_b32 s12, m0
	s_mov_b32 m0, s11
	s_nop 0
	global_load_lds_dwordx4 v[12:13], off
	s_mov_b32 m0, s12
	v_lshl_add_u64 v[10:11], v[6:7], 0, s[20:21]
	s_add_i32 s12, s41, 0xa400
	s_mov_b32 s19, m0
	s_mov_b32 m0, s12
	s_nop 0
	global_load_lds_dwordx4 v[10:11], off
	s_mov_b32 m0, s19
	s_waitcnt vmcnt(6)
	s_barrier
	v_lshl_add_u64 v[12:13], v[4:5], 0, s[28:29]
	s_add_i32 s19, s14, 0xc000
	s_mov_b32 s34, m0
	s_mov_b32 m0, s19
	s_nop 0
	global_load_lds_dwordx4 v[12:13], off
	s_mov_b32 m0, s34
	s_mov_b64 s[20:21], 0x2080
	v_lshl_add_u64 v[12:13], v[4:5], 0, s[20:21]
	s_add_i32 s34, s14, 0xc400
	s_mov_b32 s38, m0
	s_mov_b32 m0, s34
	s_nop 0
	global_load_lds_dwordx4 v[12:13], off
	s_mov_b32 m0, s38
	v_lshl_add_u64 v[12:13], v[4:5], 0, s[94:95]
	s_add_i32 s38, s14, 0xc800
	s_mov_b32 s39, m0
	s_mov_b32 m0, s38
	s_nop 0
	global_load_lds_dwordx4 v[12:13], off
	s_mov_b32 m0, s39
	s_mov_b64 s[22:23], 0x6080
	v_lshl_add_u64 v[12:13], v[4:5], 0, s[22:23]
	s_add_i32 s39, s14, 0xcc00
	s_mov_b32 s40, m0
	s_mov_b32 m0, s39
	s_nop 0
	global_load_lds_dwordx4 v[12:13], off
	s_mov_b32 m0, s40
	v_and_b32_e32 v90, 0xffffffc0, v9
	v_lshl_add_u64 v[10:11], v[6:7], 0, s[28:29]
	s_add_i32 s40, s41, 0x10000
	s_mov_b32 s42, m0
	s_mov_b32 m0, s40
	s_nop 0
	global_load_lds_dwordx4 v[10:11], off
	s_mov_b32 m0, s42
	v_lshl_add_u64 v[10:11], v[6:7], 0, s[20:21]
	s_add_i32 s41, s41, 0x10400
	s_mov_b32 s42, m0
	s_mov_b32 m0, s41
	s_nop 0
	global_load_lds_dwordx4 v[10:11], off
	s_mov_b32 m0, s42
	v_lshl_or_b32 v9, v90, 6, v8
	ds_read_b128 v[10:13], v9
	ds_read_b128 v[14:17], v9 offset:1024
	ds_read_b128 v[18:21], v9 offset:2048
	ds_read_b128 v[22:25], v9 offset:3072
	ds_read_b128 v[26:29], v8 offset:16384
	ds_read_b128 v[30:33], v8 offset:17408
	ds_read_b128 v[34:37], v8 offset:18432
	ds_read_b128 v[38:41], v8 offset:19456
	ds_read_b128 v[96:99], v8 offset:20480
	ds_read_b128 v[100:103], v8 offset:21504
	ds_read_b128 v[104:107], v8 offset:22528
	ds_read_b128 v[108:111], v8 offset:23552
	s_mov_b64 s[20:21], 0xc0
	v_mov_b32_e32 v1, v0
	v_mov_b32_e32 v2, v0
	v_mov_b32_e32 v3, v0
	v_lshl_add_u64 v[86:87], v[4:5], 0, s[20:21]
	v_lshl_add_u64 v[148:149], v[6:7], 0, s[20:21]
	s_waitcnt vmcnt(6)
	s_waitcnt lgkmcnt(0)
	s_barrier
; template <int N> DI void wait_vm() { asm volatile("s_waitcnt vmcnt(%0)" ::"n"(N) : "memory"); }
; template <int BM, class Epi>
; DI void gemm_dma(const u16* __restrict__ X, long ldx, const u16* __restrict__ W, long ldw, int K, char* smem,
;                  int m0, int n0, const Epi& epi) {
;     ...
;   do {
;     if (kt + D - 2 < nk) wait_vm<PW * (D - 2)>(); else wait_vm<0>();
;     __syncthreads();
;     if (kt + D - 1 < nk) GD_ISSUE(nxt)
;     nxt = (nxt + 1 == D) ? 0 : nxt + 1;
;     const char* base = smem + cur * STG;
;     cur = (cur + 1 == D) ? 0 : cur + 1;
;     bf16x8 xf[MT];
; #pragma unroll
;     for (int i = 0; i < MT; ++i) xf[i] = *(const bf16x8*)(base + (xrow0 + i * 16) * 64 + rd);
; #pragma unroll
;     for (int nh = 0; nh < NT / 4; ++nh) {
;       bf16x8 wf[4];
; #pragma unroll
;       for (int i = 0; i < 4; ++i) wf[i] = *(const bf16x8*)(base + BM * 64 + (wrow0 + (nh * 4 + i) * 16) * 64 + rd);
; #pragma unroll
;       for (int i = 0; i < 4; ++i)
; #pragma unroll
;         for (int mt = 0; mt < MT; ++mt)
;           acc[nh * 4 + i][mt] = __builtin_amdgcn_mfma_f32_16x16x32_bf16(wf[i], xf[mt], acc[nh * 4 + i][mt], 0, 0, 0);
	s_mov_b32 s42, m0
	s_mov_b32 m0, s14
	s_nop 0
	global_load_lds_dwordx4 v[86:87], off
	s_mov_b32 m0, s42
	s_mov_b64 s[20:21], 0x20c0
	v_mfma_f32_16x16x32_bf16 v[42:45], v[26:29], v[10:13], v[0:3]
	s_mov_b64 s[22:23], 0x40c0
	v_or_b32_e32 v91, 0x10000, v8
	v_or_b32_e32 v174, 0x10400, v8
	v_mfma_f32_16x16x32_bf16 v[46:49], v[26:29], v[14:17], v[0:3]
	v_or_b32_e32 v175, 0x10800, v8
	v_or_b32_e32 v176, 0x10c00, v8
	v_or_b32_e32 v177, 0x11000, v8
	v_mfma_f32_16x16x32_bf16 v[50:53], v[26:29], v[18:21], v[0:3]
	v_or_b32_e32 v178, 0x11400, v8
	v_or_b32_e32 v179, 0x11800, v8
	v_or_b32_e32 v180, 0x11c00, v8
	v_mfma_f32_16x16x32_bf16 v[26:29], v[26:29], v[22:25], v[0:3]
	v_lshl_add_u32 v90, s6, 8, v90
	s_lshl_b32 s5, s5, 8
	v_lshl_or_b32 v182, v88, 3, s5
	v_mfma_f32_16x16x32_bf16 v[54:57], v[30:33], v[10:13], v[0:3]
	v_mfma_f32_16x16x32_bf16 v[58:61], v[30:33], v[14:17], v[0:3]
	v_mfma_f32_16x16x32_bf16 v[62:65], v[30:33], v[18:21], v[0:3]
	v_mfma_f32_16x16x32_bf16 v[30:33], v[30:33], v[22:25], v[0:3]
	v_mfma_f32_16x16x32_bf16 v[66:69], v[34:37], v[10:13], v[0:3]
	v_mfma_f32_16x16x32_bf16 v[70:73], v[34:37], v[14:17], v[0:3]
	v_mfma_f32_16x16x32_bf16 v[74:77], v[34:37], v[18:21], v[0:3]
	v_mfma_f32_16x16x32_bf16 v[34:37], v[34:37], v[22:25], v[0:3]
	v_mfma_f32_16x16x32_bf16 v[78:81], v[38:41], v[10:13], v[0:3]
	v_mfma_f32_16x16x32_bf16 v[82:85], v[38:41], v[14:17], v[0:3]
	v_mfma_f32_16x16x32_bf16 v[92:95], v[38:41], v[18:21], v[0:3]
	v_mfma_f32_16x16x32_bf16 v[38:41], v[38:41], v[22:25], v[0:3]
	v_mfma_f32_16x16x32_bf16 v[112:115], v[96:99], v[10:13], v[0:3]
	v_mfma_f32_16x16x32_bf16 v[116:119], v[96:99], v[14:17], v[0:3]
	v_mfma_f32_16x16x32_bf16 v[120:123], v[96:99], v[18:21], v[0:3]
	v_mfma_f32_16x16x32_bf16 v[96:99], v[96:99], v[22:25], v[0:3]
	v_mfma_f32_16x16x32_bf16 v[124:127], v[100:103], v[10:13], v[0:3]
	v_mfma_f32_16x16x32_bf16 v[128:131], v[100:103], v[14:17], v[0:3]
	v_mfma_f32_16x16x32_bf16 v[132:135], v[100:103], v[18:21], v[0:3]
	v_mfma_f32_16x16x32_bf16 v[100:103], v[100:103], v[22:25], v[0:3]
	v_mfma_f32_16x16x32_bf16 v[136:139], v[104:107], v[10:13], v[0:3]
	v_mfma_f32_16x16x32_bf16 v[140:143], v[104:107], v[14:17], v[0:3]
	v_mfma_f32_16x16x32_bf16 v[144:147], v[104:107], v[18:21], v[0:3]
	v_mfma_f32_16x16x32_bf16 v[104:107], v[104:107], v[22:25], v[0:3]
	v_mfma_f32_16x16x32_bf16 v[10:13], v[108:111], v[10:13], v[0:3]
	v_mfma_f32_16x16x32_bf16 v[14:17], v[108:111], v[14:17], v[0:3]
	v_mfma_f32_16x16x32_bf16 v[18:21], v[108:111], v[18:21], v[0:3]
	v_mfma_f32_16x16x32_bf16 v[0:3], v[108:111], v[22:25], v[0:3]
	v_lshl_add_u64 v[22:23], v[4:5], 0, s[20:21]
	s_mov_b32 s42, m0
	s_mov_b32 m0, s15
	s_nop 0
	global_load_lds_dwordx4 v[22:23], off
	s_mov_b32 m0, s42
	v_lshl_add_u64 v[22:23], v[4:5], 0, s[22:23]
	s_mov_b32 s42, m0
	s_mov_b32 m0, s16
	s_nop 0
	global_load_lds_dwordx4 v[22:23], off
	s_mov_b32 m0, s42
	s_mov_b64 s[22:23], 0x60c0
	v_lshl_add_u64 v[22:23], v[4:5], 0, s[22:23]
	s_mov_b32 s42, m0
	s_mov_b32 m0, s17
	s_nop 0
	global_load_lds_dwordx4 v[22:23], off
	s_mov_b32 m0, s42
	v_lshl_add_u64 v[22:23], v[6:7], 0, s[20:21]
	s_mov_b32 s42, m0
	s_mov_b32 m0, s13
	s_nop 0
	global_load_lds_dwordx4 v[148:149], off
	s_mov_b32 m0, s42
	s_mov_b64 s[20:21], 0x100
	s_mov_b32 s42, m0
	s_mov_b32 m0, s18
	s_nop 0
	global_load_lds_dwordx4 v[22:23], off
	s_mov_b32 m0, s42
	ds_read_b128 v[22:25], v9 offset:24576
	ds_read_b128 v[108:111], v9 offset:25600
	ds_read_b128 v[148:151], v9 offset:26624
	ds_read_b128 v[152:155], v9 offset:27648
	ds_read_b128 v[156:159], v8 offset:40960
	ds_read_b128 v[160:163], v8 offset:41984
	ds_read_b128 v[164:167], v8 offset:43008
	ds_read_b128 v[168:171], v8 offset:44032
	s_waitcnt lgkmcnt(3)
	v_mfma_f32_16x16x32_bf16 v[42:45], v[156:159], v[22:25], v[42:45]
	v_lshl_add_u64 v[86:87], v[4:5], 0, s[20:21]
	v_lshl_add_u64 v[172:173], v[6:7], 0, s[20:21]
	s_mov_b64 s[20:21], 0x2100
	v_mfma_f32_16x16x32_bf16 v[46:49], v[156:159], v[108:111], v[46:49]
	s_mov_b64 s[22:23], 0x4100
	v_mfma_f32_16x16x32_bf16 v[50:53], v[156:159], v[148:151], v[50:53]
	v_mfma_f32_16x16x32_bf16 v[26:29], v[156:159], v[152:155], v[26:29]
	s_waitcnt lgkmcnt(2)
	v_mfma_f32_16x16x32_bf16 v[54:57], v[160:163], v[22:25], v[54:57]
	v_mfma_f32_16x16x32_bf16 v[58:61], v[160:163], v[108:111], v[58:61]
	v_mfma_f32_16x16x32_bf16 v[62:65], v[160:163], v[148:151], v[62:65]
	v_mfma_f32_16x16x32_bf16 v[30:33], v[160:163], v[152:155], v[30:33]
	s_waitcnt lgkmcnt(1)
	v_mfma_f32_16x16x32_bf16 v[66:69], v[164:167], v[22:25], v[66:69]
	v_mfma_f32_16x16x32_bf16 v[70:73], v[164:167], v[108:111], v[70:73]
	v_mfma_f32_16x16x32_bf16 v[74:77], v[164:167], v[148:151], v[74:77]
	v_mfma_f32_16x16x32_bf16 v[34:37], v[164:167], v[152:155], v[34:37]
	s_waitcnt lgkmcnt(0)
	v_mfma_f32_16x16x32_bf16 v[78:81], v[168:171], v[22:25], v[78:81]
	v_mfma_f32_16x16x32_bf16 v[82:85], v[168:171], v[108:111], v[82:85]
	v_mfma_f32_16x16x32_bf16 v[92:95], v[168:171], v[148:151], v[92:95]
	v_mfma_f32_16x16x32_bf16 v[38:41], v[168:171], v[152:155], v[38:41]
	ds_read_b128 v[156:159], v8 offset:45056
	ds_read_b128 v[160:163], v8 offset:46080
	ds_read_b128 v[164:167], v8 offset:47104
	ds_read_b128 v[168:171], v8 offset:48128
	s_waitcnt vmcnt(6)
	s_waitcnt lgkmcnt(0)
	s_barrier
; template <int N> DI void wait_vm() { asm volatile("s_waitcnt vmcnt(%0)" ::"n"(N) : "memory"); }
; template <int BM, class Epi>
; DI void gemm_dma(const u16* __restrict__ X, long ldx, const u16* __restrict__ W, long ldw, int K, char* smem,
;                  int m0, int n0, const Epi& epi) {
;     ...
;   do {
;     if (kt + D - 2 < nk) wait_vm<PW * (D - 2)>(); else wait_vm<0>();
;     __syncthreads();
;     if (kt + D - 1 < nk) GD_ISSUE(nxt)
;     nxt = (nxt + 1 == D) ? 0 : nxt + 1;
;     const char* base = smem + cur * STG;
;     cur = (cur + 1 == D) ? 0 : cur + 1;
;     bf16x8 xf[MT];
; #pragma unroll
;     for (int i = 0; i < MT; ++i) xf[i] = *(const bf16x8*)(base + (xrow0 + i * 16) * 64 + rd);
; #pragma unroll
;     for (int nh = 0; nh < NT / 4; ++nh) {
;       bf16x8 wf[4];
; #pragma unroll
;       for (int i = 0; i < 4; ++i) wf[i] = *(const bf16x8*)(base + BM * 64 + (wrow0 + (nh * 4 + i) * 16) * 64 + rd);
; #pragma unroll
;       for (int i = 0; i < 4; ++i)
; #pragma unroll
;         for (int mt = 0; mt < MT; ++mt)
;           acc[nh * 4 + i][mt] = __builtin_amdgcn_mfma_f32_16x16x32_bf16(wf[i], xf[mt], acc[nh * 4 + i][mt], 0, 0, 0);
	s_mov_b32 s42, m0
	s_mov_b32 m0, s7
	s_nop 0
	global_load_lds_dwordx4 v[86:87], off
	s_mov_b32 m0, s42
	v_mfma_f32_16x16x32_bf16 v[112:115], v[156:159], v[22:25], v[112:115]
	v_mfma_f32_16x16x32_bf16 v[124:127], v[160:163], v[22:25], v[124:127]
	v_mfma_f32_16x16x32_bf16 v[136:139], v[164:167], v[22:25], v[136:139]
	v_mfma_f32_16x16x32_bf16 v[10:13], v[168:171], v[22:25], v[10:13]
	v_lshl_add_u64 v[22:23], v[4:5], 0, s[20:21]
	s_mov_b32 s42, m0
	s_mov_b32 m0, s8
	s_nop 0
	global_load_lds_dwordx4 v[22:23], off
	s_mov_b32 m0, s42
	v_lshl_add_u64 v[22:23], v[4:5], 0, s[22:23]
	s_mov_b32 s42, m0
	s_mov_b32 m0, s9
	s_nop 0
	global_load_lds_dwordx4 v[22:23], off
	s_mov_b32 m0, s42
	s_mov_b64 s[22:23], 0x6100
	v_lshl_add_u64 v[22:23], v[4:5], 0, s[22:23]
	s_mov_b32 s42, m0
	s_mov_b32 m0, s10
	s_nop 0
	global_load_lds_dwordx4 v[22:23], off
	s_mov_b32 m0, s42
	v_lshl_add_u64 v[22:23], v[6:7], 0, s[20:21]
	s_mov_b32 s42, m0
	s_mov_b32 m0, s11
	s_nop 0
	global_load_lds_dwordx4 v[172:173], off
	s_mov_b32 m0, s42
	v_mfma_f32_16x16x32_bf16 v[116:119], v[156:159], v[108:111], v[116:119]
	s_mov_b32 s42, m0
	s_mov_b32 m0, s12
	s_nop 0
	global_load_lds_dwordx4 v[22:23], off
	s_mov_b32 m0, s42
	s_mov_b64 s[20:21], 0x140
	v_lshl_add_u64 v[86:87], v[4:5], 0, s[20:21]
	v_mfma_f32_16x16x32_bf16 v[120:123], v[156:159], v[148:151], v[120:123]
	v_lshl_add_u64 v[172:173], v[6:7], 0, s[20:21]
	s_mov_b64 s[20:21], 0x2140
	s_mov_b64 s[22:23], 0x4140
	v_mfma_f32_16x16x32_bf16 v[96:99], v[156:159], v[152:155], v[96:99]
	v_mfma_f32_16x16x32_bf16 v[128:131], v[160:163], v[108:111], v[128:131]
	v_mfma_f32_16x16x32_bf16 v[132:135], v[160:163], v[148:151], v[132:135]
	v_mfma_f32_16x16x32_bf16 v[100:103], v[160:163], v[152:155], v[100:103]
	v_mfma_f32_16x16x32_bf16 v[140:143], v[164:167], v[108:111], v[140:143]
	v_mfma_f32_16x16x32_bf16 v[144:147], v[164:167], v[148:151], v[144:147]
	v_mfma_f32_16x16x32_bf16 v[104:107], v[164:167], v[152:155], v[104:107]
	v_mfma_f32_16x16x32_bf16 v[14:17], v[168:171], v[108:111], v[14:17]
	v_mfma_f32_16x16x32_bf16 v[18:21], v[168:171], v[148:151], v[18:21]
	v_mfma_f32_16x16x32_bf16 v[0:3], v[168:171], v[152:155], v[0:3]
	ds_read_b128 v[22:25], v9 offset:49152
	ds_read_b128 v[108:111], v9 offset:50176
	ds_read_b128 v[148:151], v9 offset:51200
	ds_read_b128 v[152:155], v9 offset:52224
	ds_read_b128 v[156:159], v91
	ds_read_b128 v[160:163], v174
	ds_read_b128 v[164:167], v175
	ds_read_b128 v[168:171], v176
	s_waitcnt lgkmcnt(3)
	v_mfma_f32_16x16x32_bf16 v[42:45], v[156:159], v[22:25], v[42:45]
	v_mfma_f32_16x16x32_bf16 v[46:49], v[156:159], v[108:111], v[46:49]
	v_mfma_f32_16x16x32_bf16 v[50:53], v[156:159], v[148:151], v[50:53]
	v_mfma_f32_16x16x32_bf16 v[26:29], v[156:159], v[152:155], v[26:29]
	ds_read_b128 v[156:159], v177
	s_waitcnt lgkmcnt(3)
	v_mfma_f32_16x16x32_bf16 v[54:57], v[160:163], v[22:25], v[54:57]
	v_mfma_f32_16x16x32_bf16 v[58:61], v[160:163], v[108:111], v[58:61]
	v_mfma_f32_16x16x32_bf16 v[62:65], v[160:163], v[148:151], v[62:65]
	v_mfma_f32_16x16x32_bf16 v[30:33], v[160:163], v[152:155], v[30:33]
	ds_read_b128 v[160:163], v178
	s_waitcnt lgkmcnt(3)
	v_mfma_f32_16x16x32_bf16 v[66:69], v[164:167], v[22:25], v[66:69]
	v_mfma_f32_16x16x32_bf16 v[70:73], v[164:167], v[108:111], v[70:73]
	v_mfma_f32_16x16x32_bf16 v[74:77], v[164:167], v[148:151], v[74:77]
	v_mfma_f32_16x16x32_bf16 v[34:37], v[164:167], v[152:155], v[34:37]
	ds_read_b128 v[164:167], v179
	s_waitcnt lgkmcnt(3)
	v_mfma_f32_16x16x32_bf16 v[78:81], v[168:171], v[22:25], v[78:81]
	v_mfma_f32_16x16x32_bf16 v[82:85], v[168:171], v[108:111], v[82:85]
	v_mfma_f32_16x16x32_bf16 v[92:95], v[168:171], v[148:151], v[92:95]
	v_mfma_f32_16x16x32_bf16 v[38:41], v[168:171], v[152:155], v[38:41]
	ds_read_b128 v[168:171], v180
	s_waitcnt vmcnt(6)
	s_waitcnt lgkmcnt(0)
	s_barrier
	s_mov_b32 s42, m0
	s_mov_b32 m0, s19
	s_nop 0
	global_load_lds_dwordx4 v[86:87], off
	s_mov_b32 m0, s42
	v_mfma_f32_16x16x32_bf16 v[112:115], v[156:159], v[22:25], v[112:115]
	v_mfma_f32_16x16x32_bf16 v[124:127], v[160:163], v[22:25], v[124:127]
	v_mfma_f32_16x16x32_bf16 v[136:139], v[164:167], v[22:25], v[136:139]
	v_mfma_f32_16x16x32_bf16 v[10:13], v[168:171], v[22:25], v[10:13]
	v_lshl_add_u64 v[22:23], v[4:5], 0, s[20:21]
	s_mov_b32 s19, m0
	s_mov_b32 m0, s34
	s_nop 0
	global_load_lds_dwordx4 v[22:23], off
	s_mov_b32 m0, s19
	v_lshl_add_u64 v[22:23], v[4:5], 0, s[22:23]
	s_mov_b32 s19, m0
	s_mov_b32 m0, s38
	s_nop 0
	global_load_lds_dwordx4 v[22:23], off
	s_mov_b32 m0, s19
	s_mov_b64 s[22:23], 0x6140
	v_lshl_add_u64 v[22:23], v[4:5], 0, s[22:23]
	s_mov_b32 s19, m0
	s_mov_b32 m0, s39
	s_nop 0
	global_load_lds_dwordx4 v[22:23], off
	s_mov_b32 m0, s19
	v_lshl_add_u64 v[22:23], v[6:7], 0, s[20:21]
	s_mov_b32 s19, m0
	s_mov_b32 m0, s40
	s_nop 0
	global_load_lds_dwordx4 v[172:173], off
	s_mov_b32 m0, s19
	v_mfma_f32_16x16x32_bf16 v[116:119], v[156:159], v[108:111], v[116:119]
	s_mov_b32 s19, m0
	s_mov_b32 m0, s41
	s_nop 0
	global_load_lds_dwordx4 v[22:23], off
	s_mov_b32 m0, s19
	s_mov_b64 s[20:21], 0x180
	v_lshl_add_u64 v[86:87], v[4:5], 0, s[20:21]
	v_mfma_f32_16x16x32_bf16 v[120:123], v[156:159], v[148:151], v[120:123]
	v_lshl_add_u64 v[172:173], v[6:7], 0, s[20:21]
	s_mov_b64 s[20:21], 0x2180
	s_mov_b64 s[38:39], 0
	v_mfma_f32_16x16x32_bf16 v[96:99], v[156:159], v[152:155], v[96:99]
	v_mfma_f32_16x16x32_bf16 v[128:131], v[160:163], v[108:111], v[128:131]
	v_mfma_f32_16x16x32_bf16 v[132:135], v[160:163], v[148:151], v[132:135]
	v_mfma_f32_16x16x32_bf16 v[100:103], v[160:163], v[152:155], v[100:103]
	v_mfma_f32_16x16x32_bf16 v[140:143], v[164:167], v[108:111], v[140:143]
	v_mfma_f32_16x16x32_bf16 v[144:147], v[164:167], v[148:151], v[144:147]
	v_mfma_f32_16x16x32_bf16 v[104:107], v[164:167], v[152:155], v[104:107]
	v_mfma_f32_16x16x32_bf16 v[14:17], v[168:171], v[108:111], v[14:17]
	v_mfma_f32_16x16x32_bf16 v[18:21], v[168:171], v[148:151], v[18:21]
	v_mfma_f32_16x16x32_bf16 v[0:3], v[168:171], v[152:155], v[0:3]
	ds_read_b128 v[22:25], v9
	ds_read_b128 v[108:111], v9 offset:1024
	ds_read_b128 v[148:151], v9 offset:2048
	ds_read_b128 v[152:155], v9 offset:3072
	ds_read_b128 v[156:159], v8 offset:16384
	ds_read_b128 v[160:163], v8 offset:17408
	ds_read_b128 v[164:167], v8 offset:18432
	ds_read_b128 v[168:171], v8 offset:19456
	s_waitcnt lgkmcnt(3)
; template <int N> DI void wait_vm() { asm volatile("s_waitcnt vmcnt(%0)" ::"n"(N) : "memory"); }
; template <int BM, class Epi>
; DI void gemm_dma(const u16* __restrict__ X, long ldx, const u16* __restrict__ W, long ldw, int K, char* smem,
;                  int m0, int n0, const Epi& epi) {
;     ...
;   do {
;     if (kt + D - 2 < nk) wait_vm<PW * (D - 2)>(); else wait_vm<0>();
;     __syncthreads();
;     if (kt + D - 1 < nk) GD_ISSUE(nxt)
;     nxt = (nxt + 1 == D) ? 0 : nxt + 1;
;     const char* base = smem + cur * STG;
;     cur = (cur + 1 == D) ? 0 : cur + 1;
;     bf16x8 xf[MT];
; #pragma unroll
;     for (int i = 0; i < MT; ++i) xf[i] = *(const bf16x8*)(base + (xrow0 + i * 16) * 64 + rd);
; #pragma unroll
;     for (int nh = 0; nh < NT / 4; ++nh) {
;       bf16x8 wf[4];
; #pragma unroll
;       for (int i = 0; i < 4; ++i) wf[i] = *(const bf16x8*)(base + BM * 64 + (wrow0 + (nh * 4 + i) * 16) * 64 + rd);
; #pragma unroll
;       for (int i = 0; i < 4; ++i)
; #pragma unroll
;         for (int mt = 0; mt < MT; ++mt)
;           acc[nh * 4 + i][mt] = __builtin_amdgcn_mfma_f32_16x16x32_bf16(wf[i], xf[mt], acc[nh * 4 + i][mt], 0, 0, 0);
	v_mfma_f32_16x16x32_bf16 v[42:45], v[156:159], v[22:25], v[42:45]
	v_mfma_f32_16x16x32_bf16 v[46:49], v[156:159], v[108:111], v[46:49]
	v_mfma_f32_16x16x32_bf16 v[50:53], v[156:159], v[148:151], v[50:53]
	v_mfma_f32_16x16x32_bf16 v[26:29], v[156:159], v[152:155], v[26:29]
	s_waitcnt lgkmcnt(2)
	v_mfma_f32_16x16x32_bf16 v[54:57], v[160:163], v[22:25], v[54:57]
	v_mfma_f32_16x16x32_bf16 v[58:61], v[160:163], v[108:111], v[58:61]
	v_mfma_f32_16x16x32_bf16 v[62:65], v[160:163], v[148:151], v[62:65]
	v_mfma_f32_16x16x32_bf16 v[30:33], v[160:163], v[152:155], v[30:33]
	s_waitcnt lgkmcnt(1)
	v_mfma_f32_16x16x32_bf16 v[66:69], v[164:167], v[22:25], v[66:69]
	v_mfma_f32_16x16x32_bf16 v[70:73], v[164:167], v[108:111], v[70:73]
	v_mfma_f32_16x16x32_bf16 v[74:77], v[164:167], v[148:151], v[74:77]
	v_mfma_f32_16x16x32_bf16 v[34:37], v[164:167], v[152:155], v[34:37]
	s_waitcnt lgkmcnt(0)
	v_mfma_f32_16x16x32_bf16 v[78:81], v[168:171], v[22:25], v[78:81]
	v_mfma_f32_16x16x32_bf16 v[82:85], v[168:171], v[108:111], v[82:85]
	v_mfma_f32_16x16x32_bf16 v[92:95], v[168:171], v[148:151], v[92:95]
	v_mfma_f32_16x16x32_bf16 v[38:41], v[168:171], v[152:155], v[38:41]
	ds_read_b128 v[156:159], v8 offset:20480
	ds_read_b128 v[160:163], v8 offset:21504
	ds_read_b128 v[164:167], v8 offset:22528
	ds_read_b128 v[168:171], v8 offset:23552
	s_waitcnt vmcnt(6)
	s_waitcnt lgkmcnt(0)
	s_barrier
	s_mov_b32 s19, m0
	s_mov_b32 m0, s14
	s_nop 0
	global_load_lds_dwordx4 v[86:87], off
	s_mov_b32 m0, s19
	v_mfma_f32_16x16x32_bf16 v[112:115], v[156:159], v[22:25], v[112:115]
	v_mfma_f32_16x16x32_bf16 v[124:127], v[160:163], v[22:25], v[124:127]
	v_mfma_f32_16x16x32_bf16 v[136:139], v[164:167], v[22:25], v[136:139]
	v_mfma_f32_16x16x32_bf16 v[10:13], v[168:171], v[22:25], v[10:13]
	v_lshl_add_u64 v[22:23], v[4:5], 0, s[20:21]
	s_mov_b32 s14, m0
	s_mov_b32 m0, s15
	s_nop 0
	global_load_lds_dwordx4 v[22:23], off
	s_mov_b32 m0, s14
	s_mov_b64 s[14:15], 0x4180
	v_lshl_add_u64 v[22:23], v[4:5], 0, s[14:15]
	s_mov_b32 s14, m0
	s_mov_b32 m0, s16
	s_nop 0
	global_load_lds_dwordx4 v[22:23], off
	s_mov_b32 m0, s14
	s_mov_b64 s[14:15], 0x6180
	v_lshl_add_u64 v[22:23], v[4:5], 0, s[14:15]
	s_mov_b32 s14, m0
	s_mov_b32 m0, s17
	s_nop 0
	global_load_lds_dwordx4 v[22:23], off
	s_mov_b32 m0, s14
	v_lshl_add_u64 v[22:23], v[6:7], 0, s[20:21]
	s_mov_b32 s14, m0
	s_mov_b32 m0, s13
	s_nop 0
	global_load_lds_dwordx4 v[172:173], off
	s_mov_b32 m0, s14
	s_mov_b32 s13, m0
	s_mov_b32 m0, s18
	s_nop 0
	global_load_lds_dwordx4 v[22:23], off
	s_mov_b32 m0, s13
	v_mfma_f32_16x16x32_bf16 v[116:119], v[156:159], v[108:111], v[116:119]
	s_mov_b64 s[14:15], 0x1c0
	v_lshl_add_u64 v[86:87], v[4:5], 0, s[14:15]
	v_lshl_add_u64 v[172:173], v[6:7], 0, s[14:15]
	v_mfma_f32_16x16x32_bf16 v[120:123], v[156:159], v[148:151], v[120:123]
	s_mov_b64 s[14:15], 0x21c0
	s_mov_b64 s[16:17], 0x41c0
	v_mfma_f32_16x16x32_bf16 v[96:99], v[156:159], v[152:155], v[96:99]
	v_mfma_f32_16x16x32_bf16 v[128:131], v[160:163], v[108:111], v[128:131]
	v_mfma_f32_16x16x32_bf16 v[132:135], v[160:163], v[148:151], v[132:135]
	v_mfma_f32_16x16x32_bf16 v[100:103], v[160:163], v[152:155], v[100:103]
	v_mfma_f32_16x16x32_bf16 v[140:143], v[164:167], v[108:111], v[140:143]
	v_mfma_f32_16x16x32_bf16 v[144:147], v[164:167], v[148:151], v[144:147]
	v_mfma_f32_16x16x32_bf16 v[104:107], v[164:167], v[152:155], v[104:107]
	v_mfma_f32_16x16x32_bf16 v[14:17], v[168:171], v[108:111], v[14:17]
	v_mfma_f32_16x16x32_bf16 v[18:21], v[168:171], v[148:151], v[18:21]
	v_mfma_f32_16x16x32_bf16 v[0:3], v[168:171], v[152:155], v[0:3]
	ds_read_b128 v[22:25], v9 offset:24576
	ds_read_b128 v[108:111], v9 offset:25600
	ds_read_b128 v[148:151], v9 offset:26624
	ds_read_b128 v[152:155], v9 offset:27648
	ds_read_b128 v[156:159], v8 offset:40960
	ds_read_b128 v[160:163], v8 offset:41984
	ds_read_b128 v[164:167], v8 offset:43008
	ds_read_b128 v[168:171], v8 offset:44032
	s_waitcnt lgkmcnt(3)
	v_mfma_f32_16x16x32_bf16 v[42:45], v[156:159], v[22:25], v[42:45]
	v_mfma_f32_16x16x32_bf16 v[46:49], v[156:159], v[108:111], v[46:49]
	v_mfma_f32_16x16x32_bf16 v[50:53], v[156:159], v[148:151], v[50:53]
	v_mfma_f32_16x16x32_bf16 v[26:29], v[156:159], v[152:155], v[26:29]
	s_waitcnt lgkmcnt(2)
	v_mfma_f32_16x16x32_bf16 v[54:57], v[160:163], v[22:25], v[54:57]
	v_mfma_f32_16x16x32_bf16 v[58:61], v[160:163], v[108:111], v[58:61]
	v_mfma_f32_16x16x32_bf16 v[62:65], v[160:163], v[148:151], v[62:65]
	v_mfma_f32_16x16x32_bf16 v[30:33], v[160:163], v[152:155], v[30:33]
	s_waitcnt lgkmcnt(1)
	v_mfma_f32_16x16x32_bf16 v[66:69], v[164:167], v[22:25], v[66:69]
	v_mfma_f32_16x16x32_bf16 v[70:73], v[164:167], v[108:111], v[70:73]
	v_mfma_f32_16x16x32_bf16 v[74:77], v[164:167], v[148:151], v[74:77]
	v_mfma_f32_16x16x32_bf16 v[34:37], v[164:167], v[152:155], v[34:37]
	s_waitcnt lgkmcnt(0)
	v_mfma_f32_16x16x32_bf16 v[78:81], v[168:171], v[22:25], v[78:81]
	v_mfma_f32_16x16x32_bf16 v[82:85], v[168:171], v[108:111], v[82:85]
	v_mfma_f32_16x16x32_bf16 v[92:95], v[168:171], v[148:151], v[92:95]
	v_mfma_f32_16x16x32_bf16 v[38:41], v[168:171], v[152:155], v[38:41]
	ds_read_b128 v[156:159], v8 offset:45056
	ds_read_b128 v[160:163], v8 offset:46080
	ds_read_b128 v[164:167], v8 offset:47104
	ds_read_b128 v[168:171], v8 offset:48128
	s_waitcnt vmcnt(6)
	s_waitcnt lgkmcnt(0)
	s_barrier
; template <int N> DI void wait_vm() { asm volatile("s_waitcnt vmcnt(%0)" ::"n"(N) : "memory"); }
; template <int BM, class Epi>
; DI void gemm_dma(const u16* __restrict__ X, long ldx, const u16* __restrict__ W, long ldw, int K, char* smem,
;                  int m0, int n0, const Epi& epi) {
;     ...
;   do {
;     if (kt + D - 2 < nk) wait_vm<PW * (D - 2)>(); else wait_vm<0>();
;     __syncthreads();
;     if (kt + D - 1 < nk) GD_ISSUE(nxt)
;     nxt = (nxt + 1 == D) ? 0 : nxt + 1;
;     const char* base = smem + cur * STG;
;     cur = (cur + 1 == D) ? 0 : cur + 1;
;     bf16x8 xf[MT];
; #pragma unroll
;     for (int i = 0; i < MT; ++i) xf[i] = *(const bf16x8*)(base + (xrow0 + i * 16) * 64 + rd);
; #pragma unroll
;     for (int nh = 0; nh < NT / 4; ++nh) {
;       bf16x8 wf[4];
; #pragma unroll
;       for (int i = 0; i < 4; ++i) wf[i] = *(const bf16x8*)(base + BM * 64 + (wrow0 + (nh * 4 + i) * 16) * 64 + rd);
; #pragma unroll
;       for (int i = 0; i < 4; ++i)
; #pragma unroll
;         for (int mt = 0; mt < MT; ++mt)
;           acc[nh * 4 + i][mt] = __builtin_amdgcn_mfma_f32_16x16x32_bf16(wf[i], xf[mt], acc[nh * 4 + i][mt], 0, 0, 0);
;     }
;   } while (++kt < nk);
	s_mov_b32 s13, m0
	s_mov_b32 m0, s7
	s_nop 0
	global_load_lds_dwordx4 v[86:87], off
	s_mov_b32 m0, s13
	v_mfma_f32_16x16x32_bf16 v[112:115], v[156:159], v[22:25], v[112:115]
	v_mfma_f32_16x16x32_bf16 v[124:127], v[160:163], v[22:25], v[124:127]
	v_mfma_f32_16x16x32_bf16 v[136:139], v[164:167], v[22:25], v[136:139]
	v_mfma_f32_16x16x32_bf16 v[10:13], v[168:171], v[22:25], v[10:13]
	v_lshl_add_u64 v[22:23], v[4:5], 0, s[14:15]
	s_mov_b32 s7, m0
	s_mov_b32 m0, s8
	s_nop 0
	global_load_lds_dwordx4 v[22:23], off
	s_mov_b32 m0, s7
	v_lshl_add_u64 v[22:23], v[4:5], 0, s[16:17]
	s_mov_b32 s7, m0
	s_mov_b32 m0, s9
	s_nop 0
	global_load_lds_dwordx4 v[22:23], off
	s_mov_b32 m0, s7
	s_mov_b64 s[8:9], 0x61c0
	v_lshl_add_u64 v[4:5], v[4:5], 0, s[8:9]
	s_mov_b32 s7, m0
	s_mov_b32 m0, s10
	s_nop 0
	global_load_lds_dwordx4 v[4:5], off
	s_mov_b32 m0, s7
	v_lshl_add_u64 v[4:5], v[6:7], 0, s[14:15]
	s_mov_b32 s7, m0
	s_mov_b32 m0, s11
	s_nop 0
	global_load_lds_dwordx4 v[172:173], off
	s_mov_b32 m0, s7
	v_mfma_f32_16x16x32_bf16 v[116:119], v[156:159], v[108:111], v[116:119]
	s_mov_b32 s7, m0
	s_mov_b32 m0, s12
	s_nop 0
	global_load_lds_dwordx4 v[4:5], off
	s_mov_b32 m0, s7
	v_mfma_f32_16x16x32_bf16 v[120:123], v[156:159], v[148:151], v[120:123]
	v_mfma_f32_16x16x32_bf16 v[96:99], v[156:159], v[152:155], v[96:99]
	v_mfma_f32_16x16x32_bf16 v[128:131], v[160:163], v[108:111], v[128:131]
	v_mfma_f32_16x16x32_bf16 v[132:135], v[160:163], v[148:151], v[132:135]
	v_mfma_f32_16x16x32_bf16 v[100:103], v[160:163], v[152:155], v[100:103]
	v_mfma_f32_16x16x32_bf16 v[140:143], v[164:167], v[108:111], v[140:143]
	v_mfma_f32_16x16x32_bf16 v[144:147], v[164:167], v[148:151], v[144:147]
	v_mfma_f32_16x16x32_bf16 v[104:107], v[164:167], v[152:155], v[104:107]
	v_mfma_f32_16x16x32_bf16 v[14:17], v[168:171], v[108:111], v[14:17]
	v_mfma_f32_16x16x32_bf16 v[18:21], v[168:171], v[148:151], v[18:21]
	v_mfma_f32_16x16x32_bf16 v[0:3], v[168:171], v[152:155], v[0:3]
	ds_read_b128 v[4:7], v9 offset:49152
	ds_read_b128 v[22:25], v9 offset:50176
	ds_read_b128 v[108:111], v9 offset:51200
	ds_read_b128 v[148:151], v9 offset:52224
	ds_read_b128 v[152:155], v91
	ds_read_b128 v[156:159], v174
	ds_read_b128 v[160:163], v175
	ds_read_b128 v[164:167], v176
	s_waitcnt lgkmcnt(3)
	v_mfma_f32_16x16x32_bf16 v[42:45], v[152:155], v[4:7], v[42:45]
	v_mfma_f32_16x16x32_bf16 v[46:49], v[152:155], v[22:25], v[46:49]
	v_mfma_f32_16x16x32_bf16 v[50:53], v[152:155], v[108:111], v[50:53]
	v_mfma_f32_16x16x32_bf16 v[26:29], v[152:155], v[148:151], v[26:29]
	s_waitcnt lgkmcnt(2)
	v_mfma_f32_16x16x32_bf16 v[54:57], v[156:159], v[4:7], v[54:57]
	v_mfma_f32_16x16x32_bf16 v[58:61], v[156:159], v[22:25], v[58:61]
	v_mfma_f32_16x16x32_bf16 v[62:65], v[156:159], v[108:111], v[62:65]
	v_mfma_f32_16x16x32_bf16 v[30:33], v[156:159], v[148:151], v[30:33]
	s_waitcnt lgkmcnt(1)
	v_mfma_f32_16x16x32_bf16 v[66:69], v[160:163], v[4:7], v[66:69]
	v_mfma_f32_16x16x32_bf16 v[70:73], v[160:163], v[22:25], v[70:73]
	v_mfma_f32_16x16x32_bf16 v[74:77], v[160:163], v[108:111], v[74:77]
	v_mfma_f32_16x16x32_bf16 v[34:37], v[160:163], v[148:151], v[34:37]
	s_waitcnt lgkmcnt(0)
	v_mfma_f32_16x16x32_bf16 v[78:81], v[164:167], v[4:7], v[78:81]
	v_mfma_f32_16x16x32_bf16 v[82:85], v[164:167], v[22:25], v[82:85]
	v_mfma_f32_16x16x32_bf16 v[92:95], v[164:167], v[108:111], v[92:95]
	v_mfma_f32_16x16x32_bf16 v[38:41], v[164:167], v[148:151], v[38:41]
	ds_read_b128 v[152:155], v177
	ds_read_b128 v[156:159], v178
	ds_read_b128 v[160:163], v179
	ds_read_b128 v[164:167], v180
	s_waitcnt vmcnt(6)
	s_waitcnt lgkmcnt(0)
	v_mfma_f32_16x16x32_bf16 v[112:115], v[152:155], v[4:7], v[112:115]
	s_barrier
	v_mfma_f32_16x16x32_bf16 v[116:119], v[152:155], v[22:25], v[116:119]
	v_mfma_f32_16x16x32_bf16 v[120:123], v[152:155], v[108:111], v[120:123]
	v_mfma_f32_16x16x32_bf16 v[96:99], v[152:155], v[148:151], v[96:99]
	v_mfma_f32_16x16x32_bf16 v[124:127], v[156:159], v[4:7], v[124:127]
	v_mfma_f32_16x16x32_bf16 v[128:131], v[156:159], v[22:25], v[128:131]
	v_mfma_f32_16x16x32_bf16 v[132:135], v[156:159], v[108:111], v[132:135]
	v_mfma_f32_16x16x32_bf16 v[100:103], v[156:159], v[148:151], v[100:103]
	v_mfma_f32_16x16x32_bf16 v[136:139], v[160:163], v[4:7], v[136:139]
	v_mfma_f32_16x16x32_bf16 v[140:143], v[160:163], v[22:25], v[140:143]
	v_mfma_f32_16x16x32_bf16 v[144:147], v[160:163], v[108:111], v[144:147]
	v_mfma_f32_16x16x32_bf16 v[104:107], v[160:163], v[148:151], v[104:107]
	v_mfma_f32_16x16x32_bf16 v[4:7], v[164:167], v[4:7], v[10:13]
	v_mfma_f32_16x16x32_bf16 v[10:13], v[164:167], v[22:25], v[14:17]
	v_mfma_f32_16x16x32_bf16 v[14:17], v[164:167], v[108:111], v[18:21]
	v_mfma_f32_16x16x32_bf16 v[0:3], v[164:167], v[148:151], v[0:3]
	s_nop 1
	ds_read_b128 v[18:21], v8 offset:23552
	ds_read_b128 v[22:25], v8 offset:22528
	ds_read_b128 v[108:111], v8 offset:21504
	ds_read_b128 v[148:151], v8 offset:20480
	ds_read_b128 v[152:155], v8 offset:19456
	ds_read_b128 v[156:159], v8 offset:18432
	ds_read_b128 v[160:163], v8 offset:17408
	ds_read_b128 v[164:167], v8 offset:16384
	ds_read_b128 v[168:171], v9 offset:3072
	ds_read_b128 v[172:175], v9 offset:2048
	ds_read_b128 v[176:179], v9 offset:1024
	ds_read_b128 v[186:189], v9
	s_waitcnt vmcnt(0)
	s_waitcnt lgkmcnt(0)
	v_mfma_f32_16x16x32_bf16 v[42:45], v[164:167], v[186:189], v[42:45]
	s_barrier
; DI void st_bf4(u16* p, float a, float b, float c, float d) { *(uint2*)p = make_uint2(pk2(a, b), pk2(c, d)); }
; template <int BM, class Epi>
; DI void gemm_dma(const u16* __restrict__ X, long ldx, const u16* __restrict__ W, long ldw, int K, char* smem,
;                  int m0, int n0, const Epi& epi) {
;     ...
;     for (int i = 0; i < MT; ++i) xf[i] = *(const bf16x8*)(base + (xrow0 + i * 16) * 64 + rd);
; #pragma unroll
;     for (int nh = 0; nh < NT / 4; ++nh) {
;       bf16x8 wf[4];
; #pragma unroll
;       for (int i = 0; i < 4; ++i) wf[i] = *(const bf16x8*)(base + BM * 64 + (wrow0 + (nh * 4 + i) * 16) * 64 + rd);
; #pragma unroll
;       for (int i = 0; i < 4; ++i)
; #pragma unroll
;         for (int mt = 0; mt < MT; ++mt)
;           acc[nh * 4 + i][mt] = __builtin_amdgcn_mfma_f32_16x16x32_bf16(wf[i], xf[mt], acc[nh * 4 + i][mt], 0, 0, 0);
;     }
;   } while (++kt < nk);
;   template <int NT, int MT> DI void run(f32x4 (&acc)[NT][MT], int mb, int nb) const {
; #pragma unroll
;     for (int nt = 0; nt < NT; ++nt)
; #pragma unroll
;       for (int mt = 0; mt < MT; ++mt) {
;         f32x4 v = acc[nt][mt];
;         st_bf4(C + (size_t)(mb + mt * 16) * ldc + nb + nt * 16, v[0], v[1], v[2], v[3]);
;       }
	v_mfma_f32_16x16x32_bf16 v[46:49], v[164:167], v[176:179], v[46:49]
	v_mfma_f32_16x16x32_bf16 v[50:53], v[164:167], v[172:175], v[50:53]
	v_mfma_f32_16x16x32_bf16 v[26:29], v[164:167], v[168:171], v[26:29]
	v_mfma_f32_16x16x32_bf16 v[54:57], v[160:163], v[186:189], v[54:57]
	v_mfma_f32_16x16x32_bf16 v[58:61], v[160:163], v[176:179], v[58:61]
	v_mfma_f32_16x16x32_bf16 v[62:65], v[160:163], v[172:175], v[62:65]
	v_mfma_f32_16x16x32_bf16 v[30:33], v[160:163], v[168:171], v[30:33]
	v_mfma_f32_16x16x32_bf16 v[66:69], v[156:159], v[186:189], v[66:69]
	v_mfma_f32_16x16x32_bf16 v[70:73], v[156:159], v[176:179], v[70:73]
	v_mfma_f32_16x16x32_bf16 v[74:77], v[156:159], v[172:175], v[74:77]
	v_mfma_f32_16x16x32_bf16 v[34:37], v[156:159], v[168:171], v[34:37]
	v_mfma_f32_16x16x32_bf16 v[156:159], v[152:155], v[186:189], v[78:81]
	v_mfma_f32_16x16x32_bf16 v[84:87], v[152:155], v[176:179], v[82:85]
	v_mfma_f32_16x16x32_bf16 v[92:95], v[152:155], v[172:175], v[92:95]
	v_mfma_f32_16x16x32_bf16 v[152:155], v[152:155], v[168:171], v[38:41]
	v_mfma_f32_16x16x32_bf16 v[112:115], v[148:151], v[186:189], v[112:115]
	v_mfma_f32_16x16x32_bf16 v[116:119], v[148:151], v[176:179], v[116:119]
	v_mfma_f32_16x16x32_bf16 v[120:123], v[148:151], v[172:175], v[120:123]
	v_mfma_f32_16x16x32_bf16 v[96:99], v[148:151], v[168:171], v[96:99]
	v_mfma_f32_16x16x32_bf16 v[124:127], v[108:111], v[186:189], v[124:127]
	v_mfma_f32_16x16x32_bf16 v[128:131], v[108:111], v[176:179], v[128:131]
	v_mfma_f32_16x16x32_bf16 v[132:135], v[108:111], v[172:175], v[132:135]
	v_mfma_f32_16x16x32_bf16 v[100:103], v[108:111], v[168:171], v[100:103]
	v_mfma_f32_16x16x32_bf16 v[108:111], v[22:25], v[186:189], v[136:139]
	v_mfma_f32_16x16x32_bf16 v[136:139], v[22:25], v[176:179], v[140:143]
	v_mfma_f32_16x16x32_bf16 v[140:143], v[22:25], v[172:175], v[144:147]
	v_mfma_f32_16x16x32_bf16 v[104:107], v[22:25], v[168:171], v[104:107]
	v_mfma_f32_16x16x32_bf16 v[4:7], v[18:21], v[186:189], v[4:7]
	v_mfma_f32_16x16x32_bf16 v[144:147], v[18:21], v[176:179], v[10:13]
	v_mfma_f32_16x16x32_bf16 v[148:151], v[18:21], v[172:175], v[14:17]
	v_mfma_f32_16x16x32_bf16 v[0:3], v[18:21], v[168:171], v[0:3]
	s_nop 0
	ds_read_b128 v[10:13], v9 offset:24576
	ds_read_b128 v[160:163], v9 offset:25600
	ds_read_b128 v[164:167], v9 offset:26624
	ds_read_b128 v[168:171], v9 offset:27648
	ds_read_b128 v[14:17], v8 offset:40960
	ds_read_b128 v[18:21], v8 offset:41984
	ds_read_b128 v[22:25], v8 offset:43008
	ds_read_b128 v[172:175], v8 offset:44032
	s_waitcnt lgkmcnt(3)
	v_mfma_f32_16x16x32_bf16 v[176:179], v[14:17], v[10:13], v[42:45]
	v_mfma_f32_16x16x32_bf16 v[186:189], v[14:17], v[160:163], v[46:49]
	v_mfma_f32_16x16x32_bf16 v[190:193], v[14:17], v[164:167], v[50:53]
	v_mfma_f32_16x16x32_bf16 v[194:197], v[14:17], v[168:171], v[26:29]
	s_waitcnt lgkmcnt(2)
	v_mfma_f32_16x16x32_bf16 v[224:227], v[18:21], v[10:13], v[54:57]
	v_mfma_f32_16x16x32_bf16 v[228:231], v[18:21], v[160:163], v[58:61]
	v_mfma_f32_16x16x32_bf16 v[232:235], v[18:21], v[164:167], v[62:65]
	v_mfma_f32_16x16x32_bf16 v[236:239], v[18:21], v[168:171], v[30:33]
	s_waitcnt lgkmcnt(1)
	v_mfma_f32_16x16x32_bf16 v[240:243], v[22:25], v[10:13], v[66:69]
	v_mfma_f32_16x16x32_bf16 v[64:67], v[22:25], v[168:171], v[34:37]
	s_waitcnt lgkmcnt(0)
	v_mfma_f32_16x16x32_bf16 v[40:43], v[172:175], v[164:167], v[92:95]
	v_mfma_f32_16x16x32_bf16 v[32:35], v[172:175], v[168:171], v[152:155]
	ds_read_b128 v[14:17], v8 offset:45056
	ds_read_b128 v[18:21], v8 offset:46080
	ds_read_b128 v[92:95], v8 offset:47104
	ds_read_b128 v[152:155], v8 offset:48128
	s_nop 0
	v_cvt_pk_bf16_f32 v64, v64, v65
	v_cvt_pk_bf16_f32 v65, v66, v67
	v_mfma_f32_16x16x32_bf16 v[80:83], v[22:25], v[160:163], v[70:73]
	v_cvt_pk_bf16_f32 v32, v32, v33
	v_cvt_pk_bf16_f32 v33, v34, v35
	v_cvt_pk_bf16_f32 v40, v40, v41
	v_mfma_f32_16x16x32_bf16 v[72:75], v[22:25], v[164:167], v[74:77]
	v_cvt_pk_bf16_f32 v41, v42, v43
	s_nop 2
	v_cvt_pk_bf16_f32 v80, v80, v81
	v_cvt_pk_bf16_f32 v81, v82, v83
	v_mfma_f32_16x16x32_bf16 v[48:51], v[172:175], v[160:163], v[84:87]
	s_waitcnt lgkmcnt(3)
	v_mfma_f32_16x16x32_bf16 v[112:115], v[14:17], v[10:13], v[112:115]
	v_cvt_pk_bf16_f32 v72, v72, v73
	v_cvt_pk_bf16_f32 v73, v74, v75
	s_nop 3
	v_cvt_pk_bf16_f32 v48, v48, v49
	v_mfma_f32_16x16x32_bf16 v[84:87], v[14:17], v[160:163], v[116:119]
	v_cvt_pk_bf16_f32 v49, v50, v51
	v_mfma_f32_16x16x32_bf16 v[76:79], v[14:17], v[164:167], v[120:123]
	v_mfma_f32_16x16x32_bf16 v[68:71], v[14:17], v[168:171], v[96:99]
	s_waitcnt lgkmcnt(2)
	v_mfma_f32_16x16x32_bf16 v[60:63], v[18:21], v[10:13], v[124:127]
	s_nop 0
	v_cvt_pk_bf16_f32 v96, v190, v191
	v_cvt_pk_bf16_f32 v97, v192, v193
	v_mfma_f32_16x16x32_bf16 v[52:55], v[18:21], v[160:163], v[128:131]
	v_mfma_f32_16x16x32_bf16 v[44:47], v[18:21], v[164:167], v[132:135]
	v_mfma_f32_16x16x32_bf16 v[36:39], v[18:21], v[168:171], v[100:103]
	s_waitcnt lgkmcnt(1)
; DI void st_bf4(u16* p, float a, float b, float c, float d) { *(uint2*)p = make_uint2(pk2(a, b), pk2(c, d)); }
; template <int BM, class Epi>
; DI void gemm_dma(const u16* __restrict__ X, long ldx, const u16* __restrict__ W, long ldw, int K, char* smem,
;                  int m0, int n0, const Epi& epi) {
;     ...
;       for (int i = 0; i < 4; ++i)
; #pragma unroll
;         for (int mt = 0; mt < MT; ++mt)
;           acc[nh * 4 + i][mt] = __builtin_amdgcn_mfma_f32_16x16x32_bf16(wf[i], xf[mt], acc[nh * 4 + i][mt], 0, 0, 0);
;   template <int NT, int MT> DI void run(f32x4 (&acc)[NT][MT], int mb, int nb) const {
; #pragma unroll
;     for (int nt = 0; nt < NT; ++nt)
; #pragma unroll
;       for (int mt = 0; mt < MT; ++mt) {
;         f32x4 v = acc[nt][mt];
;         st_bf4(C + (size_t)(mb + mt * 16) * ldc + nb + nt * 16, v[0], v[1], v[2], v[3]);
;       }
	v_mfma_f32_16x16x32_bf16 v[28:31], v[92:95], v[10:13], v[108:111]
	v_mfma_f32_16x16x32_bf16 v[24:27], v[92:95], v[160:163], v[136:139]
	v_mfma_f32_16x16x32_bf16 v[20:23], v[92:95], v[164:167], v[140:143]
	s_nop 5
	v_cvt_pk_bf16_f32 v28, v28, v29
	v_cvt_pk_bf16_f32 v29, v30, v31
	v_cvt_pk_bf16_f32 v24, v24, v25
	v_mfma_f32_16x16x32_bf16 v[16:19], v[92:95], v[168:171], v[104:107]
	v_or_b32_e32 v92, v90, v89
	v_ashrrev_i32_e32 v93, 31, v92
	v_lshlrev_b64 v[90:91], 11, v[92:93]
	v_lshl_add_u64 v[90:91], s[92:93], 0, v[90:91]
	v_lshl_add_u64 v[88:89], v[90:91], 0, v[182:183]
	v_cvt_pk_bf16_f32 v90, v176, v177
	v_cvt_pk_bf16_f32 v91, v178, v179
	global_store_dwordx2 v[88:89], v[90:91], off
	v_or_b32_e32 v90, 16, v92
	v_ashrrev_i32_e32 v91, 31, v90
	v_lshlrev_b64 v[90:91], 11, v[90:91]
	v_lshl_add_u64 v[90:91], s[92:93], 0, v[90:91]
	v_lshl_add_u64 v[90:91], v[90:91], 0, v[182:183]
	v_cvt_pk_bf16_f32 v94, v186, v187
	v_cvt_pk_bf16_f32 v95, v188, v189
	global_store_dwordx2 v[90:91], v[94:95], off
	v_or_b32_e32 v94, 32, v92
	v_or_b32_e32 v92, 48, v92
	v_ashrrev_i32_e32 v93, 31, v92
	v_lshlrev_b64 v[92:93], 11, v[92:93]
	v_ashrrev_i32_e32 v95, 31, v94
	v_lshl_add_u64 v[92:93], s[92:93], 0, v[92:93]
	v_lshlrev_b64 v[94:95], 11, v[94:95]
	v_lshl_add_u64 v[92:93], v[92:93], 0, v[182:183]
	v_lshl_add_u64 v[94:95], s[92:93], 0, v[94:95]
	global_store_dwordx2 v[92:93], v[32:33], off offset:96
	v_cvt_pk_bf16_f32 v32, v112, v113
	v_cvt_pk_bf16_f32 v33, v114, v115
	v_lshl_add_u64 v[94:95], v[94:95], 0, v[182:183]
	global_store_dwordx2 v[88:89], v[32:33], off offset:128
	v_cvt_pk_bf16_f32 v32, v84, v85
	v_cvt_pk_bf16_f32 v33, v86, v87
	global_store_dwordx2 v[94:95], v[96:97], off
	v_cvt_pk_bf16_f32 v96, v194, v195
	v_cvt_pk_bf16_f32 v97, v196, v197
	global_store_dwordx2 v[90:91], v[32:33], off offset:128
	v_cvt_pk_bf16_f32 v32, v76, v77
	v_cvt_pk_bf16_f32 v33, v78, v79
	v_mfma_f32_16x16x32_bf16 v[56:59], v[172:175], v[10:13], v[156:159]
	global_store_dwordx2 v[92:93], v[96:97], off
	v_cvt_pk_bf16_f32 v96, v224, v225
	v_cvt_pk_bf16_f32 v97, v226, v227
	s_waitcnt lgkmcnt(0)
	v_mfma_f32_16x16x32_bf16 v[12:15], v[152:155], v[10:13], v[4:7]
	global_store_dwordx2 v[94:95], v[32:33], off offset:128
	v_cvt_pk_bf16_f32 v32, v68, v69
	v_cvt_pk_bf16_f32 v33, v70, v71
	v_mfma_f32_16x16x32_bf16 v[8:11], v[152:155], v[160:163], v[144:147]
	global_store_dwordx2 v[88:89], v[96:97], off offset:32
	v_cvt_pk_bf16_f32 v96, v228, v229
	v_cvt_pk_bf16_f32 v97, v230, v231
	v_mfma_f32_16x16x32_bf16 v[4:7], v[152:155], v[164:167], v[148:151]
	global_store_dwordx2 v[92:93], v[32:33], off offset:128
	v_cvt_pk_bf16_f32 v32, v60, v61
	v_cvt_pk_bf16_f32 v33, v62, v63
	v_mfma_f32_16x16x32_bf16 v[0:3], v[152:155], v[168:171], v[0:3]
	global_store_dwordx2 v[90:91], v[96:97], off offset:32
	v_cvt_pk_bf16_f32 v96, v232, v233
	v_cvt_pk_bf16_f32 v97, v234, v235
	global_store_dwordx2 v[88:89], v[32:33], off offset:160
	v_cvt_pk_bf16_f32 v32, v52, v53
	v_cvt_pk_bf16_f32 v33, v54, v55
	global_store_dwordx2 v[94:95], v[96:97], off offset:32
	v_cvt_pk_bf16_f32 v96, v236, v237
	v_cvt_pk_bf16_f32 v97, v238, v239
	global_store_dwordx2 v[90:91], v[32:33], off offset:160
	v_cvt_pk_bf16_f32 v32, v44, v45
	v_cvt_pk_bf16_f32 v33, v46, v47
	global_store_dwordx2 v[92:93], v[96:97], off offset:32
	v_cvt_pk_bf16_f32 v96, v240, v241
	v_cvt_pk_bf16_f32 v97, v242, v243
	v_cvt_pk_bf16_f32 v56, v56, v57
	v_cvt_pk_bf16_f32 v57, v58, v59
	global_store_dwordx2 v[94:95], v[32:33], off offset:160
	v_cvt_pk_bf16_f32 v32, v36, v37
	v_cvt_pk_bf16_f32 v33, v38, v39
	v_cvt_pk_bf16_f32 v25, v26, v27
	v_cvt_pk_bf16_f32 v20, v20, v21
	v_cvt_pk_bf16_f32 v21, v22, v23
	v_cvt_pk_bf16_f32 v16, v16, v17
	v_cvt_pk_bf16_f32 v17, v18, v19
	v_cvt_pk_bf16_f32 v12, v12, v13
	v_cvt_pk_bf16_f32 v13, v14, v15
	v_cvt_pk_bf16_f32 v8, v8, v9
	v_cvt_pk_bf16_f32 v9, v10, v11
	v_cvt_pk_bf16_f32 v4, v4, v5
	v_cvt_pk_bf16_f32 v5, v6, v7
	v_cvt_pk_bf16_f32 v0, v0, v1
	v_cvt_pk_bf16_f32 v1, v2, v3
	global_store_dwordx2 v[88:89], v[96:97], off offset:64
	global_store_dwordx2 v[90:91], v[80:81], off offset:64
	global_store_dwordx2 v[94:95], v[72:73], off offset:64
	global_store_dwordx2 v[92:93], v[64:65], off offset:64
	global_store_dwordx2 v[88:89], v[56:57], off offset:96
	global_store_dwordx2 v[90:91], v[48:49], off offset:96
	global_store_dwordx2 v[94:95], v[40:41], off offset:96
	global_store_dwordx2 v[92:93], v[32:33], off offset:160
	global_store_dwordx2 v[88:89], v[28:29], off offset:192
	global_store_dwordx2 v[90:91], v[24:25], off offset:192
	global_store_dwordx2 v[94:95], v[20:21], off offset:192
	global_store_dwordx2 v[92:93], v[16:17], off offset:192
	global_store_dwordx2 v[88:89], v[12:13], off offset:224
	global_store_dwordx2 v[90:91], v[8:9], off offset:224
	global_store_dwordx2 v[94:95], v[4:5], off offset:224
	global_store_dwordx2 v[92:93], v[0:1], off offset:224

; template <int N> DI void wait_vm() { asm volatile("s_waitcnt vmcnt(%0)" ::"n"(N) : "memory"); }
; template <int BM, class Epi>
; DI void gemm_dma(const u16* __restrict__ X, long ldx, const u16* __restrict__ W, long ldw, int K, char* smem,
;                  int m0, int n0, const Epi& epi) {
;     ...
;   const int wu = __builtin_amdgcn_readfirstlane(wave);
;   const unsigned sbase = (unsigned)__builtin_amdgcn_readfirstlane((int)(unsigned)(size_t)smem);
;   const int r16 = lane >> 2, chunk = (lane & 3) ^ ((4 - (r16 >> 2)) & 3);
;   const u16* xs = X + (long)(wu * XD * 16 + r16) * ldx + (chunk << 3);
;   const u16* ws = W + (long)(wu * 32 + r16) * ldw + (chunk << 3);
;   const long ldx16 = 16 * ldx, ldw16 = 16 * ldw;
;   const unsigned xdst = sbase + wu * XD * 1024, wdst = sbase + BM * 64 + wu * 2048;
;     ...
;   const int nk = K >> 5;
;   __syncthreads();
; #pragma unroll
;   for (int s = 0; s < D - 1; ++s) GD_ISSUE(s)
;   int cur = 0, nxt = D - 1, kt = 0;
;   do {
;     if (kt + D - 2 < nk) wait_vm<PW * (D - 2)>(); else wait_vm<0>();
;     __syncthreads();
;     if (kt + D - 1 < nk) GD_ISSUE(nxt)
;     nxt = (nxt + 1 == D) ? 0 : nxt + 1;
;     const char* base = smem + cur * STG;
;     cur = (cur + 1 == D) ? 0 : cur + 1;
;     bf16x8 xf[MT];
; #pragma unroll
;     for (int i = 0; i < MT; ++i) xf[i] = *(const bf16x8*)(base + (xrow0 + i * 16) * 64 + rd);
; #pragma unroll
;     for (int nh = 0; nh < NT / 4; ++nh) {
;       bf16x8 wf[4];
; #pragma unroll
;       for (int i = 0; i < 4; ++i) wf[i] = *(const bf16x8*)(base + BM * 64 + (wrow0 + (nh * 4 + i) * 16) * 64 + rd);
; DI void knope_tile(const Params& p, int u, char* smem) {
;     ...
;   const int tm = u >> 3, tn = u & 7;
;   gemm_dma<256>(ckvb + (size_t)tm * 256 * 256, 256, W + WO_KV + (size_t)tn * 128 * 256, 256, 256, smem, tm * 256, tn * 128, ek);
.LBB0_981:
	s_cmpk_gt_i32 s5, 0x62f
	s_mov_b64 s[38:39], -1
	s_cbranch_scc0 .LBB0_983
	s_add_i32 s4, s5, 0xfffff9d0
	s_bfe_u32 s98, s4, 0x30003
	s_and_b32 s99, s4, 7
	s_lshl_b32 s99, s99, 3
	s_andn2_b32 s4, s4, 63
	s_or_b32 s4, s4, s99
	s_or_b32 s4, s4, s98
	s_lshr_b32 s6, s4, 3
	s_and_b32 s4, s4, 7
	s_lshl_b32 s7, s6, 17
	s_add_u32 s8, s0, s7
	s_addc_u32 s9, s1, 0
	s_lshl_b32 s7, s4, 16
	v_mov_b32_e32 v9, v185
	s_add_u32 s10, s87, s7
	s_addc_u32 s11, s90, 0
	v_readfirstlane_b32 s7, v9
	v_lshrrev_b32_e32 v4, 4, v9
	s_ashr_i32 s12, s7, 6
	v_bfe_u32 v6, v9, 2, 4
	v_sub_u32_e32 v4, 0, v4
	s_andn2_b32 s7, s7, 63
	v_lshrrev_b32_e32 v1, 2, v9
	v_xor_b32_e32 v7, v9, v4
	v_or_b32_e32 v4, s7, v6
	v_and_b32_e32 v89, 15, v9
	v_bfe_u32 v88, v9, 4, 2
	v_sub_u32_e32 v1, 0, v1
	v_ashrrev_i32_e32 v5, 31, v4
	v_lshlrev_b32_e32 v0, 6, v89
	v_bitop3_b32 v1, v88, v1, 3 bitop3:0x78
	v_lshlrev_b64 v[4:5], 9, v[4:5]
	v_lshlrev_b32_e32 v7, 4, v7
	v_lshl_or_b32 v6, s12, 5, v6
	v_lshl_or_b32 v8, v1, 4, v0
	v_mov_b32_e32 v0, v183
	v_lshl_add_u64 v[4:5], s[8:9], 0, v[4:5]
	v_and_b32_e32 v182, 48, v7
	v_ashrrev_i32_e32 v7, 31, v6
	v_lshl_add_u64 v[4:5], v[4:5], 0, v[182:183]
	v_lshlrev_b64 v[6:7], 9, v[6:7]
	s_lshl_b32 s14, s12, 12
	s_waitcnt lgkmcnt(0)
	s_barrier
	s_mov_b32 s7, m0
	s_mov_b32 m0, s14
	s_nop 0
	global_load_lds_dwordx4 v[4:5], off
	s_mov_b32 m0, s7
	s_mov_b64 s[8:9], 0x2000
	v_lshl_add_u64 v[6:7], s[10:11], 0, v[6:7]
	v_lshl_add_u64 v[10:11], v[4:5], 0, s[8:9]
	s_or_b32 s15, s14, 0x400
	s_mov_b32 s7, m0
	s_mov_b32 m0, s15
	s_nop 0
	global_load_lds_dwordx4 v[10:11], off
	s_mov_b32 m0, s7
	s_mov_b64 s[10:11], 0x4000
	v_lshl_add_u64 v[10:11], v[4:5], 0, s[10:11]
	s_or_b32 s16, s14, 0x800
	s_mov_b32 s7, m0
	s_mov_b32 m0, s16
	s_nop 0
	global_load_lds_dwordx4 v[10:11], off
	s_mov_b32 m0, s7
	s_mov_b64 s[10:11], 0x6000
	s_lshl_b32 s42, s12, 11
	v_lshl_add_u64 v[10:11], v[4:5], 0, s[10:11]
	s_or_b32 s17, s14, 0xc00
	s_mov_b32 s7, m0
	s_mov_b32 m0, s17
	s_nop 0
	global_load_lds_dwordx4 v[10:11], off
	s_mov_b32 m0, s7
	v_lshl_add_u64 v[6:7], v[6:7], 0, v[182:183]
	s_add_i32 s13, s42, 0x4000
	s_mov_b32 s7, m0
	s_mov_b32 m0, s13
	s_nop 0
	global_load_lds_dwordx4 v[6:7], off
	s_mov_b32 m0, s7
	v_lshl_add_u64 v[10:11], v[6:7], 0, s[8:9]
	s_add_i32 s18, s42, 0x4400
	s_mov_b32 s7, m0
	s_mov_b32 m0, s18
	s_nop 0
	global_load_lds_dwordx4 v[10:11], off
	s_mov_b32 m0, s7
	v_lshl_add_u64 v[10:11], v[4:5], 0, 64
	s_add_i32 s7, s14, 0x6000
	s_mov_b32 s8, m0
	s_mov_b32 m0, s7
	s_nop 0
	global_load_lds_dwordx4 v[10:11], off
	s_mov_b32 m0, s8
	s_mov_b64 s[20:21], 0x2040
	v_lshl_add_u64 v[10:11], v[4:5], 0, s[20:21]
	s_add_i32 s8, s14, 0x6400
	s_mov_b32 s9, m0
	s_mov_b32 m0, s8
	s_nop 0
	global_load_lds_dwordx4 v[10:11], off
	s_mov_b32 m0, s9
	s_mov_b64 s[10:11], 0x4040
	v_lshl_add_u64 v[10:11], v[4:5], 0, s[10:11]
	s_add_i32 s9, s14, 0x6800
	s_mov_b32 s10, m0
	s_mov_b32 m0, s9
	s_nop 0
	global_load_lds_dwordx4 v[10:11], off
	s_mov_b32 m0, s10
	s_mov_b64 s[10:11], 0x6040
	v_lshl_add_u64 v[10:11], v[4:5], 0, s[10:11]
	s_add_i32 s10, s14, 0x6c00
	s_mov_b32 s11, m0
	s_mov_b32 m0, s10
	s_nop 0
	global_load_lds_dwordx4 v[10:11], off
	s_mov_b32 m0, s11
	v_lshl_add_u64 v[12:13], v[6:7], 0, 64
	s_add_i32 s11, s42, 0xa000
	s_mov_b32 s12, m0
	s_mov_b32 m0, s11
	s_nop 0
	global_load_lds_dwordx4 v[12:13], off
	s_mov_b32 m0, s12
	v_lshl_add_u64 v[10:11], v[6:7], 0, s[20:21]
	s_add_i32 s12, s42, 0xa400
	s_mov_b32 s19, m0
	s_mov_b32 m0, s12
	s_nop 0
	global_load_lds_dwordx4 v[10:11], off
	s_mov_b32 m0, s19
	s_waitcnt vmcnt(6)
	s_barrier
	v_lshl_add_u64 v[12:13], v[4:5], 0, s[28:29]
	s_add_i32 s19, s14, 0xc000
	s_mov_b32 s34, m0
	s_mov_b32 m0, s19
	s_nop 0
	global_load_lds_dwordx4 v[12:13], off
	s_mov_b32 m0, s34
	s_mov_b64 s[20:21], 0x2080
	v_lshl_add_u64 v[12:13], v[4:5], 0, s[20:21]
	s_add_i32 s34, s14, 0xc400
	s_mov_b32 s38, m0
	s_mov_b32 m0, s34
	s_nop 0
	global_load_lds_dwordx4 v[12:13], off
	s_mov_b32 m0, s38
	v_lshl_add_u64 v[12:13], v[4:5], 0, s[94:95]
	s_add_i32 s38, s14, 0xc800
	s_mov_b32 s39, m0
	s_mov_b32 m0, s38
	s_nop 0
	global_load_lds_dwordx4 v[12:13], off
	s_mov_b32 m0, s39
	s_mov_b64 s[22:23], 0x6080
	v_lshl_add_u64 v[12:13], v[4:5], 0, s[22:23]
	s_add_i32 s43, s14, 0xcc00
	s_mov_b32 s39, m0
	s_mov_b32 m0, s43
	s_nop 0
	global_load_lds_dwordx4 v[12:13], off
	s_mov_b32 m0, s39
	v_and_b32_e32 v90, 0xffffffc0, v9
	v_lshl_add_u64 v[10:11], v[6:7], 0, s[28:29]
	s_add_i32 s39, s42, 0x10000
	s_mov_b32 s44, m0
	s_mov_b32 m0, s39
	s_nop 0
	global_load_lds_dwordx4 v[10:11], off
	s_mov_b32 m0, s44
	v_lshl_add_u64 v[10:11], v[6:7], 0, s[20:21]
	s_add_i32 s42, s42, 0x10400
	s_mov_b32 s44, m0
	s_mov_b32 m0, s42
	s_nop 0
	global_load_lds_dwordx4 v[10:11], off
	s_mov_b32 m0, s44
	v_lshl_or_b32 v9, v90, 6, v8
	ds_read_b128 v[10:13], v9
	s_waitcnt vmcnt(7)
	ds_read_b128 v[14:17], v9 offset:1024
	s_waitcnt vmcnt(5)
	ds_read_b128 v[18:21], v9 offset:2048
	s_waitcnt vmcnt(5)
	ds_read_b128 v[22:25], v9 offset:3072
	s_waitcnt vmcnt(4)
	ds_read_b128 v[26:29], v8 offset:16384
	s_waitcnt vmcnt(4)
	ds_read_b128 v[30:33], v8 offset:17408
	ds_read_b128 v[34:37], v8 offset:18432
	ds_read_b128 v[38:41], v8 offset:19456
	s_waitcnt vmcnt(0)
	ds_read_b128 v[96:99], v8 offset:20480
	ds_read_b128 v[100:103], v8 offset:21504
	ds_read_b128 v[104:107], v8 offset:22528
	ds_read_b128 v[108:111], v8 offset:23552
	s_mov_b64 s[20:21], 0xc0
	v_mov_b32_e32 v1, v0
	v_mov_b32_e32 v2, v0
	v_mov_b32_e32 v3, v0
	v_lshl_add_u64 v[86:87], v[4:5], 0, s[20:21]
	v_lshl_add_u64 v[148:149], v[6:7], 0, s[20:21]
	s_waitcnt vmcnt(6)
	s_waitcnt lgkmcnt(0)
	s_barrier
; template <int N> DI void wait_vm() { asm volatile("s_waitcnt vmcnt(%0)" ::"n"(N) : "memory"); }
; template <int BM, class Epi>
; DI void gemm_dma(const u16* __restrict__ X, long ldx, const u16* __restrict__ W, long ldw, int K, char* smem,
;                  int m0, int n0, const Epi& epi) {
;     ...
;   do {
;     if (kt + D - 2 < nk) wait_vm<PW * (D - 2)>(); else wait_vm<0>();
;     __syncthreads();
;     if (kt + D - 1 < nk) GD_ISSUE(nxt)
;     nxt = (nxt + 1 == D) ? 0 : nxt + 1;
;     const char* base = smem + cur * STG;
;     cur = (cur + 1 == D) ? 0 : cur + 1;
;     bf16x8 xf[MT];
; #pragma unroll
;     for (int i = 0; i < MT; ++i) xf[i] = *(const bf16x8*)(base + (xrow0 + i * 16) * 64 + rd);
; #pragma unroll
;     for (int nh = 0; nh < NT / 4; ++nh) {
;       bf16x8 wf[4];
; #pragma unroll
;       for (int i = 0; i < 4; ++i) wf[i] = *(const bf16x8*)(base + BM * 64 + (wrow0 + (nh * 4 + i) * 16) * 64 + rd);
; #pragma unroll
;       for (int i = 0; i < 4; ++i)
; #pragma unroll
;         for (int mt = 0; mt < MT; ++mt)
;           acc[nh * 4 + i][mt] = __builtin_amdgcn_mfma_f32_16x16x32_bf16(wf[i], xf[mt], acc[nh * 4 + i][mt], 0, 0, 0);
	s_mov_b32 s44, m0
	s_mov_b32 m0, s14
	s_nop 0
	global_load_lds_dwordx4 v[86:87], off
	s_mov_b32 m0, s44
	s_mov_b64 s[20:21], 0x20c0
	v_mfma_f32_16x16x32_bf16 v[42:45], v[26:29], v[10:13], v[0:3]
	s_mov_b64 s[22:23], 0x40c0
	v_or_b32_e32 v91, 0x10000, v8
	v_or_b32_e32 v174, 0x10400, v8
	v_mfma_f32_16x16x32_bf16 v[46:49], v[26:29], v[14:17], v[0:3]
	v_or_b32_e32 v175, 0x10800, v8
	v_or_b32_e32 v176, 0x10c00, v8
	v_or_b32_e32 v177, 0x11000, v8
	v_mfma_f32_16x16x32_bf16 v[50:53], v[26:29], v[18:21], v[0:3]
	v_or_b32_e32 v178, 0x11400, v8
	v_or_b32_e32 v179, 0x11800, v8
	v_or_b32_e32 v180, 0x11c00, v8
	v_mfma_f32_16x16x32_bf16 v[26:29], v[26:29], v[22:25], v[0:3]
	v_lshl_add_u32 v90, s6, 8, v90
	s_lshl_b32 s4, s4, 8
	v_lshl_or_b32 v182, v88, 3, s4
	v_mfma_f32_16x16x32_bf16 v[54:57], v[30:33], v[10:13], v[0:3]
	v_mfma_f32_16x16x32_bf16 v[58:61], v[30:33], v[14:17], v[0:3]
	v_mfma_f32_16x16x32_bf16 v[62:65], v[30:33], v[18:21], v[0:3]
	v_mfma_f32_16x16x32_bf16 v[30:33], v[30:33], v[22:25], v[0:3]
	v_mfma_f32_16x16x32_bf16 v[66:69], v[34:37], v[10:13], v[0:3]
	v_mfma_f32_16x16x32_bf16 v[70:73], v[34:37], v[14:17], v[0:3]
	v_mfma_f32_16x16x32_bf16 v[74:77], v[34:37], v[18:21], v[0:3]
	v_mfma_f32_16x16x32_bf16 v[34:37], v[34:37], v[22:25], v[0:3]
	v_mfma_f32_16x16x32_bf16 v[78:81], v[38:41], v[10:13], v[0:3]
	v_mfma_f32_16x16x32_bf16 v[82:85], v[38:41], v[14:17], v[0:3]
	v_mfma_f32_16x16x32_bf16 v[92:95], v[38:41], v[18:21], v[0:3]
	v_mfma_f32_16x16x32_bf16 v[38:41], v[38:41], v[22:25], v[0:3]
	v_mfma_f32_16x16x32_bf16 v[112:115], v[96:99], v[10:13], v[0:3]
	v_mfma_f32_16x16x32_bf16 v[116:119], v[96:99], v[14:17], v[0:3]
	v_mfma_f32_16x16x32_bf16 v[120:123], v[96:99], v[18:21], v[0:3]
	v_mfma_f32_16x16x32_bf16 v[96:99], v[96:99], v[22:25], v[0:3]
	v_mfma_f32_16x16x32_bf16 v[124:127], v[100:103], v[10:13], v[0:3]
	v_mfma_f32_16x16x32_bf16 v[128:131], v[100:103], v[14:17], v[0:3]
	v_mfma_f32_16x16x32_bf16 v[132:135], v[100:103], v[18:21], v[0:3]
	v_mfma_f32_16x16x32_bf16 v[100:103], v[100:103], v[22:25], v[0:3]
	v_mfma_f32_16x16x32_bf16 v[136:139], v[104:107], v[10:13], v[0:3]
	v_mfma_f32_16x16x32_bf16 v[140:143], v[104:107], v[14:17], v[0:3]
	v_mfma_f32_16x16x32_bf16 v[144:147], v[104:107], v[18:21], v[0:3]
	v_mfma_f32_16x16x32_bf16 v[104:107], v[104:107], v[22:25], v[0:3]
	v_mfma_f32_16x16x32_bf16 v[10:13], v[108:111], v[10:13], v[0:3]
	v_mfma_f32_16x16x32_bf16 v[14:17], v[108:111], v[14:17], v[0:3]
	v_mfma_f32_16x16x32_bf16 v[18:21], v[108:111], v[18:21], v[0:3]
	v_mfma_f32_16x16x32_bf16 v[0:3], v[108:111], v[22:25], v[0:3]
	v_lshl_add_u64 v[22:23], v[4:5], 0, s[20:21]
	s_mov_b32 s44, m0
	s_mov_b32 m0, s15
	s_nop 0
	global_load_lds_dwordx4 v[22:23], off
	s_mov_b32 m0, s44
	v_lshl_add_u64 v[22:23], v[4:5], 0, s[22:23]
	s_mov_b32 s44, m0
	s_mov_b32 m0, s16
	s_nop 0
	global_load_lds_dwordx4 v[22:23], off
	s_mov_b32 m0, s44
	s_mov_b64 s[22:23], 0x60c0
	v_lshl_add_u64 v[22:23], v[4:5], 0, s[22:23]
	s_mov_b32 s44, m0
	s_mov_b32 m0, s17
	s_nop 0
	global_load_lds_dwordx4 v[22:23], off
	s_mov_b32 m0, s44
	v_lshl_add_u64 v[22:23], v[6:7], 0, s[20:21]
	s_mov_b32 s44, m0
	s_mov_b32 m0, s13
	s_nop 0
	global_load_lds_dwordx4 v[148:149], off
	s_mov_b32 m0, s44
	s_mov_b64 s[20:21], 0x100
	s_mov_b32 s44, m0
	s_mov_b32 m0, s18
	s_nop 0
	global_load_lds_dwordx4 v[22:23], off
	s_mov_b32 m0, s44
	ds_read_b128 v[22:25], v9 offset:24576
	ds_read_b128 v[108:111], v9 offset:25600
	ds_read_b128 v[148:151], v9 offset:26624
	ds_read_b128 v[152:155], v9 offset:27648
	ds_read_b128 v[156:159], v8 offset:40960
	ds_read_b128 v[160:163], v8 offset:41984
	ds_read_b128 v[164:167], v8 offset:43008
	ds_read_b128 v[168:171], v8 offset:44032
	s_waitcnt lgkmcnt(3)
	v_mfma_f32_16x16x32_bf16 v[42:45], v[156:159], v[22:25], v[42:45]
	v_lshl_add_u64 v[86:87], v[4:5], 0, s[20:21]
	v_lshl_add_u64 v[172:173], v[6:7], 0, s[20:21]
	s_mov_b64 s[20:21], 0x2100
	v_mfma_f32_16x16x32_bf16 v[46:49], v[156:159], v[108:111], v[46:49]
	s_mov_b64 s[22:23], 0x4100
	v_mfma_f32_16x16x32_bf16 v[50:53], v[156:159], v[148:151], v[50:53]
	v_mfma_f32_16x16x32_bf16 v[26:29], v[156:159], v[152:155], v[26:29]
	s_waitcnt lgkmcnt(2)
	v_mfma_f32_16x16x32_bf16 v[54:57], v[160:163], v[22:25], v[54:57]
	v_mfma_f32_16x16x32_bf16 v[58:61], v[160:163], v[108:111], v[58:61]
	v_mfma_f32_16x16x32_bf16 v[62:65], v[160:163], v[148:151], v[62:65]
	v_mfma_f32_16x16x32_bf16 v[30:33], v[160:163], v[152:155], v[30:33]
	s_waitcnt lgkmcnt(1)
	v_mfma_f32_16x16x32_bf16 v[66:69], v[164:167], v[22:25], v[66:69]
	v_mfma_f32_16x16x32_bf16 v[70:73], v[164:167], v[108:111], v[70:73]
	v_mfma_f32_16x16x32_bf16 v[74:77], v[164:167], v[148:151], v[74:77]
	v_mfma_f32_16x16x32_bf16 v[34:37], v[164:167], v[152:155], v[34:37]
	s_waitcnt lgkmcnt(0)
	v_mfma_f32_16x16x32_bf16 v[78:81], v[168:171], v[22:25], v[78:81]
	v_mfma_f32_16x16x32_bf16 v[82:85], v[168:171], v[108:111], v[82:85]
	v_mfma_f32_16x16x32_bf16 v[92:95], v[168:171], v[148:151], v[92:95]
	v_mfma_f32_16x16x32_bf16 v[38:41], v[168:171], v[152:155], v[38:41]
	ds_read_b128 v[156:159], v8 offset:45056
	ds_read_b128 v[160:163], v8 offset:46080
	ds_read_b128 v[164:167], v8 offset:47104
	ds_read_b128 v[168:171], v8 offset:48128
	s_waitcnt vmcnt(6)
	s_waitcnt lgkmcnt(0)
	s_barrier
; template <int N> DI void wait_vm() { asm volatile("s_waitcnt vmcnt(%0)" ::"n"(N) : "memory"); }
; template <int BM, class Epi>
; DI void gemm_dma(const u16* __restrict__ X, long ldx, const u16* __restrict__ W, long ldw, int K, char* smem,
;                  int m0, int n0, const Epi& epi) {
;     ...
;   do {
;     if (kt + D - 2 < nk) wait_vm<PW * (D - 2)>(); else wait_vm<0>();
;     __syncthreads();
;     if (kt + D - 1 < nk) GD_ISSUE(nxt)
;     nxt = (nxt + 1 == D) ? 0 : nxt + 1;
;     const char* base = smem + cur * STG;
;     cur = (cur + 1 == D) ? 0 : cur + 1;
;     bf16x8 xf[MT];
; #pragma unroll
;     for (int i = 0; i < MT; ++i) xf[i] = *(const bf16x8*)(base + (xrow0 + i * 16) * 64 + rd);
; #pragma unroll
;     for (int nh = 0; nh < NT / 4; ++nh) {
;       bf16x8 wf[4];
; #pragma unroll
;       for (int i = 0; i < 4; ++i) wf[i] = *(const bf16x8*)(base + BM * 64 + (wrow0 + (nh * 4 + i) * 16) * 64 + rd);
; #pragma unroll
;       for (int i = 0; i < 4; ++i)
; #pragma unroll
;         for (int mt = 0; mt < MT; ++mt)
;           acc[nh * 4 + i][mt] = __builtin_amdgcn_mfma_f32_16x16x32_bf16(wf[i], xf[mt], acc[nh * 4 + i][mt], 0, 0, 0);
	s_mov_b32 s44, m0
	s_mov_b32 m0, s7
	s_nop 0
	global_load_lds_dwordx4 v[86:87], off
	s_mov_b32 m0, s44
	v_mfma_f32_16x16x32_bf16 v[112:115], v[156:159], v[22:25], v[112:115]
	v_mfma_f32_16x16x32_bf16 v[124:127], v[160:163], v[22:25], v[124:127]
	v_mfma_f32_16x16x32_bf16 v[136:139], v[164:167], v[22:25], v[136:139]
	v_mfma_f32_16x16x32_bf16 v[10:13], v[168:171], v[22:25], v[10:13]
	v_lshl_add_u64 v[22:23], v[4:5], 0, s[20:21]
	s_mov_b32 s44, m0
	s_mov_b32 m0, s8
	s_nop 0
	global_load_lds_dwordx4 v[22:23], off
	s_mov_b32 m0, s44
	v_lshl_add_u64 v[22:23], v[4:5], 0, s[22:23]
	s_mov_b32 s44, m0
	s_mov_b32 m0, s9
	s_nop 0
	global_load_lds_dwordx4 v[22:23], off
	s_mov_b32 m0, s44
	s_mov_b64 s[22:23], 0x6100
	v_lshl_add_u64 v[22:23], v[4:5], 0, s[22:23]
	s_mov_b32 s44, m0
	s_mov_b32 m0, s10
	s_nop 0
	global_load_lds_dwordx4 v[22:23], off
	s_mov_b32 m0, s44
	v_lshl_add_u64 v[22:23], v[6:7], 0, s[20:21]
	s_mov_b32 s44, m0
	s_mov_b32 m0, s11
	s_nop 0
	global_load_lds_dwordx4 v[172:173], off
	s_mov_b32 m0, s44
	v_mfma_f32_16x16x32_bf16 v[116:119], v[156:159], v[108:111], v[116:119]
	s_mov_b32 s44, m0
	s_mov_b32 m0, s12
	s_nop 0
	global_load_lds_dwordx4 v[22:23], off
	s_mov_b32 m0, s44
	s_mov_b64 s[20:21], 0x140
	v_lshl_add_u64 v[86:87], v[4:5], 0, s[20:21]
	v_mfma_f32_16x16x32_bf16 v[120:123], v[156:159], v[148:151], v[120:123]
	v_lshl_add_u64 v[172:173], v[6:7], 0, s[20:21]
	s_mov_b64 s[20:21], 0x2140
	s_mov_b64 s[22:23], 0x4140
	v_mfma_f32_16x16x32_bf16 v[96:99], v[156:159], v[152:155], v[96:99]
	v_mfma_f32_16x16x32_bf16 v[128:131], v[160:163], v[108:111], v[128:131]
	v_mfma_f32_16x16x32_bf16 v[132:135], v[160:163], v[148:151], v[132:135]
	v_mfma_f32_16x16x32_bf16 v[100:103], v[160:163], v[152:155], v[100:103]
	v_mfma_f32_16x16x32_bf16 v[140:143], v[164:167], v[108:111], v[140:143]
	v_mfma_f32_16x16x32_bf16 v[144:147], v[164:167], v[148:151], v[144:147]
	v_mfma_f32_16x16x32_bf16 v[104:107], v[164:167], v[152:155], v[104:107]
	v_mfma_f32_16x16x32_bf16 v[14:17], v[168:171], v[108:111], v[14:17]
	v_mfma_f32_16x16x32_bf16 v[18:21], v[168:171], v[148:151], v[18:21]
	v_mfma_f32_16x16x32_bf16 v[0:3], v[168:171], v[152:155], v[0:3]
	ds_read_b128 v[22:25], v9 offset:49152
	ds_read_b128 v[108:111], v9 offset:50176
	ds_read_b128 v[148:151], v9 offset:51200
	ds_read_b128 v[152:155], v9 offset:52224
	ds_read_b128 v[156:159], v91
	ds_read_b128 v[160:163], v174
	ds_read_b128 v[164:167], v175
	ds_read_b128 v[168:171], v176
	s_waitcnt lgkmcnt(3)
	v_mfma_f32_16x16x32_bf16 v[42:45], v[156:159], v[22:25], v[42:45]
	v_mfma_f32_16x16x32_bf16 v[46:49], v[156:159], v[108:111], v[46:49]
	v_mfma_f32_16x16x32_bf16 v[50:53], v[156:159], v[148:151], v[50:53]
	v_mfma_f32_16x16x32_bf16 v[26:29], v[156:159], v[152:155], v[26:29]
	ds_read_b128 v[156:159], v177
	s_waitcnt lgkmcnt(3)
	v_mfma_f32_16x16x32_bf16 v[54:57], v[160:163], v[22:25], v[54:57]
	v_mfma_f32_16x16x32_bf16 v[58:61], v[160:163], v[108:111], v[58:61]
	v_mfma_f32_16x16x32_bf16 v[62:65], v[160:163], v[148:151], v[62:65]
	v_mfma_f32_16x16x32_bf16 v[30:33], v[160:163], v[152:155], v[30:33]
	ds_read_b128 v[160:163], v178
	s_waitcnt lgkmcnt(3)
	v_mfma_f32_16x16x32_bf16 v[66:69], v[164:167], v[22:25], v[66:69]
	v_mfma_f32_16x16x32_bf16 v[70:73], v[164:167], v[108:111], v[70:73]
	v_mfma_f32_16x16x32_bf16 v[74:77], v[164:167], v[148:151], v[74:77]
	v_mfma_f32_16x16x32_bf16 v[34:37], v[164:167], v[152:155], v[34:37]
	ds_read_b128 v[164:167], v179
	s_waitcnt lgkmcnt(3)
	v_mfma_f32_16x16x32_bf16 v[78:81], v[168:171], v[22:25], v[78:81]
	v_mfma_f32_16x16x32_bf16 v[82:85], v[168:171], v[108:111], v[82:85]
	v_mfma_f32_16x16x32_bf16 v[92:95], v[168:171], v[148:151], v[92:95]
	v_mfma_f32_16x16x32_bf16 v[38:41], v[168:171], v[152:155], v[38:41]
	ds_read_b128 v[168:171], v180
	s_waitcnt vmcnt(6)
	s_waitcnt lgkmcnt(0)
	s_barrier
	s_mov_b32 s44, m0
	s_mov_b32 m0, s19
	s_nop 0
	global_load_lds_dwordx4 v[86:87], off
	s_mov_b32 m0, s44
	v_mfma_f32_16x16x32_bf16 v[112:115], v[156:159], v[22:25], v[112:115]
	v_mfma_f32_16x16x32_bf16 v[124:127], v[160:163], v[22:25], v[124:127]
	v_mfma_f32_16x16x32_bf16 v[136:139], v[164:167], v[22:25], v[136:139]
	v_mfma_f32_16x16x32_bf16 v[10:13], v[168:171], v[22:25], v[10:13]
	v_lshl_add_u64 v[22:23], v[4:5], 0, s[20:21]
	s_mov_b32 s19, m0
	s_mov_b32 m0, s34
	s_nop 0
	global_load_lds_dwordx4 v[22:23], off
	s_mov_b32 m0, s19
	v_lshl_add_u64 v[22:23], v[4:5], 0, s[22:23]
	s_mov_b32 s19, m0
	s_mov_b32 m0, s38
	s_nop 0
	global_load_lds_dwordx4 v[22:23], off
	s_mov_b32 m0, s19
	s_mov_b64 s[22:23], 0x6140
	v_lshl_add_u64 v[22:23], v[4:5], 0, s[22:23]
	s_mov_b32 s19, m0
	s_mov_b32 m0, s43
	s_nop 0
	global_load_lds_dwordx4 v[22:23], off
	s_mov_b32 m0, s19
	v_lshl_add_u64 v[22:23], v[6:7], 0, s[20:21]
	s_mov_b32 s19, m0
	s_mov_b32 m0, s39
	s_nop 0
	global_load_lds_dwordx4 v[172:173], off
	s_mov_b32 m0, s19
	v_mfma_f32_16x16x32_bf16 v[116:119], v[156:159], v[108:111], v[116:119]
	s_mov_b32 s19, m0
	s_mov_b32 m0, s42
	s_nop 0
	global_load_lds_dwordx4 v[22:23], off
	s_mov_b32 m0, s19
	s_mov_b64 s[20:21], 0x180
	v_lshl_add_u64 v[86:87], v[4:5], 0, s[20:21]
	v_mfma_f32_16x16x32_bf16 v[120:123], v[156:159], v[148:151], v[120:123]
	v_lshl_add_u64 v[172:173], v[6:7], 0, s[20:21]
	s_mov_b64 s[20:21], 0x2180
	s_mov_b64 s[38:39], 0
	v_mfma_f32_16x16x32_bf16 v[96:99], v[156:159], v[152:155], v[96:99]
	v_mfma_f32_16x16x32_bf16 v[128:131], v[160:163], v[108:111], v[128:131]
	v_mfma_f32_16x16x32_bf16 v[132:135], v[160:163], v[148:151], v[132:135]
	v_mfma_f32_16x16x32_bf16 v[100:103], v[160:163], v[152:155], v[100:103]
	v_mfma_f32_16x16x32_bf16 v[140:143], v[164:167], v[108:111], v[140:143]
	v_mfma_f32_16x16x32_bf16 v[144:147], v[164:167], v[148:151], v[144:147]
	v_mfma_f32_16x16x32_bf16 v[104:107], v[164:167], v[152:155], v[104:107]
	v_mfma_f32_16x16x32_bf16 v[14:17], v[168:171], v[108:111], v[14:17]
	v_mfma_f32_16x16x32_bf16 v[18:21], v[168:171], v[148:151], v[18:21]
	v_mfma_f32_16x16x32_bf16 v[0:3], v[168:171], v[152:155], v[0:3]
	ds_read_b128 v[22:25], v9
	ds_read_b128 v[108:111], v9 offset:1024
	ds_read_b128 v[148:151], v9 offset:2048
	ds_read_b128 v[152:155], v9 offset:3072
	ds_read_b128 v[156:159], v8 offset:16384
	ds_read_b128 v[160:163], v8 offset:17408
	ds_read_b128 v[164:167], v8 offset:18432
	ds_read_b128 v[168:171], v8 offset:19456
	s_waitcnt lgkmcnt(3)
; template <int N> DI void wait_vm() { asm volatile("s_waitcnt vmcnt(%0)" ::"n"(N) : "memory"); }
; template <int BM, class Epi>
; DI void gemm_dma(const u16* __restrict__ X, long ldx, const u16* __restrict__ W, long ldw, int K, char* smem,
;                  int m0, int n0, const Epi& epi) {
;     ...
;   do {
;     if (kt + D - 2 < nk) wait_vm<PW * (D - 2)>(); else wait_vm<0>();
;     __syncthreads();
;     if (kt + D - 1 < nk) GD_ISSUE(nxt)
;     nxt = (nxt + 1 == D) ? 0 : nxt + 1;
;     const char* base = smem + cur * STG;
;     cur = (cur + 1 == D) ? 0 : cur + 1;
;     bf16x8 xf[MT];
; #pragma unroll
;     for (int i = 0; i < MT; ++i) xf[i] = *(const bf16x8*)(base + (xrow0 + i * 16) * 64 + rd);
; #pragma unroll
;     for (int nh = 0; nh < NT / 4; ++nh) {
;       bf16x8 wf[4];
; #pragma unroll
;       for (int i = 0; i < 4; ++i) wf[i] = *(const bf16x8*)(base + BM * 64 + (wrow0 + (nh * 4 + i) * 16) * 64 + rd);
; #pragma unroll
;       for (int i = 0; i < 4; ++i)
; #pragma unroll
;         for (int mt = 0; mt < MT; ++mt)
;           acc[nh * 4 + i][mt] = __builtin_amdgcn_mfma_f32_16x16x32_bf16(wf[i], xf[mt], acc[nh * 4 + i][mt], 0, 0, 0);
	v_mfma_f32_16x16x32_bf16 v[42:45], v[156:159], v[22:25], v[42:45]
	v_mfma_f32_16x16x32_bf16 v[46:49], v[156:159], v[108:111], v[46:49]
	v_mfma_f32_16x16x32_bf16 v[50:53], v[156:159], v[148:151], v[50:53]
	v_mfma_f32_16x16x32_bf16 v[26:29], v[156:159], v[152:155], v[26:29]
	s_waitcnt lgkmcnt(2)
	v_mfma_f32_16x16x32_bf16 v[54:57], v[160:163], v[22:25], v[54:57]
	v_mfma_f32_16x16x32_bf16 v[58:61], v[160:163], v[108:111], v[58:61]
	v_mfma_f32_16x16x32_bf16 v[62:65], v[160:163], v[148:151], v[62:65]
	v_mfma_f32_16x16x32_bf16 v[30:33], v[160:163], v[152:155], v[30:33]
	s_waitcnt lgkmcnt(1)
	v_mfma_f32_16x16x32_bf16 v[66:69], v[164:167], v[22:25], v[66:69]
	v_mfma_f32_16x16x32_bf16 v[70:73], v[164:167], v[108:111], v[70:73]
	v_mfma_f32_16x16x32_bf16 v[74:77], v[164:167], v[148:151], v[74:77]
	v_mfma_f32_16x16x32_bf16 v[34:37], v[164:167], v[152:155], v[34:37]
	s_waitcnt lgkmcnt(0)
	v_mfma_f32_16x16x32_bf16 v[78:81], v[168:171], v[22:25], v[78:81]
	v_mfma_f32_16x16x32_bf16 v[82:85], v[168:171], v[108:111], v[82:85]
	v_mfma_f32_16x16x32_bf16 v[92:95], v[168:171], v[148:151], v[92:95]
	v_mfma_f32_16x16x32_bf16 v[38:41], v[168:171], v[152:155], v[38:41]
	ds_read_b128 v[156:159], v8 offset:20480
	ds_read_b128 v[160:163], v8 offset:21504
	ds_read_b128 v[164:167], v8 offset:22528
	ds_read_b128 v[168:171], v8 offset:23552
	s_waitcnt vmcnt(6)
	s_waitcnt lgkmcnt(0)
	s_barrier
	s_mov_b32 s19, m0
	s_mov_b32 m0, s14
	s_nop 0
	global_load_lds_dwordx4 v[86:87], off
	s_mov_b32 m0, s19
	v_mfma_f32_16x16x32_bf16 v[112:115], v[156:159], v[22:25], v[112:115]
	v_mfma_f32_16x16x32_bf16 v[124:127], v[160:163], v[22:25], v[124:127]
	v_mfma_f32_16x16x32_bf16 v[136:139], v[164:167], v[22:25], v[136:139]
	v_mfma_f32_16x16x32_bf16 v[10:13], v[168:171], v[22:25], v[10:13]
	v_lshl_add_u64 v[22:23], v[4:5], 0, s[20:21]
	s_mov_b32 s14, m0
	s_mov_b32 m0, s15
	s_nop 0
	global_load_lds_dwordx4 v[22:23], off
	s_mov_b32 m0, s14
	s_mov_b64 s[14:15], 0x4180
	v_lshl_add_u64 v[22:23], v[4:5], 0, s[14:15]
	s_mov_b32 s14, m0
	s_mov_b32 m0, s16
	s_nop 0
	global_load_lds_dwordx4 v[22:23], off
	s_mov_b32 m0, s14
	s_mov_b64 s[14:15], 0x6180
	v_lshl_add_u64 v[22:23], v[4:5], 0, s[14:15]
	s_mov_b32 s14, m0
	s_mov_b32 m0, s17
	s_nop 0
	global_load_lds_dwordx4 v[22:23], off
	s_mov_b32 m0, s14
	v_lshl_add_u64 v[22:23], v[6:7], 0, s[20:21]
	s_mov_b32 s14, m0
	s_mov_b32 m0, s13
	s_nop 0
	global_load_lds_dwordx4 v[172:173], off
	s_mov_b32 m0, s14
	s_mov_b32 s13, m0
	s_mov_b32 m0, s18
	s_nop 0
	global_load_lds_dwordx4 v[22:23], off
	s_mov_b32 m0, s13
	v_mfma_f32_16x16x32_bf16 v[116:119], v[156:159], v[108:111], v[116:119]
	s_mov_b64 s[14:15], 0x1c0
	v_lshl_add_u64 v[86:87], v[4:5], 0, s[14:15]
	v_lshl_add_u64 v[172:173], v[6:7], 0, s[14:15]
	v_mfma_f32_16x16x32_bf16 v[120:123], v[156:159], v[148:151], v[120:123]
	s_mov_b64 s[14:15], 0x21c0
	s_mov_b64 s[16:17], 0x41c0
	v_mfma_f32_16x16x32_bf16 v[96:99], v[156:159], v[152:155], v[96:99]
	v_mfma_f32_16x16x32_bf16 v[128:131], v[160:163], v[108:111], v[128:131]
	v_mfma_f32_16x16x32_bf16 v[132:135], v[160:163], v[148:151], v[132:135]
	v_mfma_f32_16x16x32_bf16 v[100:103], v[160:163], v[152:155], v[100:103]
	v_mfma_f32_16x16x32_bf16 v[140:143], v[164:167], v[108:111], v[140:143]
	v_mfma_f32_16x16x32_bf16 v[144:147], v[164:167], v[148:151], v[144:147]
	v_mfma_f32_16x16x32_bf16 v[104:107], v[164:167], v[152:155], v[104:107]
	v_mfma_f32_16x16x32_bf16 v[14:17], v[168:171], v[108:111], v[14:17]
	v_mfma_f32_16x16x32_bf16 v[18:21], v[168:171], v[148:151], v[18:21]
	v_mfma_f32_16x16x32_bf16 v[0:3], v[168:171], v[152:155], v[0:3]
	ds_read_b128 v[22:25], v9 offset:24576
	ds_read_b128 v[108:111], v9 offset:25600
	ds_read_b128 v[148:151], v9 offset:26624
	ds_read_b128 v[152:155], v9 offset:27648
	ds_read_b128 v[156:159], v8 offset:40960
	ds_read_b128 v[160:163], v8 offset:41984
	ds_read_b128 v[164:167], v8 offset:43008
	ds_read_b128 v[168:171], v8 offset:44032
	s_waitcnt lgkmcnt(3)
	v_mfma_f32_16x16x32_bf16 v[42:45], v[156:159], v[22:25], v[42:45]
	v_mfma_f32_16x16x32_bf16 v[46:49], v[156:159], v[108:111], v[46:49]
	v_mfma_f32_16x16x32_bf16 v[50:53], v[156:159], v[148:151], v[50:53]
	v_mfma_f32_16x16x32_bf16 v[26:29], v[156:159], v[152:155], v[26:29]
	s_waitcnt lgkmcnt(2)
	v_mfma_f32_16x16x32_bf16 v[54:57], v[160:163], v[22:25], v[54:57]
	v_mfma_f32_16x16x32_bf16 v[58:61], v[160:163], v[108:111], v[58:61]
	v_mfma_f32_16x16x32_bf16 v[62:65], v[160:163], v[148:151], v[62:65]
	v_mfma_f32_16x16x32_bf16 v[30:33], v[160:163], v[152:155], v[30:33]
	s_waitcnt lgkmcnt(1)
	v_mfma_f32_16x16x32_bf16 v[66:69], v[164:167], v[22:25], v[66:69]
	v_mfma_f32_16x16x32_bf16 v[70:73], v[164:167], v[108:111], v[70:73]
	v_mfma_f32_16x16x32_bf16 v[74:77], v[164:167], v[148:151], v[74:77]
	v_mfma_f32_16x16x32_bf16 v[34:37], v[164:167], v[152:155], v[34:37]
	s_waitcnt lgkmcnt(0)
	v_mfma_f32_16x16x32_bf16 v[78:81], v[168:171], v[22:25], v[78:81]
	v_mfma_f32_16x16x32_bf16 v[82:85], v[168:171], v[108:111], v[82:85]
	v_mfma_f32_16x16x32_bf16 v[92:95], v[168:171], v[148:151], v[92:95]
	v_mfma_f32_16x16x32_bf16 v[38:41], v[168:171], v[152:155], v[38:41]
	ds_read_b128 v[156:159], v8 offset:45056
	ds_read_b128 v[160:163], v8 offset:46080
	ds_read_b128 v[164:167], v8 offset:47104
	ds_read_b128 v[168:171], v8 offset:48128
	s_waitcnt vmcnt(6)
	s_waitcnt lgkmcnt(0)
	s_barrier
; template <int N> DI void wait_vm() { asm volatile("s_waitcnt vmcnt(%0)" ::"n"(N) : "memory"); }
; template <int BM, class Epi>
; DI void gemm_dma(const u16* __restrict__ X, long ldx, const u16* __restrict__ W, long ldw, int K, char* smem,
;                  int m0, int n0, const Epi& epi) {
;     ...
;   do {
;     if (kt + D - 2 < nk) wait_vm<PW * (D - 2)>(); else wait_vm<0>();
;     __syncthreads();
;     if (kt + D - 1 < nk) GD_ISSUE(nxt)
;     nxt = (nxt + 1 == D) ? 0 : nxt + 1;
;     const char* base = smem + cur * STG;
;     cur = (cur + 1 == D) ? 0 : cur + 1;
;     bf16x8 xf[MT];
; #pragma unroll
;     for (int i = 0; i < MT; ++i) xf[i] = *(const bf16x8*)(base + (xrow0 + i * 16) * 64 + rd);
; #pragma unroll
;     for (int nh = 0; nh < NT / 4; ++nh) {
;       bf16x8 wf[4];
; #pragma unroll
;       for (int i = 0; i < 4; ++i) wf[i] = *(const bf16x8*)(base + BM * 64 + (wrow0 + (nh * 4 + i) * 16) * 64 + rd);
; #pragma unroll
;       for (int i = 0; i < 4; ++i)
; #pragma unroll
;         for (int mt = 0; mt < MT; ++mt)
;           acc[nh * 4 + i][mt] = __builtin_amdgcn_mfma_f32_16x16x32_bf16(wf[i], xf[mt], acc[nh * 4 + i][mt], 0, 0, 0);
;     }
;   } while (++kt < nk);
	s_mov_b32 s13, m0
	s_mov_b32 m0, s7
	s_nop 0
	global_load_lds_dwordx4 v[86:87], off
	s_mov_b32 m0, s13
	v_mfma_f32_16x16x32_bf16 v[112:115], v[156:159], v[22:25], v[112:115]
	v_mfma_f32_16x16x32_bf16 v[124:127], v[160:163], v[22:25], v[124:127]
	v_mfma_f32_16x16x32_bf16 v[136:139], v[164:167], v[22:25], v[136:139]
	v_mfma_f32_16x16x32_bf16 v[10:13], v[168:171], v[22:25], v[10:13]
	v_lshl_add_u64 v[22:23], v[4:5], 0, s[14:15]
	s_mov_b32 s7, m0
	s_mov_b32 m0, s8
	s_nop 0
	global_load_lds_dwordx4 v[22:23], off
	s_mov_b32 m0, s7
	v_lshl_add_u64 v[22:23], v[4:5], 0, s[16:17]
	s_mov_b32 s7, m0
	s_mov_b32 m0, s9
	s_nop 0
	global_load_lds_dwordx4 v[22:23], off
	s_mov_b32 m0, s7
	s_mov_b64 s[8:9], 0x61c0
	v_lshl_add_u64 v[4:5], v[4:5], 0, s[8:9]
	s_mov_b32 s7, m0
	s_mov_b32 m0, s10
	s_nop 0
	global_load_lds_dwordx4 v[4:5], off
	s_mov_b32 m0, s7
	v_lshl_add_u64 v[4:5], v[6:7], 0, s[14:15]
	s_mov_b32 s7, m0
	s_mov_b32 m0, s11
	s_nop 0
	global_load_lds_dwordx4 v[172:173], off
	s_mov_b32 m0, s7
	v_mfma_f32_16x16x32_bf16 v[116:119], v[156:159], v[108:111], v[116:119]
	s_mov_b32 s7, m0
	s_mov_b32 m0, s12
	s_nop 0
	global_load_lds_dwordx4 v[4:5], off
	s_mov_b32 m0, s7
	v_readlane_b32 s8, v255, 5
	v_readlane_b32 s14, v255, 11
	v_mfma_f32_16x16x32_bf16 v[120:123], v[156:159], v[148:151], v[120:123]
	v_readlane_b32 s9, v255, 6
	v_readlane_b32 s10, v255, 7
	v_readlane_b32 s11, v255, 8
	v_mfma_f32_16x16x32_bf16 v[96:99], v[156:159], v[152:155], v[96:99]
	v_readlane_b32 s12, v255, 9
	v_readlane_b32 s13, v255, 10
	v_readlane_b32 s15, v255, 12
	v_mfma_f32_16x16x32_bf16 v[128:131], v[160:163], v[108:111], v[128:131]
	s_add_i32 s4, s5, s14
	v_mfma_f32_16x16x32_bf16 v[132:135], v[160:163], v[148:151], v[132:135]
	v_mfma_f32_16x16x32_bf16 v[100:103], v[160:163], v[152:155], v[100:103]
	v_mfma_f32_16x16x32_bf16 v[140:143], v[164:167], v[108:111], v[140:143]
	v_mfma_f32_16x16x32_bf16 v[144:147], v[164:167], v[148:151], v[144:147]
	v_mfma_f32_16x16x32_bf16 v[104:107], v[164:167], v[152:155], v[104:107]
	v_mfma_f32_16x16x32_bf16 v[14:17], v[168:171], v[108:111], v[14:17]
	v_mfma_f32_16x16x32_bf16 v[18:21], v[168:171], v[148:151], v[18:21]
	v_mfma_f32_16x16x32_bf16 v[0:3], v[168:171], v[152:155], v[0:3]
	ds_read_b128 v[4:7], v9 offset:49152
	ds_read_b128 v[22:25], v9 offset:50176
	ds_read_b128 v[108:111], v9 offset:51200
	ds_read_b128 v[148:151], v9 offset:52224
	ds_read_b128 v[152:155], v91
	ds_read_b128 v[156:159], v174
	ds_read_b128 v[160:163], v175
	ds_read_b128 v[164:167], v176
	s_waitcnt lgkmcnt(3)
	v_mfma_f32_16x16x32_bf16 v[42:45], v[152:155], v[4:7], v[42:45]
	v_mfma_f32_16x16x32_bf16 v[46:49], v[152:155], v[22:25], v[46:49]
	v_mfma_f32_16x16x32_bf16 v[50:53], v[152:155], v[108:111], v[50:53]
	v_mfma_f32_16x16x32_bf16 v[26:29], v[152:155], v[148:151], v[26:29]
	s_waitcnt lgkmcnt(2)
	v_mfma_f32_16x16x32_bf16 v[54:57], v[156:159], v[4:7], v[54:57]
	v_mfma_f32_16x16x32_bf16 v[58:61], v[156:159], v[22:25], v[58:61]
	v_mfma_f32_16x16x32_bf16 v[62:65], v[156:159], v[108:111], v[62:65]
	v_mfma_f32_16x16x32_bf16 v[30:33], v[156:159], v[148:151], v[30:33]
	s_waitcnt lgkmcnt(1)
	v_mfma_f32_16x16x32_bf16 v[66:69], v[160:163], v[4:7], v[66:69]
	v_mfma_f32_16x16x32_bf16 v[70:73], v[160:163], v[22:25], v[70:73]
	v_mfma_f32_16x16x32_bf16 v[74:77], v[160:163], v[108:111], v[74:77]
	v_mfma_f32_16x16x32_bf16 v[34:37], v[160:163], v[148:151], v[34:37]
	s_waitcnt lgkmcnt(0)
	v_mfma_f32_16x16x32_bf16 v[78:81], v[164:167], v[4:7], v[78:81]
	v_mfma_f32_16x16x32_bf16 v[82:85], v[164:167], v[22:25], v[82:85]
	v_mfma_f32_16x16x32_bf16 v[92:95], v[164:167], v[108:111], v[92:95]
	v_mfma_f32_16x16x32_bf16 v[38:41], v[164:167], v[148:151], v[38:41]
	ds_read_b128 v[152:155], v177
	ds_read_b128 v[156:159], v178
	ds_read_b128 v[160:163], v179
	ds_read_b128 v[164:167], v180
	s_waitcnt vmcnt(6)
	s_waitcnt lgkmcnt(0)
	v_mfma_f32_16x16x32_bf16 v[112:115], v[152:155], v[4:7], v[112:115]
	s_barrier
	v_mfma_f32_16x16x32_bf16 v[116:119], v[152:155], v[22:25], v[116:119]
	v_mfma_f32_16x16x32_bf16 v[120:123], v[152:155], v[108:111], v[120:123]
	v_mfma_f32_16x16x32_bf16 v[96:99], v[152:155], v[148:151], v[96:99]
	v_mfma_f32_16x16x32_bf16 v[124:127], v[156:159], v[4:7], v[124:127]
	v_mfma_f32_16x16x32_bf16 v[128:131], v[156:159], v[22:25], v[128:131]
	v_mfma_f32_16x16x32_bf16 v[132:135], v[156:159], v[108:111], v[132:135]
	v_mfma_f32_16x16x32_bf16 v[100:103], v[156:159], v[148:151], v[100:103]
	v_mfma_f32_16x16x32_bf16 v[136:139], v[160:163], v[4:7], v[136:139]
	v_mfma_f32_16x16x32_bf16 v[140:143], v[160:163], v[22:25], v[140:143]
	v_mfma_f32_16x16x32_bf16 v[144:147], v[160:163], v[108:111], v[144:147]
	v_mfma_f32_16x16x32_bf16 v[104:107], v[160:163], v[148:151], v[104:107]
	v_mfma_f32_16x16x32_bf16 v[4:7], v[164:167], v[4:7], v[10:13]
	v_mfma_f32_16x16x32_bf16 v[10:13], v[164:167], v[22:25], v[14:17]
	v_mfma_f32_16x16x32_bf16 v[14:17], v[164:167], v[108:111], v[18:21]
	v_mfma_f32_16x16x32_bf16 v[0:3], v[164:167], v[148:151], v[0:3]
	s_nop 1
	ds_read_b128 v[18:21], v8 offset:23552
	ds_read_b128 v[22:25], v8 offset:22528
	ds_read_b128 v[108:111], v8 offset:21504
	ds_read_b128 v[148:151], v8 offset:20480
	ds_read_b128 v[152:155], v8 offset:19456
	ds_read_b128 v[156:159], v8 offset:18432
	ds_read_b128 v[160:163], v8 offset:17408
	ds_read_b128 v[164:167], v8 offset:16384
	ds_read_b128 v[168:171], v9 offset:3072
	ds_read_b128 v[172:175], v9 offset:2048
	ds_read_b128 v[176:179], v9 offset:1024
	ds_read_b128 v[186:189], v9
	s_waitcnt vmcnt(0)
	s_waitcnt lgkmcnt(0)
	v_mfma_f32_16x16x32_bf16 v[42:45], v[164:167], v[186:189], v[42:45]
	s_barrier
; DI void st_bf4(u16* p, float a, float b, float c, float d) { *(uint2*)p = make_uint2(pk2(a, b), pk2(c, d)); }
; template <int BM, class Epi>
; DI void gemm_dma(const u16* __restrict__ X, long ldx, const u16* __restrict__ W, long ldw, int K, char* smem,
;                  int m0, int n0, const Epi& epi) {
;     ...
;     for (int i = 0; i < MT; ++i) xf[i] = *(const bf16x8*)(base + (xrow0 + i * 16) * 64 + rd);
; #pragma unroll
;     for (int nh = 0; nh < NT / 4; ++nh) {
;       bf16x8 wf[4];
; #pragma unroll
;       for (int i = 0; i < 4; ++i) wf[i] = *(const bf16x8*)(base + BM * 64 + (wrow0 + (nh * 4 + i) * 16) * 64 + rd);
; #pragma unroll
;       for (int i = 0; i < 4; ++i)
; #pragma unroll
;         for (int mt = 0; mt < MT; ++mt)
;           acc[nh * 4 + i][mt] = __builtin_amdgcn_mfma_f32_16x16x32_bf16(wf[i], xf[mt], acc[nh * 4 + i][mt], 0, 0, 0);
;     }
;   } while (++kt < nk);
;   template <int NT, int MT> DI void run(f32x4 (&acc)[NT][MT], int mb, int nb) const {
; #pragma unroll
;     for (int nt = 0; nt < NT; ++nt)
; #pragma unroll
;       for (int mt = 0; mt < MT; ++mt) {
;         f32x4 v = acc[nt][mt];
;         st_bf4(C + (size_t)(mb + mt * 16) * ldc + nb + nt * 16, v[0], v[1], v[2], v[3]);
;       }
	v_mfma_f32_16x16x32_bf16 v[46:49], v[164:167], v[176:179], v[46:49]
	v_mfma_f32_16x16x32_bf16 v[50:53], v[164:167], v[172:175], v[50:53]
	v_mfma_f32_16x16x32_bf16 v[26:29], v[164:167], v[168:171], v[26:29]
	v_mfma_f32_16x16x32_bf16 v[54:57], v[160:163], v[186:189], v[54:57]
	v_mfma_f32_16x16x32_bf16 v[58:61], v[160:163], v[176:179], v[58:61]
	v_mfma_f32_16x16x32_bf16 v[62:65], v[160:163], v[172:175], v[62:65]
	v_mfma_f32_16x16x32_bf16 v[30:33], v[160:163], v[168:171], v[30:33]
	v_mfma_f32_16x16x32_bf16 v[66:69], v[156:159], v[186:189], v[66:69]
	v_mfma_f32_16x16x32_bf16 v[70:73], v[156:159], v[176:179], v[70:73]
	v_mfma_f32_16x16x32_bf16 v[74:77], v[156:159], v[172:175], v[74:77]
	v_mfma_f32_16x16x32_bf16 v[34:37], v[156:159], v[168:171], v[34:37]
	v_mfma_f32_16x16x32_bf16 v[156:159], v[152:155], v[186:189], v[78:81]
	v_mfma_f32_16x16x32_bf16 v[84:87], v[152:155], v[176:179], v[82:85]
	v_mfma_f32_16x16x32_bf16 v[92:95], v[152:155], v[172:175], v[92:95]
	v_mfma_f32_16x16x32_bf16 v[152:155], v[152:155], v[168:171], v[38:41]
	v_mfma_f32_16x16x32_bf16 v[112:115], v[148:151], v[186:189], v[112:115]
	v_mfma_f32_16x16x32_bf16 v[116:119], v[148:151], v[176:179], v[116:119]
	v_mfma_f32_16x16x32_bf16 v[120:123], v[148:151], v[172:175], v[120:123]
	v_mfma_f32_16x16x32_bf16 v[96:99], v[148:151], v[168:171], v[96:99]
	v_mfma_f32_16x16x32_bf16 v[124:127], v[108:111], v[186:189], v[124:127]
	v_mfma_f32_16x16x32_bf16 v[128:131], v[108:111], v[176:179], v[128:131]
	v_mfma_f32_16x16x32_bf16 v[132:135], v[108:111], v[172:175], v[132:135]
	v_mfma_f32_16x16x32_bf16 v[100:103], v[108:111], v[168:171], v[100:103]
	v_mfma_f32_16x16x32_bf16 v[108:111], v[22:25], v[186:189], v[136:139]
	v_mfma_f32_16x16x32_bf16 v[136:139], v[22:25], v[176:179], v[140:143]
	v_mfma_f32_16x16x32_bf16 v[140:143], v[22:25], v[172:175], v[144:147]
	v_mfma_f32_16x16x32_bf16 v[104:107], v[22:25], v[168:171], v[104:107]
	v_mfma_f32_16x16x32_bf16 v[4:7], v[18:21], v[186:189], v[4:7]
	v_mfma_f32_16x16x32_bf16 v[144:147], v[18:21], v[176:179], v[10:13]
	v_mfma_f32_16x16x32_bf16 v[148:151], v[18:21], v[172:175], v[14:17]
	v_mfma_f32_16x16x32_bf16 v[0:3], v[18:21], v[168:171], v[0:3]
	s_nop 0
	ds_read_b128 v[10:13], v9 offset:24576
	ds_read_b128 v[160:163], v9 offset:25600
	ds_read_b128 v[164:167], v9 offset:26624
	ds_read_b128 v[168:171], v9 offset:27648
	ds_read_b128 v[14:17], v8 offset:40960
	ds_read_b128 v[18:21], v8 offset:41984
	ds_read_b128 v[22:25], v8 offset:43008
	ds_read_b128 v[172:175], v8 offset:44032
	s_waitcnt lgkmcnt(3)
	v_mfma_f32_16x16x32_bf16 v[176:179], v[14:17], v[10:13], v[42:45]
	v_mfma_f32_16x16x32_bf16 v[186:189], v[14:17], v[160:163], v[46:49]
	v_mfma_f32_16x16x32_bf16 v[190:193], v[14:17], v[164:167], v[50:53]
	v_mfma_f32_16x16x32_bf16 v[194:197], v[14:17], v[168:171], v[26:29]
	s_waitcnt lgkmcnt(2)
	v_mfma_f32_16x16x32_bf16 v[224:227], v[18:21], v[10:13], v[54:57]
	v_mfma_f32_16x16x32_bf16 v[228:231], v[18:21], v[160:163], v[58:61]
	v_mfma_f32_16x16x32_bf16 v[232:235], v[18:21], v[164:167], v[62:65]
	v_mfma_f32_16x16x32_bf16 v[236:239], v[18:21], v[168:171], v[30:33]
	s_waitcnt lgkmcnt(1)
	v_mfma_f32_16x16x32_bf16 v[240:243], v[22:25], v[10:13], v[66:69]
	v_mfma_f32_16x16x32_bf16 v[64:67], v[22:25], v[168:171], v[34:37]
	s_waitcnt lgkmcnt(0)
	v_mfma_f32_16x16x32_bf16 v[40:43], v[172:175], v[164:167], v[92:95]
	v_mfma_f32_16x16x32_bf16 v[32:35], v[172:175], v[168:171], v[152:155]
	ds_read_b128 v[14:17], v8 offset:45056
	ds_read_b128 v[18:21], v8 offset:46080
	ds_read_b128 v[92:95], v8 offset:47104
	ds_read_b128 v[152:155], v8 offset:48128
	s_nop 0
	v_cvt_pk_bf16_f32 v64, v64, v65
	v_cvt_pk_bf16_f32 v65, v66, v67
	v_mfma_f32_16x16x32_bf16 v[80:83], v[22:25], v[160:163], v[70:73]
	v_cvt_pk_bf16_f32 v32, v32, v33
	v_cvt_pk_bf16_f32 v33, v34, v35
	v_cvt_pk_bf16_f32 v40, v40, v41
	v_mfma_f32_16x16x32_bf16 v[72:75], v[22:25], v[164:167], v[74:77]
	v_cvt_pk_bf16_f32 v41, v42, v43
	s_nop 2
	v_cvt_pk_bf16_f32 v80, v80, v81
	v_cvt_pk_bf16_f32 v81, v82, v83
	v_mfma_f32_16x16x32_bf16 v[48:51], v[172:175], v[160:163], v[84:87]
	s_waitcnt lgkmcnt(3)
	v_mfma_f32_16x16x32_bf16 v[112:115], v[14:17], v[10:13], v[112:115]
	v_cvt_pk_bf16_f32 v72, v72, v73
	v_cvt_pk_bf16_f32 v73, v74, v75
	s_nop 3
	v_cvt_pk_bf16_f32 v48, v48, v49
	v_mfma_f32_16x16x32_bf16 v[84:87], v[14:17], v[160:163], v[116:119]
	v_cvt_pk_bf16_f32 v49, v50, v51
	v_mfma_f32_16x16x32_bf16 v[76:79], v[14:17], v[164:167], v[120:123]
	v_mfma_f32_16x16x32_bf16 v[68:71], v[14:17], v[168:171], v[96:99]
	s_waitcnt lgkmcnt(2)
	v_mfma_f32_16x16x32_bf16 v[60:63], v[18:21], v[10:13], v[124:127]
	s_nop 0
	v_cvt_pk_bf16_f32 v96, v190, v191
	v_cvt_pk_bf16_f32 v97, v192, v193
	v_mfma_f32_16x16x32_bf16 v[52:55], v[18:21], v[160:163], v[128:131]
	v_mfma_f32_16x16x32_bf16 v[44:47], v[18:21], v[164:167], v[132:135]
	v_mfma_f32_16x16x32_bf16 v[36:39], v[18:21], v[168:171], v[100:103]
	s_waitcnt lgkmcnt(1)
; DI void st_bf4(u16* p, float a, float b, float c, float d) { *(uint2*)p = make_uint2(pk2(a, b), pk2(c, d)); }
; template <int BM, class Epi>
; DI void gemm_dma(const u16* __restrict__ X, long ldx, const u16* __restrict__ W, long ldw, int K, char* smem,
;                  int m0, int n0, const Epi& epi) {
;     ...
;       for (int i = 0; i < 4; ++i)
; #pragma unroll
;         for (int mt = 0; mt < MT; ++mt)
;           acc[nh * 4 + i][mt] = __builtin_amdgcn_mfma_f32_16x16x32_bf16(wf[i], xf[mt], acc[nh * 4 + i][mt], 0, 0, 0);
;   template <int NT, int MT> DI void run(f32x4 (&acc)[NT][MT], int mb, int nb) const {
; #pragma unroll
;     for (int nt = 0; nt < NT; ++nt)
; #pragma unroll
;       for (int mt = 0; mt < MT; ++mt) {
;         f32x4 v = acc[nt][mt];
;         st_bf4(C + (size_t)(mb + mt * 16) * ldc + nb + nt * 16, v[0], v[1], v[2], v[3]);
;       }
	v_mfma_f32_16x16x32_bf16 v[28:31], v[92:95], v[10:13], v[108:111]
	v_mfma_f32_16x16x32_bf16 v[24:27], v[92:95], v[160:163], v[136:139]
	v_mfma_f32_16x16x32_bf16 v[20:23], v[92:95], v[164:167], v[140:143]
	s_nop 5
	v_cvt_pk_bf16_f32 v28, v28, v29
	v_cvt_pk_bf16_f32 v29, v30, v31
	v_cvt_pk_bf16_f32 v24, v24, v25
	v_mfma_f32_16x16x32_bf16 v[16:19], v[92:95], v[168:171], v[104:107]
	v_or_b32_e32 v92, v90, v89
	v_ashrrev_i32_e32 v93, 31, v92
	v_lshlrev_b64 v[90:91], 11, v[92:93]
	v_lshl_add_u64 v[90:91], s[92:93], 0, v[90:91]
	v_lshl_add_u64 v[88:89], v[90:91], 0, v[182:183]
	v_cvt_pk_bf16_f32 v90, v176, v177
	v_cvt_pk_bf16_f32 v91, v178, v179
	global_store_dwordx2 v[88:89], v[90:91], off
	v_or_b32_e32 v90, 16, v92
	v_ashrrev_i32_e32 v91, 31, v90
	v_lshlrev_b64 v[90:91], 11, v[90:91]
	v_lshl_add_u64 v[90:91], s[92:93], 0, v[90:91]
	v_lshl_add_u64 v[90:91], v[90:91], 0, v[182:183]
	v_cvt_pk_bf16_f32 v94, v186, v187
	v_cvt_pk_bf16_f32 v95, v188, v189
	global_store_dwordx2 v[90:91], v[94:95], off
	v_or_b32_e32 v94, 32, v92
	v_or_b32_e32 v92, 48, v92
	v_ashrrev_i32_e32 v93, 31, v92
	v_lshlrev_b64 v[92:93], 11, v[92:93]
	v_ashrrev_i32_e32 v95, 31, v94
	v_lshl_add_u64 v[92:93], s[92:93], 0, v[92:93]
	v_lshlrev_b64 v[94:95], 11, v[94:95]
	v_lshl_add_u64 v[92:93], v[92:93], 0, v[182:183]
	v_lshl_add_u64 v[94:95], s[92:93], 0, v[94:95]
	global_store_dwordx2 v[92:93], v[32:33], off offset:96
	v_cvt_pk_bf16_f32 v32, v112, v113
	v_cvt_pk_bf16_f32 v33, v114, v115
	v_lshl_add_u64 v[94:95], v[94:95], 0, v[182:183]
	global_store_dwordx2 v[88:89], v[32:33], off offset:128
	v_cvt_pk_bf16_f32 v32, v84, v85
	v_cvt_pk_bf16_f32 v33, v86, v87
	global_store_dwordx2 v[94:95], v[96:97], off
	v_cvt_pk_bf16_f32 v96, v194, v195
	v_cvt_pk_bf16_f32 v97, v196, v197
	global_store_dwordx2 v[90:91], v[32:33], off offset:128
	v_cvt_pk_bf16_f32 v32, v76, v77
	v_cvt_pk_bf16_f32 v33, v78, v79
	v_mfma_f32_16x16x32_bf16 v[56:59], v[172:175], v[10:13], v[156:159]
	global_store_dwordx2 v[92:93], v[96:97], off
	v_cvt_pk_bf16_f32 v96, v224, v225
	v_cvt_pk_bf16_f32 v97, v226, v227
	s_waitcnt lgkmcnt(0)
	v_mfma_f32_16x16x32_bf16 v[12:15], v[152:155], v[10:13], v[4:7]
	global_store_dwordx2 v[94:95], v[32:33], off offset:128
	v_cvt_pk_bf16_f32 v32, v68, v69
	v_cvt_pk_bf16_f32 v33, v70, v71
	v_mfma_f32_16x16x32_bf16 v[8:11], v[152:155], v[160:163], v[144:147]
	global_store_dwordx2 v[88:89], v[96:97], off offset:32
	v_cvt_pk_bf16_f32 v96, v228, v229
	v_cvt_pk_bf16_f32 v97, v230, v231
	v_mfma_f32_16x16x32_bf16 v[4:7], v[152:155], v[164:167], v[148:151]
	global_store_dwordx2 v[92:93], v[32:33], off offset:128
	v_cvt_pk_bf16_f32 v32, v60, v61
	v_cvt_pk_bf16_f32 v33, v62, v63
	v_mfma_f32_16x16x32_bf16 v[0:3], v[152:155], v[168:171], v[0:3]
	global_store_dwordx2 v[90:91], v[96:97], off offset:32
	v_cvt_pk_bf16_f32 v96, v232, v233
	v_cvt_pk_bf16_f32 v97, v234, v235
	global_store_dwordx2 v[88:89], v[32:33], off offset:160
	v_cvt_pk_bf16_f32 v32, v52, v53
	v_cvt_pk_bf16_f32 v33, v54, v55
	global_store_dwordx2 v[94:95], v[96:97], off offset:32
	v_cvt_pk_bf16_f32 v96, v236, v237
	v_cvt_pk_bf16_f32 v97, v238, v239
	global_store_dwordx2 v[90:91], v[32:33], off offset:160
	v_cvt_pk_bf16_f32 v32, v44, v45
	v_cvt_pk_bf16_f32 v33, v46, v47
	global_store_dwordx2 v[92:93], v[96:97], off offset:32
	v_cvt_pk_bf16_f32 v96, v240, v241
	v_cvt_pk_bf16_f32 v97, v242, v243
	v_cvt_pk_bf16_f32 v56, v56, v57
	v_cvt_pk_bf16_f32 v57, v58, v59
	global_store_dwordx2 v[94:95], v[32:33], off offset:160
	v_cvt_pk_bf16_f32 v32, v36, v37
	v_cvt_pk_bf16_f32 v33, v38, v39
	v_cvt_pk_bf16_f32 v25, v26, v27
	v_cvt_pk_bf16_f32 v20, v20, v21
	v_cvt_pk_bf16_f32 v21, v22, v23
	v_cvt_pk_bf16_f32 v16, v16, v17
	v_cvt_pk_bf16_f32 v17, v18, v19
	v_cvt_pk_bf16_f32 v12, v12, v13
	v_cvt_pk_bf16_f32 v13, v14, v15
	v_cvt_pk_bf16_f32 v8, v8, v9
	v_cvt_pk_bf16_f32 v9, v10, v11
	v_cvt_pk_bf16_f32 v4, v4, v5
	v_cvt_pk_bf16_f32 v5, v6, v7
	v_cvt_pk_bf16_f32 v0, v0, v1
	v_cvt_pk_bf16_f32 v1, v2, v3
	global_store_dwordx2 v[88:89], v[96:97], off offset:64
	global_store_dwordx2 v[90:91], v[80:81], off offset:64
	global_store_dwordx2 v[94:95], v[72:73], off offset:64
	global_store_dwordx2 v[92:93], v[64:65], off offset:64
	global_store_dwordx2 v[88:89], v[56:57], off offset:96
	global_store_dwordx2 v[90:91], v[48:49], off offset:96
	global_store_dwordx2 v[94:95], v[40:41], off offset:96
	global_store_dwordx2 v[92:93], v[32:33], off offset:160
	global_store_dwordx2 v[88:89], v[28:29], off offset:192
	global_store_dwordx2 v[90:91], v[24:25], off offset:192
	global_store_dwordx2 v[94:95], v[20:21], off offset:192
	global_store_dwordx2 v[92:93], v[16:17], off offset:192
	global_store_dwordx2 v[88:89], v[12:13], off offset:224
	global_store_dwordx2 v[90:91], v[8:9], off offset:224
	global_store_dwordx2 v[94:95], v[4:5], off offset:224
	global_store_dwordx2 v[92:93], v[0:1], off offset:224
